# GEMM epilogues: bias/gate/norm-vector loads hoisted to one wait per tile (F, M1, residual GEMMs); scan as before
# speedup vs baseline: 1.0222x; 1.0222x over previous
; DI void st8(bf16_t* p, const pg8::f32x4& v0, const pg8::f32x4& v1) { u32x4 w; w.x = cvtpk(v0[0], v0[1]); w.y = cvtpk(v0[2], v0[3]); w.z = cvtpk(v1[0], v1[1]); w.w = cvtpk(v1[2], v1[3]); *(u32x4*)p = w; }
;     DI void operator()(const pg8::f32x4 (&acc)[2][2][4][2], const pg8::Unit& u, int wr, int wc, int fr, int fq) const {
;     ...
;         const int b = u.pm / 9, seg = u.pm - b * 9, mrow = seg == 0 ? 32 : b;
;         const float* gbase = mods + (size_t)mrow * 6144 + gidx * 1024; const float* gpb = gp + (size_t)mrow * 1024;
; #pragma unroll
;         for (int ai = 0; ai < 2; ++ai)
; #pragma unroll
;             for (int m = 0; m < 4; ++m) { const int rit = ai * 128 + wr * 64 + m * 16 + fr; float ss = 0.f;
;                 const size_t roff = (seg == 0 ? (size_t)(b * TC + rit) * DM : (size_t)(b * SEQ + (seg - 1) * 256 + rit) * DM);
; #pragma unroll
;                 for (int bj = 0; bj < 2; ++bj) { const int col0 = u.pn * 256 + bj * 128 + wc * 32 + 8 * fq;
;                     float* p = (seg == 0 ? xc : out) + roff + col0; const float* q = (seg == 0 ? sc : sx) + roff + col0;
;                     const pg8::f32x4 g0 = *(const pg8::f32x4*)(gbase + col0), g1 = *(const pg8::f32x4*)(gbase + col0 + 4); pg8::f32x4 x0 = *(const pg8::f32x4*)q, x1 = *(const pg8::f32x4*)(q + 4);
;                     x0 += g0 * acc[ai][bj][m][0]; x1 += g1 * acc[ai][bj][m][1]; *(pg8::f32x4*)p = x0; *(pg8::f32x4*)(p + 4) = x1;
;                     if (emit) { const pg8::f32x4 p0 = *(const pg8::f32x4*)(gpb + col0), p1 = *(const pg8::f32x4*)(gpb + col0 + 4);
;                         ss += x0[0] * x0[0] + x0[1] * x0[1] + x0[2] * x0[2] + x0[3] * x0[3] + x1[0] * x1[0] + x1[1] * x1[1] + x1[2] * x1[2] + x1[3] * x1[3];
;                         st8(H + (size_t)(u.pm * 256 + rit) * 1024 + col0, x0 * p0, x1 * p1); }
;                     __builtin_amdgcn_sched_barrier(0); }
;                 if (emit) { ss += __shfl_xor(ss, 16, 64); ss += __shfl_xor(ss, 32, 64); if (fq == 0) atomicAdd(rs + u.pm * 256 + rit, ss); }
.LBB0_878:
	s_mul_hi_i32 s2, s20, 0x38e38e39
	s_lshr_b32 s4, s2, 31
	s_ashr_i32 s2, s2, 1
	s_add_i32 s2, s2, s4
	s_mul_i32 s4, s2, -9
	s_add_i32 s4, s4, s20
	s_cmp_eq_u32 s4, 0
	s_cselect_b64 s[36:37], -1, 0
	s_and_b64 s[40:41], s[36:37], exec
	s_cselect_b32 s50, 32, s2
	s_ashr_i32 s51, s50, 31
	s_mul_i32 s7, s50, 0x6000
	s_mul_hi_i32 s5, s50, 0x6000
	s_add_u32 s7, s79, s7
	s_addc_u32 s5, s82, s5
	s_add_u32 s40, s7, 0x5000
	s_addc_u32 s41, s5, 0
	s_lshl_b32 s5, s6, 8
	v_mov_b32_e32 v158, v170
	v_mov_b32_e32 v159, v0
	s_or_b32 s5, s5, s44
	s_lshl_b32 s4, s4, 8
	v_lshl_add_u32 v160, v159, 3, s5
	s_lshl_b32 s5, s2, 11
	s_add_i32 s4, s5, s4
	s_lshl_b64 s[50:51], s[50:51], 12
	s_lshl_b32 s6, s20, 8
	s_addk_i32 s4, 0xff00
	s_lshl_b32 s2, s2, 8
	s_and_b64 s[20:21], s[36:37], exec
	v_add_u32_e32 v158, s39, v158
	s_cselect_b32 s2, s2, s4
	v_add_u32_e32 v162, s2, v158
	v_ashrrev_i32_e32 v163, 31, v162
	v_add_u32_e32 v164, s6, v158
	v_ashrrev_i32_e32 v165, 31, v164
	s_cselect_b32 s59, s38, s63
	s_cselect_b32 s58, s91, s62
	v_lshlrev_b64 v[162:163], 12, v[162:163]
	v_ashrrev_i32_e32 v161, 31, v160
	v_lshlrev_b64 v[168:169], 11, v[164:165]
	v_lshl_add_u64 v[162:163], s[58:59], 0, v[162:163]
	v_lshlrev_b64 v[164:165], 2, v[160:161]
	v_lshl_add_u64 v[166:167], v[162:163], 0, v[164:165]
	v_lshl_add_u64 v[164:165], s[40:41], 0, v[164:165]
	flat_load_dwordx4 v[208:211], v[164:165]
	flat_load_dwordx4 v[212:215], v[164:165] offset:16
	flat_load_dwordx4 v[198:201], v[166:167]
	flat_load_dwordx4 v[202:205], v[166:167] offset:16
	v_lshl_add_u64 v[152:153], v[138:139], 0, s[50:51]
	v_cndmask_b32_e64 v162, 0, 1, s[8:9]
	v_lshl_add_u64 v[168:169], s[64:65], 0, v[168:169]
	v_mov_b32_e32 v189, 0
	v_cmp_ne_u32_e64 s[36:37], 1, v162
	s_andn2_b64 vcc, exec, s[8:9]
	v_lshl_add_u64 v[162:163], v[160:161], 2, v[152:153]
	v_lshl_add_u64 v[168:169], v[160:161], 1, v[168:169]
	s_movk_i32 s33, 0x1000
	flat_load_dwordx4 v[216:219], v[164:165] offset:512
	flat_load_dwordx4 v[220:223], v[164:165] offset:528
	flat_load_dwordx4 v[224:227], v[162:163]
	flat_load_dwordx4 v[228:231], v[162:163] offset:16
	flat_load_dwordx4 v[232:235], v[162:163] offset:512
	flat_load_dwordx4 v[236:239], v[162:163] offset:528
	s_waitcnt vmcnt(0) lgkmcnt(0)
	v_pk_fma_f32 v[128:129], v[128:129], v[210:211], v[200:201]
	v_pk_fma_f32 v[126:127], v[126:127], v[208:209], v[198:199]
	v_pk_fma_f32 v[124:125], v[124:125], v[214:215], v[204:205]
	v_pk_fma_f32 v[122:123], v[122:123], v[212:213], v[202:203]
	flat_store_dwordx4 v[166:167], v[126:129]
	flat_store_dwordx4 v[166:167], v[122:125] offset:16
	s_cbranch_vccnz .LBB0_880
	v_pk_mul_f32 v[198:199], v[126:127], v[126:127]
	v_pk_mul_f32 v[152:153], v[128:129], v[128:129]
	v_add_f32_e32 v189, v198, v199
	v_add_f32_e32 v152, v152, v189
	v_pk_mul_f32 v[202:203], v[122:123], v[122:123]
	v_add_f32_e32 v152, v153, v152
	v_add_f32_e32 v152, v202, v152
	v_pk_mul_f32 v[200:201], v[124:125], v[124:125]
	v_add_f32_e32 v152, v203, v152
	v_add_f32_e32 v152, v200, v152
	v_add_f32_e32 v189, v201, v152
	v_pk_mul_f32 v[128:129], v[128:129], v[226:227]
	v_pk_mul_f32 v[152:153], v[124:125], v[230:231]
	v_pk_mul_f32 v[124:125], v[122:123], v[228:229]
	v_pk_mul_f32 v[126:127], v[126:127], v[224:225]
	s_nop 0
	v_cvt_pk_bf16_f32 v122, v126, v127
	v_cvt_pk_bf16_f32 v123, v128, v129
	v_cvt_pk_bf16_f32 v124, v124, v125
	v_cvt_pk_bf16_f32 v125, v152, v153
	flat_store_dwordx4 v[168:169], v[122:125]
.LBB0_880:
	s_nop 1
	v_add_u32_e32 v122, 0x80, v160
	v_ashrrev_i32_e32 v123, 31, v122
	v_lshl_add_u64 v[122:123], v[122:123], 2, s[40:41]
	flat_load_dwordx4 v[190:193], v[166:167] offset:512
	flat_load_dwordx4 v[194:197], v[166:167] offset:528
	s_and_b64 vcc, exec, s[36:37]
	s_waitcnt vmcnt(0) lgkmcnt(0)
	v_pk_fma_f32 v[120:121], v[120:121], v[218:219], v[192:193]
	v_pk_fma_f32 v[118:119], v[118:119], v[216:217], v[190:191]
	v_pk_fma_f32 v[116:117], v[116:117], v[222:223], v[196:197]
	v_pk_fma_f32 v[114:115], v[114:115], v[220:221], v[194:195]
	flat_store_dwordx4 v[166:167], v[118:121] offset:512
	flat_store_dwordx4 v[166:167], v[114:117] offset:528
	s_cbranch_vccnz .LBB0_882
	v_pk_mul_f32 v[152:153], v[118:119], v[118:119]
	v_pk_mul_f32 v[128:129], v[120:121], v[120:121]
	v_add_f32_e32 v152, v152, v153
	v_add_f32_e32 v128, v128, v152
	v_pk_mul_f32 v[194:195], v[114:115], v[114:115]
	v_add_f32_e32 v128, v129, v128
	v_add_f32_e32 v128, v194, v128
	v_pk_mul_f32 v[166:167], v[116:117], v[116:117]
	v_add_f32_e32 v128, v195, v128
	v_add_f32_e32 v128, v166, v128
	v_add_f32_e32 v128, v167, v128
	v_add_f32_e32 v189, v189, v128
	v_pk_mul_f32 v[118:119], v[118:119], v[232:233]
	v_pk_mul_f32 v[124:125], v[116:117], v[238:239]
	v_pk_mul_f32 v[116:117], v[114:115], v[236:237]
	v_pk_mul_f32 v[120:121], v[120:121], v[234:235]
	v_cvt_pk_bf16_f32 v114, v118, v119
	s_nop 0
	v_cvt_pk_bf16_f32 v115, v120, v121
	v_cvt_pk_bf16_f32 v116, v116, v117
	v_cvt_pk_bf16_f32 v117, v124, v125
	flat_store_dwordx4 v[168:169], v[114:117] offset:256

; DI void st8(bf16_t* p, const pg8::f32x4& v0, const pg8::f32x4& v1) { u32x4 w; w.x = cvtpk(v0[0], v0[1]); w.y = cvtpk(v0[2], v0[3]); w.z = cvtpk(v1[0], v1[1]); w.w = cvtpk(v1[2], v1[3]); *(u32x4*)p = w; }
;     DI void operator()(const pg8::f32x4 (&acc)[2][2][4][2], const pg8::Unit& u, int wr, int wc, int fr, int fq) const {
;     ...
;         const int b = u.pm / 9, seg = u.pm - b * 9, mrow = seg == 0 ? 32 : b;
;         const float* gbase = mods + (size_t)mrow * 6144 + gidx * 1024; const float* gpb = gp + (size_t)mrow * 1024;
; #pragma unroll
;         for (int ai = 0; ai < 2; ++ai)
; #pragma unroll
;             for (int m = 0; m < 4; ++m) { const int rit = ai * 128 + wr * 64 + m * 16 + fr; float ss = 0.f;
;                 const size_t roff = (seg == 0 ? (size_t)(b * TC + rit) * DM : (size_t)(b * SEQ + (seg - 1) * 256 + rit) * DM);
; #pragma unroll
;                 for (int bj = 0; bj < 2; ++bj) { const int col0 = u.pn * 256 + bj * 128 + wc * 32 + 8 * fq;
;                     float* p = (seg == 0 ? xc : out) + roff + col0; const float* q = (seg == 0 ? sc : sx) + roff + col0;
;                     const pg8::f32x4 g0 = *(const pg8::f32x4*)(gbase + col0), g1 = *(const pg8::f32x4*)(gbase + col0 + 4); pg8::f32x4 x0 = *(const pg8::f32x4*)q, x1 = *(const pg8::f32x4*)(q + 4);
;                     x0 += g0 * acc[ai][bj][m][0]; x1 += g1 * acc[ai][bj][m][1]; *(pg8::f32x4*)p = x0; *(pg8::f32x4*)(p + 4) = x1;
;                     if (emit) { const pg8::f32x4 p0 = *(const pg8::f32x4*)(gpb + col0), p1 = *(const pg8::f32x4*)(gpb + col0 + 4);
;                         ss += x0[0] * x0[0] + x0[1] * x0[1] + x0[2] * x0[2] + x0[3] * x0[3] + x1[0] * x1[0] + x1[1] * x1[1] + x1[2] * x1[2] + x1[3] * x1[3];
;                         st8(H + (size_t)(u.pm * 256 + rit) * 1024 + col0, x0 * p0, x1 * p1); }
;                     __builtin_amdgcn_sched_barrier(0); }
;                 if (emit) { ss += __shfl_xor(ss, 16, 64); ss += __shfl_xor(ss, 32, 64); if (fq == 0) atomicAdd(rs + u.pm * 256 + rit, ss); }
.LBB0_886:
	v_add_u32_e32 v116, 16, v158
	v_add_u32_e32 v114, s2, v116
	s_waitcnt lgkmcnt(0)
	v_ashrrev_i32_e32 v115, 31, v114
	v_add_u32_e32 v116, s6, v116
	v_lshlrev_b64 v[114:115], 12, v[114:115]
	v_ashrrev_i32_e32 v117, 31, v116
	v_lshl_add_u64 v[114:115], s[58:59], 0, v[114:115]
	v_lshlrev_b64 v[120:121], 11, v[116:117]
	v_lshl_add_u64 v[114:115], v[160:161], 2, v[114:115]
	flat_load_dwordx4 v[166:169], v[114:115]
	flat_load_dwordx4 v[190:193], v[114:115] offset:16
	s_and_b64 vcc, exec, s[36:37]
	s_waitcnt vmcnt(0) lgkmcnt(0)
	v_pk_fma_f32 v[110:111], v[110:111], v[208:209], v[166:167]
	v_lshl_add_u64 v[116:117], s[64:65], 0, v[120:121]
	v_pk_fma_f32 v[112:113], v[112:113], v[210:211], v[168:169]
	v_pk_fma_f32 v[108:109], v[108:109], v[214:215], v[192:193]
	v_pk_fma_f32 v[106:107], v[106:107], v[212:213], v[190:191]
	v_mov_b32_e32 v118, 0
	v_lshl_add_u64 v[116:117], v[160:161], 1, v[116:117]
	flat_store_dwordx4 v[114:115], v[110:113]
	flat_store_dwordx4 v[114:115], v[106:109] offset:16
	s_cbranch_vccnz .LBB0_888
	v_pk_mul_f32 v[120:121], v[110:111], v[110:111]
	v_pk_mul_f32 v[118:119], v[112:113], v[112:113]
	v_add_f32_e32 v120, v120, v121
	v_add_f32_e32 v118, v118, v120
	v_pk_mul_f32 v[152:153], v[106:107], v[106:107]
	v_add_f32_e32 v118, v119, v118
	v_add_f32_e32 v118, v152, v118
	v_pk_mul_f32 v[128:129], v[108:109], v[108:109]
	v_add_f32_e32 v118, v153, v118
	v_add_f32_e32 v118, v128, v118
	v_add_f32_e32 v118, v129, v118
	v_pk_mul_f32 v[112:113], v[112:113], v[226:227]
	v_pk_mul_f32 v[120:121], v[108:109], v[230:231]
	v_pk_mul_f32 v[108:109], v[106:107], v[228:229]
	v_pk_mul_f32 v[110:111], v[110:111], v[224:225]
	s_nop 0
	v_cvt_pk_bf16_f32 v106, v110, v111
	v_cvt_pk_bf16_f32 v107, v112, v113
	v_cvt_pk_bf16_f32 v108, v108, v109
	v_cvt_pk_bf16_f32 v109, v120, v121
	flat_store_dwordx4 v[116:117], v[106:109]
.LBB0_888:
	flat_load_dwordx4 v[106:109], v[114:115] offset:512
	s_nop 0
	flat_load_dwordx4 v[166:169], v[114:115] offset:528
	s_and_b64 vcc, exec, s[36:37]
	s_waitcnt vmcnt(0) lgkmcnt(0)
	v_pk_fma_f32 v[104:105], v[104:105], v[218:219], v[108:109]
	v_pk_fma_f32 v[102:103], v[102:103], v[216:217], v[106:107]
	v_pk_fma_f32 v[100:101], v[100:101], v[222:223], v[168:169]
	v_pk_fma_f32 v[98:99], v[98:99], v[220:221], v[166:167]
	flat_store_dwordx4 v[114:115], v[102:105] offset:512
	flat_store_dwordx4 v[114:115], v[98:101] offset:528
	s_cbranch_vccnz .LBB0_890
	v_pk_mul_f32 v[120:121], v[102:103], v[102:103]
	v_pk_mul_f32 v[114:115], v[104:105], v[104:105]
	v_add_f32_e32 v119, v120, v121
	v_add_f32_e32 v114, v114, v119
	v_pk_mul_f32 v[126:127], v[98:99], v[98:99]
	v_add_f32_e32 v114, v115, v114
	v_add_f32_e32 v114, v126, v114
	v_pk_mul_f32 v[124:125], v[100:101], v[100:101]
	v_add_f32_e32 v114, v127, v114
	v_add_f32_e32 v114, v124, v114
	v_add_f32_e32 v114, v125, v114
	v_add_f32_e32 v118, v118, v114
	v_pk_mul_f32 v[102:103], v[102:103], v[232:233]
	v_pk_mul_f32 v[106:107], v[100:101], v[238:239]
	v_pk_mul_f32 v[100:101], v[98:99], v[236:237]
	v_pk_mul_f32 v[104:105], v[104:105], v[234:235]
	v_cvt_pk_bf16_f32 v98, v102, v103
	s_nop 0
	v_cvt_pk_bf16_f32 v99, v104, v105
	v_cvt_pk_bf16_f32 v100, v100, v101
	v_cvt_pk_bf16_f32 v101, v106, v107
	flat_store_dwordx4 v[116:117], v[98:101] offset:256

; DI void st8(bf16_t* p, const pg8::f32x4& v0, const pg8::f32x4& v1) { u32x4 w; w.x = cvtpk(v0[0], v0[1]); w.y = cvtpk(v0[2], v0[3]); w.z = cvtpk(v1[0], v1[1]); w.w = cvtpk(v1[2], v1[3]); *(u32x4*)p = w; }
;     DI void operator()(const pg8::f32x4 (&acc)[2][2][4][2], const pg8::Unit& u, int wr, int wc, int fr, int fq) const {
;     ...
;         const int b = u.pm / 9, seg = u.pm - b * 9, mrow = seg == 0 ? 32 : b;
;         const float* gbase = mods + (size_t)mrow * 6144 + gidx * 1024; const float* gpb = gp + (size_t)mrow * 1024;
; #pragma unroll
;         for (int ai = 0; ai < 2; ++ai)
; #pragma unroll
;             for (int m = 0; m < 4; ++m) { const int rit = ai * 128 + wr * 64 + m * 16 + fr; float ss = 0.f;
;                 const size_t roff = (seg == 0 ? (size_t)(b * TC + rit) * DM : (size_t)(b * SEQ + (seg - 1) * 256 + rit) * DM);
; #pragma unroll
;                 for (int bj = 0; bj < 2; ++bj) { const int col0 = u.pn * 256 + bj * 128 + wc * 32 + 8 * fq;
;                     float* p = (seg == 0 ? xc : out) + roff + col0; const float* q = (seg == 0 ? sc : sx) + roff + col0;
;                     const pg8::f32x4 g0 = *(const pg8::f32x4*)(gbase + col0), g1 = *(const pg8::f32x4*)(gbase + col0 + 4); pg8::f32x4 x0 = *(const pg8::f32x4*)q, x1 = *(const pg8::f32x4*)(q + 4);
;                     x0 += g0 * acc[ai][bj][m][0]; x1 += g1 * acc[ai][bj][m][1]; *(pg8::f32x4*)p = x0; *(pg8::f32x4*)(p + 4) = x1;
;                     if (emit) { const pg8::f32x4 p0 = *(const pg8::f32x4*)(gpb + col0), p1 = *(const pg8::f32x4*)(gpb + col0 + 4);
;                         ss += x0[0] * x0[0] + x0[1] * x0[1] + x0[2] * x0[2] + x0[3] * x0[3] + x1[0] * x1[0] + x1[1] * x1[1] + x1[2] * x1[2] + x1[3] * x1[3];
;                         st8(H + (size_t)(u.pm * 256 + rit) * 1024 + col0, x0 * p0, x1 * p1); }
;                     __builtin_amdgcn_sched_barrier(0); }
;                 if (emit) { ss += __shfl_xor(ss, 16, 64); ss += __shfl_xor(ss, 32, 64); if (fq == 0) atomicAdd(rs + u.pm * 256 + rit, ss); }
.LBB0_894:
	v_add_u32_e32 v100, 32, v158
	v_add_u32_e32 v98, s2, v100
	s_waitcnt lgkmcnt(0)
	v_ashrrev_i32_e32 v99, 31, v98
	v_add_u32_e32 v100, s6, v100
	v_lshlrev_b64 v[98:99], 12, v[98:99]
	v_ashrrev_i32_e32 v101, 31, v100
	v_lshl_add_u64 v[98:99], s[58:59], 0, v[98:99]
	v_lshlrev_b64 v[116:117], 11, v[100:101]
	v_lshl_add_u64 v[98:99], v[160:161], 2, v[98:99]
	flat_load_dwordx4 v[108:111], v[98:99]
	flat_load_dwordx4 v[112:115], v[98:99] offset:16
	s_and_b64 vcc, exec, s[36:37]
	s_waitcnt vmcnt(0) lgkmcnt(0)
	v_pk_fma_f32 v[94:95], v[94:95], v[208:209], v[108:109]
	v_lshl_add_u64 v[100:101], s[64:65], 0, v[116:117]
	v_pk_fma_f32 v[96:97], v[96:97], v[210:211], v[110:111]
	v_pk_fma_f32 v[92:93], v[92:93], v[214:215], v[114:115]
	v_pk_fma_f32 v[90:91], v[90:91], v[212:213], v[112:113]
	v_mov_b32_e32 v102, 0
	v_lshl_add_u64 v[100:101], v[160:161], 1, v[100:101]
	flat_store_dwordx4 v[98:99], v[94:97]
	flat_store_dwordx4 v[98:99], v[90:93] offset:16
	s_cbranch_vccnz .LBB0_896
	v_pk_mul_f32 v[112:113], v[94:95], v[94:95]
	v_pk_mul_f32 v[102:103], v[96:97], v[96:97]
	v_add_f32_e32 v112, v112, v113
	v_add_f32_e32 v102, v102, v112
	v_pk_mul_f32 v[116:117], v[90:91], v[90:91]
	v_add_f32_e32 v102, v103, v102
	v_add_f32_e32 v102, v116, v102
	v_pk_mul_f32 v[114:115], v[92:93], v[92:93]
	v_add_f32_e32 v102, v117, v102
	v_add_f32_e32 v102, v114, v102
	v_add_f32_e32 v102, v115, v102
	v_pk_mul_f32 v[94:95], v[94:95], v[224:225]
	v_pk_mul_f32 v[104:105], v[92:93], v[230:231]
	v_pk_mul_f32 v[92:93], v[90:91], v[228:229]
	v_pk_mul_f32 v[96:97], v[96:97], v[226:227]
	v_cvt_pk_bf16_f32 v90, v94, v95
	s_nop 0
	v_cvt_pk_bf16_f32 v91, v96, v97
	v_cvt_pk_bf16_f32 v92, v92, v93
	v_cvt_pk_bf16_f32 v93, v104, v105
	flat_store_dwordx4 v[100:101], v[90:93]
.LBB0_896:
	flat_load_dwordx4 v[90:93], v[98:99] offset:512
	s_nop 0
	flat_load_dwordx4 v[108:111], v[98:99] offset:528
	s_and_b64 vcc, exec, s[36:37]
	s_waitcnt vmcnt(0) lgkmcnt(0)
	v_pk_fma_f32 v[88:89], v[88:89], v[218:219], v[92:93]
	v_pk_fma_f32 v[86:87], v[86:87], v[216:217], v[90:91]
	v_pk_fma_f32 v[84:85], v[84:85], v[222:223], v[110:111]
	v_pk_fma_f32 v[82:83], v[82:83], v[220:221], v[108:109]
	flat_store_dwordx4 v[98:99], v[86:89] offset:512
	flat_store_dwordx4 v[98:99], v[82:85] offset:528
	s_cbranch_vccnz .LBB0_898
	v_pk_mul_f32 v[104:105], v[86:87], v[86:87]
	v_pk_mul_f32 v[98:99], v[88:89], v[88:89]
	v_add_f32_e32 v103, v104, v105
	v_add_f32_e32 v98, v98, v103
	v_pk_mul_f32 v[108:109], v[82:83], v[82:83]
	v_add_f32_e32 v98, v99, v98
	v_add_f32_e32 v98, v108, v98
	v_pk_mul_f32 v[106:107], v[84:85], v[84:85]
	v_add_f32_e32 v98, v109, v98
	v_add_f32_e32 v98, v106, v98
	v_add_f32_e32 v98, v107, v98
	v_add_f32_e32 v102, v102, v98
	v_pk_mul_f32 v[86:87], v[86:87], v[232:233]
	v_pk_mul_f32 v[90:91], v[84:85], v[238:239]
	v_pk_mul_f32 v[84:85], v[82:83], v[236:237]
	v_pk_mul_f32 v[88:89], v[88:89], v[234:235]
	v_cvt_pk_bf16_f32 v82, v86, v87
	s_nop 0
	v_cvt_pk_bf16_f32 v83, v88, v89
	v_cvt_pk_bf16_f32 v84, v84, v85
	v_cvt_pk_bf16_f32 v85, v90, v91
	flat_store_dwordx4 v[100:101], v[82:85] offset:256

; DI void st8(bf16_t* p, const pg8::f32x4& v0, const pg8::f32x4& v1) { u32x4 w; w.x = cvtpk(v0[0], v0[1]); w.y = cvtpk(v0[2], v0[3]); w.z = cvtpk(v1[0], v1[1]); w.w = cvtpk(v1[2], v1[3]); *(u32x4*)p = w; }
;     DI void operator()(const pg8::f32x4 (&acc)[2][2][4][2], const pg8::Unit& u, int wr, int wc, int fr, int fq) const {
;     ...
;         const int b = u.pm / 9, seg = u.pm - b * 9, mrow = seg == 0 ? 32 : b;
;         const float* gbase = mods + (size_t)mrow * 6144 + gidx * 1024; const float* gpb = gp + (size_t)mrow * 1024;
; #pragma unroll
;         for (int ai = 0; ai < 2; ++ai)
; #pragma unroll
;             for (int m = 0; m < 4; ++m) { const int rit = ai * 128 + wr * 64 + m * 16 + fr; float ss = 0.f;
;                 const size_t roff = (seg == 0 ? (size_t)(b * TC + rit) * DM : (size_t)(b * SEQ + (seg - 1) * 256 + rit) * DM);
; #pragma unroll
;                 for (int bj = 0; bj < 2; ++bj) { const int col0 = u.pn * 256 + bj * 128 + wc * 32 + 8 * fq;
;                     float* p = (seg == 0 ? xc : out) + roff + col0; const float* q = (seg == 0 ? sc : sx) + roff + col0;
;                     const pg8::f32x4 g0 = *(const pg8::f32x4*)(gbase + col0), g1 = *(const pg8::f32x4*)(gbase + col0 + 4); pg8::f32x4 x0 = *(const pg8::f32x4*)q, x1 = *(const pg8::f32x4*)(q + 4);
;                     x0 += g0 * acc[ai][bj][m][0]; x1 += g1 * acc[ai][bj][m][1]; *(pg8::f32x4*)p = x0; *(pg8::f32x4*)(p + 4) = x1;
;                     if (emit) { const pg8::f32x4 p0 = *(const pg8::f32x4*)(gpb + col0), p1 = *(const pg8::f32x4*)(gpb + col0 + 4);
;                         ss += x0[0] * x0[0] + x0[1] * x0[1] + x0[2] * x0[2] + x0[3] * x0[3] + x1[0] * x1[0] + x1[1] * x1[1] + x1[2] * x1[2] + x1[3] * x1[3];
;                         st8(H + (size_t)(u.pm * 256 + rit) * 1024 + col0, x0 * p0, x1 * p1); }
;                     __builtin_amdgcn_sched_barrier(0); }
;                 if (emit) { ss += __shfl_xor(ss, 16, 64); ss += __shfl_xor(ss, 32, 64); if (fq == 0) atomicAdd(rs + u.pm * 256 + rit, ss); }
.LBB0_902:
	v_add_u32_e32 v84, 48, v158
	v_add_u32_e32 v82, s2, v84
	s_waitcnt lgkmcnt(0)
	v_ashrrev_i32_e32 v83, 31, v82
	v_add_u32_e32 v84, s6, v84
	v_lshlrev_b64 v[82:83], 12, v[82:83]
	v_ashrrev_i32_e32 v85, 31, v84
	v_lshl_add_u64 v[82:83], s[58:59], 0, v[82:83]
	v_lshlrev_b64 v[100:101], 11, v[84:85]
	v_lshl_add_u64 v[82:83], v[160:161], 2, v[82:83]
	flat_load_dwordx4 v[92:95], v[82:83]
	flat_load_dwordx4 v[96:99], v[82:83] offset:16
	s_and_b64 vcc, exec, s[36:37]
	s_waitcnt vmcnt(0) lgkmcnt(0)
	v_pk_fma_f32 v[78:79], v[78:79], v[208:209], v[92:93]
	v_lshl_add_u64 v[84:85], s[64:65], 0, v[100:101]
	v_pk_fma_f32 v[80:81], v[80:81], v[210:211], v[94:95]
	v_pk_fma_f32 v[76:77], v[76:77], v[214:215], v[98:99]
	v_pk_fma_f32 v[74:75], v[74:75], v[212:213], v[96:97]
	v_mov_b32_e32 v86, 0
	v_lshl_add_u64 v[84:85], v[160:161], 1, v[84:85]
	flat_store_dwordx4 v[82:83], v[78:81]
	flat_store_dwordx4 v[82:83], v[74:77] offset:16
	s_cbranch_vccnz .LBB0_904
	v_pk_mul_f32 v[96:97], v[78:79], v[78:79]
	v_pk_mul_f32 v[86:87], v[80:81], v[80:81]
	v_add_f32_e32 v96, v96, v97
	v_add_f32_e32 v86, v86, v96
	v_pk_mul_f32 v[100:101], v[74:75], v[74:75]
	v_add_f32_e32 v86, v87, v86
	v_add_f32_e32 v86, v100, v86
	v_pk_mul_f32 v[98:99], v[76:77], v[76:77]
	v_add_f32_e32 v86, v101, v86
	v_add_f32_e32 v86, v98, v86
	v_add_f32_e32 v86, v99, v86
	v_pk_mul_f32 v[78:79], v[78:79], v[224:225]
	v_pk_mul_f32 v[88:89], v[76:77], v[230:231]
	v_pk_mul_f32 v[76:77], v[74:75], v[228:229]
	v_pk_mul_f32 v[80:81], v[80:81], v[226:227]
	v_cvt_pk_bf16_f32 v74, v78, v79
	s_nop 0
	v_cvt_pk_bf16_f32 v75, v80, v81
	v_cvt_pk_bf16_f32 v76, v76, v77
	v_cvt_pk_bf16_f32 v77, v88, v89
	flat_store_dwordx4 v[84:85], v[74:77]
.LBB0_904:
	flat_load_dwordx4 v[74:77], v[82:83] offset:512
	s_nop 0
	flat_load_dwordx4 v[92:95], v[82:83] offset:528
	s_and_b64 vcc, exec, s[36:37]
	s_waitcnt vmcnt(0) lgkmcnt(0)
	v_pk_fma_f32 v[72:73], v[72:73], v[218:219], v[76:77]
	v_pk_fma_f32 v[70:71], v[70:71], v[216:217], v[74:75]
	v_pk_fma_f32 v[68:69], v[68:69], v[222:223], v[94:95]
	v_pk_fma_f32 v[66:67], v[66:67], v[220:221], v[92:93]
	flat_store_dwordx4 v[82:83], v[70:73] offset:512
	flat_store_dwordx4 v[82:83], v[66:69] offset:528
	s_cbranch_vccnz .LBB0_906
	v_pk_mul_f32 v[88:89], v[70:71], v[70:71]
	v_pk_mul_f32 v[82:83], v[72:73], v[72:73]
	v_add_f32_e32 v87, v88, v89
	v_add_f32_e32 v82, v82, v87
	v_pk_mul_f32 v[92:93], v[66:67], v[66:67]
	v_add_f32_e32 v82, v83, v82
	v_add_f32_e32 v82, v92, v82
	v_pk_mul_f32 v[90:91], v[68:69], v[68:69]
	v_add_f32_e32 v82, v93, v82
	v_add_f32_e32 v82, v90, v82
	v_add_f32_e32 v82, v91, v82
	v_add_f32_e32 v86, v86, v82
	v_pk_mul_f32 v[70:71], v[70:71], v[232:233]
	v_pk_mul_f32 v[74:75], v[68:69], v[238:239]
	v_pk_mul_f32 v[68:69], v[66:67], v[236:237]
	v_pk_mul_f32 v[72:73], v[72:73], v[234:235]
	v_cvt_pk_bf16_f32 v66, v70, v71
	s_nop 0
	v_cvt_pk_bf16_f32 v67, v72, v73
	v_cvt_pk_bf16_f32 v68, v68, v69
	v_cvt_pk_bf16_f32 v69, v74, v75
	flat_store_dwordx4 v[84:85], v[66:69] offset:256

; DI void st8(bf16_t* p, const pg8::f32x4& v0, const pg8::f32x4& v1) { u32x4 w; w.x = cvtpk(v0[0], v0[1]); w.y = cvtpk(v0[2], v0[3]); w.z = cvtpk(v1[0], v1[1]); w.w = cvtpk(v1[2], v1[3]); *(u32x4*)p = w; }
;     DI void operator()(const pg8::f32x4 (&acc)[2][2][4][2], const pg8::Unit& u, int wr, int wc, int fr, int fq) const {
;     ...
;         const int b = u.pm / 9, seg = u.pm - b * 9, mrow = seg == 0 ? 32 : b;
;         const float* gbase = mods + (size_t)mrow * 6144 + gidx * 1024; const float* gpb = gp + (size_t)mrow * 1024;
; #pragma unroll
;         for (int ai = 0; ai < 2; ++ai)
; #pragma unroll
;             for (int m = 0; m < 4; ++m) { const int rit = ai * 128 + wr * 64 + m * 16 + fr; float ss = 0.f;
;                 const size_t roff = (seg == 0 ? (size_t)(b * TC + rit) * DM : (size_t)(b * SEQ + (seg - 1) * 256 + rit) * DM);
; #pragma unroll
;                 for (int bj = 0; bj < 2; ++bj) { const int col0 = u.pn * 256 + bj * 128 + wc * 32 + 8 * fq;
;                     float* p = (seg == 0 ? xc : out) + roff + col0; const float* q = (seg == 0 ? sc : sx) + roff + col0;
;                     const pg8::f32x4 g0 = *(const pg8::f32x4*)(gbase + col0), g1 = *(const pg8::f32x4*)(gbase + col0 + 4); pg8::f32x4 x0 = *(const pg8::f32x4*)q, x1 = *(const pg8::f32x4*)(q + 4);
;                     x0 += g0 * acc[ai][bj][m][0]; x1 += g1 * acc[ai][bj][m][1]; *(pg8::f32x4*)p = x0; *(pg8::f32x4*)(p + 4) = x1;
;                     if (emit) { const pg8::f32x4 p0 = *(const pg8::f32x4*)(gpb + col0), p1 = *(const pg8::f32x4*)(gpb + col0 + 4);
;                         ss += x0[0] * x0[0] + x0[1] * x0[1] + x0[2] * x0[2] + x0[3] * x0[3] + x1[0] * x1[0] + x1[1] * x1[1] + x1[2] * x1[2] + x1[3] * x1[3];
;                         st8(H + (size_t)(u.pm * 256 + rit) * 1024 + col0, x0 * p0, x1 * p1); }
;                     __builtin_amdgcn_sched_barrier(0); }
;                 if (emit) { ss += __shfl_xor(ss, 16, 64); ss += __shfl_xor(ss, 32, 64); if (fq == 0) atomicAdd(rs + u.pm * 256 + rit, ss); }
.LBB0_910:
	v_add_u32_e32 v68, 0x80, v158
	v_add_u32_e32 v66, s2, v68
	s_waitcnt lgkmcnt(0)
	v_ashrrev_i32_e32 v67, 31, v66
	v_add_u32_e32 v68, s6, v68
	v_lshlrev_b64 v[66:67], 12, v[66:67]
	v_ashrrev_i32_e32 v69, 31, v68
	v_lshl_add_u64 v[66:67], s[58:59], 0, v[66:67]
	v_lshlrev_b64 v[84:85], 11, v[68:69]
	v_lshl_add_u64 v[66:67], v[160:161], 2, v[66:67]
	flat_load_dwordx4 v[76:79], v[66:67]
	flat_load_dwordx4 v[80:83], v[66:67] offset:16
	s_and_b64 vcc, exec, s[36:37]
	s_waitcnt vmcnt(0) lgkmcnt(0)
	v_pk_fma_f32 v[62:63], v[62:63], v[208:209], v[76:77]
	v_lshl_add_u64 v[68:69], s[64:65], 0, v[84:85]
	v_pk_fma_f32 v[64:65], v[64:65], v[210:211], v[78:79]
	v_pk_fma_f32 v[60:61], v[60:61], v[214:215], v[82:83]
	v_pk_fma_f32 v[58:59], v[58:59], v[212:213], v[80:81]
	v_mov_b32_e32 v70, 0
	v_lshl_add_u64 v[68:69], v[160:161], 1, v[68:69]
	flat_store_dwordx4 v[66:67], v[62:65]
	flat_store_dwordx4 v[66:67], v[58:61] offset:16
	s_cbranch_vccnz .LBB0_912
	v_pk_mul_f32 v[80:81], v[62:63], v[62:63]
	v_pk_mul_f32 v[70:71], v[64:65], v[64:65]
	v_add_f32_e32 v80, v80, v81
	v_add_f32_e32 v70, v70, v80
	v_pk_mul_f32 v[84:85], v[58:59], v[58:59]
	v_add_f32_e32 v70, v71, v70
	v_add_f32_e32 v70, v84, v70
	v_pk_mul_f32 v[82:83], v[60:61], v[60:61]
	v_add_f32_e32 v70, v85, v70
	v_add_f32_e32 v70, v82, v70
	v_add_f32_e32 v70, v83, v70
	v_pk_mul_f32 v[62:63], v[62:63], v[224:225]
	v_pk_mul_f32 v[72:73], v[60:61], v[230:231]
	v_pk_mul_f32 v[60:61], v[58:59], v[228:229]
	v_pk_mul_f32 v[64:65], v[64:65], v[226:227]
	v_cvt_pk_bf16_f32 v58, v62, v63
	s_nop 0
	v_cvt_pk_bf16_f32 v59, v64, v65
	v_cvt_pk_bf16_f32 v60, v60, v61
	v_cvt_pk_bf16_f32 v61, v72, v73
	flat_store_dwordx4 v[68:69], v[58:61]
.LBB0_912:
	flat_load_dwordx4 v[58:61], v[66:67] offset:512
	s_nop 0
	flat_load_dwordx4 v[76:79], v[66:67] offset:528
	s_and_b64 vcc, exec, s[36:37]
	s_waitcnt vmcnt(0) lgkmcnt(0)
	v_pk_fma_f32 v[56:57], v[56:57], v[218:219], v[60:61]
	v_pk_fma_f32 v[54:55], v[54:55], v[216:217], v[58:59]
	v_pk_fma_f32 v[52:53], v[52:53], v[222:223], v[78:79]
	v_pk_fma_f32 v[50:51], v[50:51], v[220:221], v[76:77]
	flat_store_dwordx4 v[66:67], v[54:57] offset:512
	flat_store_dwordx4 v[66:67], v[50:53] offset:528
	s_cbranch_vccnz .LBB0_914
	v_pk_mul_f32 v[72:73], v[54:55], v[54:55]
	v_pk_mul_f32 v[66:67], v[56:57], v[56:57]
	v_add_f32_e32 v71, v72, v73
	v_add_f32_e32 v66, v66, v71
	v_pk_mul_f32 v[76:77], v[50:51], v[50:51]
	v_add_f32_e32 v66, v67, v66
	v_add_f32_e32 v66, v76, v66
	v_pk_mul_f32 v[74:75], v[52:53], v[52:53]
	v_add_f32_e32 v66, v77, v66
	v_add_f32_e32 v66, v74, v66
	v_add_f32_e32 v66, v75, v66
	v_add_f32_e32 v70, v70, v66
	v_pk_mul_f32 v[54:55], v[54:55], v[232:233]
	v_pk_mul_f32 v[58:59], v[52:53], v[238:239]
	v_pk_mul_f32 v[52:53], v[50:51], v[236:237]
	v_pk_mul_f32 v[56:57], v[56:57], v[234:235]
	v_cvt_pk_bf16_f32 v50, v54, v55
	s_nop 0
	v_cvt_pk_bf16_f32 v51, v56, v57
	v_cvt_pk_bf16_f32 v52, v52, v53
	v_cvt_pk_bf16_f32 v53, v58, v59
	flat_store_dwordx4 v[68:69], v[50:53] offset:256

; DI void st8(bf16_t* p, const pg8::f32x4& v0, const pg8::f32x4& v1) { u32x4 w; w.x = cvtpk(v0[0], v0[1]); w.y = cvtpk(v0[2], v0[3]); w.z = cvtpk(v1[0], v1[1]); w.w = cvtpk(v1[2], v1[3]); *(u32x4*)p = w; }
;     DI void operator()(const pg8::f32x4 (&acc)[2][2][4][2], const pg8::Unit& u, int wr, int wc, int fr, int fq) const {
;     ...
;         const int b = u.pm / 9, seg = u.pm - b * 9, mrow = seg == 0 ? 32 : b;
;         const float* gbase = mods + (size_t)mrow * 6144 + gidx * 1024; const float* gpb = gp + (size_t)mrow * 1024;
; #pragma unroll
;         for (int ai = 0; ai < 2; ++ai)
; #pragma unroll
;             for (int m = 0; m < 4; ++m) { const int rit = ai * 128 + wr * 64 + m * 16 + fr; float ss = 0.f;
;                 const size_t roff = (seg == 0 ? (size_t)(b * TC + rit) * DM : (size_t)(b * SEQ + (seg - 1) * 256 + rit) * DM);
; #pragma unroll
;                 for (int bj = 0; bj < 2; ++bj) { const int col0 = u.pn * 256 + bj * 128 + wc * 32 + 8 * fq;
;                     float* p = (seg == 0 ? xc : out) + roff + col0; const float* q = (seg == 0 ? sc : sx) + roff + col0;
;                     const pg8::f32x4 g0 = *(const pg8::f32x4*)(gbase + col0), g1 = *(const pg8::f32x4*)(gbase + col0 + 4); pg8::f32x4 x0 = *(const pg8::f32x4*)q, x1 = *(const pg8::f32x4*)(q + 4);
;                     x0 += g0 * acc[ai][bj][m][0]; x1 += g1 * acc[ai][bj][m][1]; *(pg8::f32x4*)p = x0; *(pg8::f32x4*)(p + 4) = x1;
;                     if (emit) { const pg8::f32x4 p0 = *(const pg8::f32x4*)(gpb + col0), p1 = *(const pg8::f32x4*)(gpb + col0 + 4);
;                         ss += x0[0] * x0[0] + x0[1] * x0[1] + x0[2] * x0[2] + x0[3] * x0[3] + x1[0] * x1[0] + x1[1] * x1[1] + x1[2] * x1[2] + x1[3] * x1[3];
;                         st8(H + (size_t)(u.pm * 256 + rit) * 1024 + col0, x0 * p0, x1 * p1); }
;                     __builtin_amdgcn_sched_barrier(0); }
;                 if (emit) { ss += __shfl_xor(ss, 16, 64); ss += __shfl_xor(ss, 32, 64); if (fq == 0) atomicAdd(rs + u.pm * 256 + rit, ss); }
.LBB0_918:
	v_add_u32_e32 v52, 0x90, v158
	v_add_u32_e32 v50, s2, v52
	s_waitcnt lgkmcnt(0)
	v_ashrrev_i32_e32 v51, 31, v50
	v_add_u32_e32 v52, s6, v52
	v_lshlrev_b64 v[50:51], 12, v[50:51]
	v_ashrrev_i32_e32 v53, 31, v52
	v_lshl_add_u64 v[50:51], s[58:59], 0, v[50:51]
	v_lshlrev_b64 v[68:69], 11, v[52:53]
	v_lshl_add_u64 v[50:51], v[160:161], 2, v[50:51]
	flat_load_dwordx4 v[60:63], v[50:51]
	flat_load_dwordx4 v[64:67], v[50:51] offset:16
	s_and_b64 vcc, exec, s[36:37]
	s_waitcnt vmcnt(0) lgkmcnt(0)
	v_pk_fma_f32 v[46:47], v[46:47], v[208:209], v[60:61]
	v_lshl_add_u64 v[52:53], s[64:65], 0, v[68:69]
	v_pk_fma_f32 v[48:49], v[48:49], v[210:211], v[62:63]
	v_pk_fma_f32 v[44:45], v[44:45], v[214:215], v[66:67]
	v_pk_fma_f32 v[42:43], v[42:43], v[212:213], v[64:65]
	v_mov_b32_e32 v54, 0
	v_lshl_add_u64 v[52:53], v[160:161], 1, v[52:53]
	flat_store_dwordx4 v[50:51], v[46:49]
	flat_store_dwordx4 v[50:51], v[42:45] offset:16
	s_cbranch_vccnz .LBB0_920
	v_pk_mul_f32 v[64:65], v[46:47], v[46:47]
	v_pk_mul_f32 v[54:55], v[48:49], v[48:49]
	v_add_f32_e32 v64, v64, v65
	v_add_f32_e32 v54, v54, v64
	v_pk_mul_f32 v[68:69], v[42:43], v[42:43]
	v_add_f32_e32 v54, v55, v54
	v_add_f32_e32 v54, v68, v54
	v_pk_mul_f32 v[66:67], v[44:45], v[44:45]
	v_add_f32_e32 v54, v69, v54
	v_add_f32_e32 v54, v66, v54
	v_add_f32_e32 v54, v67, v54
	v_pk_mul_f32 v[46:47], v[46:47], v[224:225]
	v_pk_mul_f32 v[56:57], v[44:45], v[230:231]
	v_pk_mul_f32 v[44:45], v[42:43], v[228:229]
	v_pk_mul_f32 v[48:49], v[48:49], v[226:227]
	v_cvt_pk_bf16_f32 v42, v46, v47
	s_nop 0
	v_cvt_pk_bf16_f32 v43, v48, v49
	v_cvt_pk_bf16_f32 v44, v44, v45
	v_cvt_pk_bf16_f32 v45, v56, v57
	flat_store_dwordx4 v[52:53], v[42:45]
.LBB0_920:
	flat_load_dwordx4 v[42:45], v[50:51] offset:512
	s_nop 0
	flat_load_dwordx4 v[60:63], v[50:51] offset:528
	s_and_b64 vcc, exec, s[36:37]
	s_waitcnt vmcnt(0) lgkmcnt(0)
	v_pk_fma_f32 v[40:41], v[40:41], v[218:219], v[44:45]
	v_pk_fma_f32 v[38:39], v[38:39], v[216:217], v[42:43]
	v_pk_fma_f32 v[36:37], v[36:37], v[222:223], v[62:63]
	v_pk_fma_f32 v[34:35], v[34:35], v[220:221], v[60:61]
	flat_store_dwordx4 v[50:51], v[38:41] offset:512
	flat_store_dwordx4 v[50:51], v[34:37] offset:528
	s_cbranch_vccnz .LBB0_922
	v_pk_mul_f32 v[56:57], v[38:39], v[38:39]
	v_pk_mul_f32 v[50:51], v[40:41], v[40:41]
	v_add_f32_e32 v55, v56, v57
	v_add_f32_e32 v50, v50, v55
	v_pk_mul_f32 v[60:61], v[34:35], v[34:35]
	v_add_f32_e32 v50, v51, v50
	v_add_f32_e32 v50, v60, v50
	v_pk_mul_f32 v[58:59], v[36:37], v[36:37]
	v_add_f32_e32 v50, v61, v50
	v_add_f32_e32 v50, v58, v50
	v_add_f32_e32 v50, v59, v50
	v_add_f32_e32 v54, v54, v50
	v_pk_mul_f32 v[38:39], v[38:39], v[232:233]
	v_pk_mul_f32 v[42:43], v[36:37], v[238:239]
	v_pk_mul_f32 v[36:37], v[34:35], v[236:237]
	v_pk_mul_f32 v[40:41], v[40:41], v[234:235]
	v_cvt_pk_bf16_f32 v34, v38, v39
	s_nop 0
	v_cvt_pk_bf16_f32 v35, v40, v41
	v_cvt_pk_bf16_f32 v36, v36, v37
	v_cvt_pk_bf16_f32 v37, v42, v43
	flat_store_dwordx4 v[52:53], v[34:37] offset:256

; DI void st8(bf16_t* p, const pg8::f32x4& v0, const pg8::f32x4& v1) { u32x4 w; w.x = cvtpk(v0[0], v0[1]); w.y = cvtpk(v0[2], v0[3]); w.z = cvtpk(v1[0], v1[1]); w.w = cvtpk(v1[2], v1[3]); *(u32x4*)p = w; }
;     DI void operator()(const pg8::f32x4 (&acc)[2][2][4][2], const pg8::Unit& u, int wr, int wc, int fr, int fq) const {
;     ...
;         const int b = u.pm / 9, seg = u.pm - b * 9, mrow = seg == 0 ? 32 : b;
;         const float* gbase = mods + (size_t)mrow * 6144 + gidx * 1024; const float* gpb = gp + (size_t)mrow * 1024;
; #pragma unroll
;         for (int ai = 0; ai < 2; ++ai)
; #pragma unroll
;             for (int m = 0; m < 4; ++m) { const int rit = ai * 128 + wr * 64 + m * 16 + fr; float ss = 0.f;
;                 const size_t roff = (seg == 0 ? (size_t)(b * TC + rit) * DM : (size_t)(b * SEQ + (seg - 1) * 256 + rit) * DM);
; #pragma unroll
;                 for (int bj = 0; bj < 2; ++bj) { const int col0 = u.pn * 256 + bj * 128 + wc * 32 + 8 * fq;
;                     float* p = (seg == 0 ? xc : out) + roff + col0; const float* q = (seg == 0 ? sc : sx) + roff + col0;
;                     const pg8::f32x4 g0 = *(const pg8::f32x4*)(gbase + col0), g1 = *(const pg8::f32x4*)(gbase + col0 + 4); pg8::f32x4 x0 = *(const pg8::f32x4*)q, x1 = *(const pg8::f32x4*)(q + 4);
;                     x0 += g0 * acc[ai][bj][m][0]; x1 += g1 * acc[ai][bj][m][1]; *(pg8::f32x4*)p = x0; *(pg8::f32x4*)(p + 4) = x1;
;                     if (emit) { const pg8::f32x4 p0 = *(const pg8::f32x4*)(gpb + col0), p1 = *(const pg8::f32x4*)(gpb + col0 + 4);
;                         ss += x0[0] * x0[0] + x0[1] * x0[1] + x0[2] * x0[2] + x0[3] * x0[3] + x1[0] * x1[0] + x1[1] * x1[1] + x1[2] * x1[2] + x1[3] * x1[3];
;                         st8(H + (size_t)(u.pm * 256 + rit) * 1024 + col0, x0 * p0, x1 * p1); }
;                     __builtin_amdgcn_sched_barrier(0); }
;                 if (emit) { ss += __shfl_xor(ss, 16, 64); ss += __shfl_xor(ss, 32, 64); if (fq == 0) atomicAdd(rs + u.pm * 256 + rit, ss); }
.LBB0_926:
	v_add_u32_e32 v36, 0xa0, v158
	v_add_u32_e32 v34, s2, v36
	s_waitcnt lgkmcnt(0)
	v_ashrrev_i32_e32 v35, 31, v34
	v_add_u32_e32 v36, s6, v36
	v_lshlrev_b64 v[34:35], 12, v[34:35]
	v_ashrrev_i32_e32 v37, 31, v36
	v_lshl_add_u64 v[34:35], s[58:59], 0, v[34:35]
	v_lshlrev_b64 v[52:53], 11, v[36:37]
	v_lshl_add_u64 v[34:35], v[160:161], 2, v[34:35]
	flat_load_dwordx4 v[44:47], v[34:35]
	flat_load_dwordx4 v[48:51], v[34:35] offset:16
	s_and_b64 vcc, exec, s[36:37]
	s_waitcnt vmcnt(0) lgkmcnt(0)
	v_pk_fma_f32 v[30:31], v[30:31], v[208:209], v[44:45]
	v_lshl_add_u64 v[36:37], s[64:65], 0, v[52:53]
	v_pk_fma_f32 v[32:33], v[32:33], v[210:211], v[46:47]
	v_pk_fma_f32 v[28:29], v[28:29], v[214:215], v[50:51]
	v_pk_fma_f32 v[26:27], v[26:27], v[212:213], v[48:49]
	v_mov_b32_e32 v38, 0
	v_lshl_add_u64 v[36:37], v[160:161], 1, v[36:37]
	flat_store_dwordx4 v[34:35], v[30:33]
	flat_store_dwordx4 v[34:35], v[26:29] offset:16
	s_cbranch_vccnz .LBB0_928
	v_pk_mul_f32 v[48:49], v[30:31], v[30:31]
	v_pk_mul_f32 v[38:39], v[32:33], v[32:33]
	v_add_f32_e32 v48, v48, v49
	v_add_f32_e32 v38, v38, v48
	v_pk_mul_f32 v[52:53], v[26:27], v[26:27]
	v_add_f32_e32 v38, v39, v38
	v_add_f32_e32 v38, v52, v38
	v_pk_mul_f32 v[50:51], v[28:29], v[28:29]
	v_add_f32_e32 v38, v53, v38
	v_add_f32_e32 v38, v50, v38
	v_add_f32_e32 v38, v51, v38
	v_pk_mul_f32 v[30:31], v[30:31], v[224:225]
	v_pk_mul_f32 v[40:41], v[28:29], v[230:231]
	v_pk_mul_f32 v[28:29], v[26:27], v[228:229]
	v_pk_mul_f32 v[32:33], v[32:33], v[226:227]
	v_cvt_pk_bf16_f32 v26, v30, v31
	s_nop 0
	v_cvt_pk_bf16_f32 v27, v32, v33
	v_cvt_pk_bf16_f32 v28, v28, v29
	v_cvt_pk_bf16_f32 v29, v40, v41
	flat_store_dwordx4 v[36:37], v[26:29]
.LBB0_928:
	flat_load_dwordx4 v[26:29], v[34:35] offset:512
	s_nop 0
	flat_load_dwordx4 v[44:47], v[34:35] offset:528
	s_and_b64 vcc, exec, s[36:37]
	s_waitcnt vmcnt(0) lgkmcnt(0)
	v_pk_fma_f32 v[24:25], v[24:25], v[218:219], v[28:29]
	v_pk_fma_f32 v[22:23], v[22:23], v[216:217], v[26:27]
	v_pk_fma_f32 v[20:21], v[20:21], v[222:223], v[46:47]
	v_pk_fma_f32 v[18:19], v[18:19], v[220:221], v[44:45]
	flat_store_dwordx4 v[34:35], v[22:25] offset:512
	flat_store_dwordx4 v[34:35], v[18:21] offset:528
	s_cbranch_vccnz .LBB0_930
	v_pk_mul_f32 v[40:41], v[22:23], v[22:23]
	v_pk_mul_f32 v[34:35], v[24:25], v[24:25]
	v_add_f32_e32 v39, v40, v41
	v_add_f32_e32 v34, v34, v39
	v_pk_mul_f32 v[44:45], v[18:19], v[18:19]
	v_add_f32_e32 v34, v35, v34
	v_add_f32_e32 v34, v44, v34
	v_pk_mul_f32 v[42:43], v[20:21], v[20:21]
	v_add_f32_e32 v34, v45, v34
	v_add_f32_e32 v34, v42, v34
	v_add_f32_e32 v34, v43, v34
	v_add_f32_e32 v38, v38, v34
	v_pk_mul_f32 v[22:23], v[22:23], v[232:233]
	v_pk_mul_f32 v[26:27], v[20:21], v[238:239]
	v_pk_mul_f32 v[20:21], v[18:19], v[236:237]
	v_pk_mul_f32 v[24:25], v[24:25], v[234:235]
	v_cvt_pk_bf16_f32 v18, v22, v23
	s_nop 0
	v_cvt_pk_bf16_f32 v19, v24, v25
	v_cvt_pk_bf16_f32 v20, v20, v21
	v_cvt_pk_bf16_f32 v21, v26, v27
	flat_store_dwordx4 v[36:37], v[18:21] offset:256

; DI void st8(bf16_t* p, const pg8::f32x4& v0, const pg8::f32x4& v1) { u32x4 w; w.x = cvtpk(v0[0], v0[1]); w.y = cvtpk(v0[2], v0[3]); w.z = cvtpk(v1[0], v1[1]); w.w = cvtpk(v1[2], v1[3]); *(u32x4*)p = w; }
;     DI void operator()(const pg8::f32x4 (&acc)[2][2][4][2], const pg8::Unit& u, int wr, int wc, int fr, int fq) const {
;     ...
;         const int b = u.pm / 9, seg = u.pm - b * 9, mrow = seg == 0 ? 32 : b;
;         const float* gbase = mods + (size_t)mrow * 6144 + gidx * 1024; const float* gpb = gp + (size_t)mrow * 1024;
; #pragma unroll
;         for (int ai = 0; ai < 2; ++ai)
; #pragma unroll
;             for (int m = 0; m < 4; ++m) { const int rit = ai * 128 + wr * 64 + m * 16 + fr; float ss = 0.f;
;                 const size_t roff = (seg == 0 ? (size_t)(b * TC + rit) * DM : (size_t)(b * SEQ + (seg - 1) * 256 + rit) * DM);
; #pragma unroll
;                 for (int bj = 0; bj < 2; ++bj) { const int col0 = u.pn * 256 + bj * 128 + wc * 32 + 8 * fq;
;                     float* p = (seg == 0 ? xc : out) + roff + col0; const float* q = (seg == 0 ? sc : sx) + roff + col0;
;                     const pg8::f32x4 g0 = *(const pg8::f32x4*)(gbase + col0), g1 = *(const pg8::f32x4*)(gbase + col0 + 4); pg8::f32x4 x0 = *(const pg8::f32x4*)q, x1 = *(const pg8::f32x4*)(q + 4);
;                     x0 += g0 * acc[ai][bj][m][0]; x1 += g1 * acc[ai][bj][m][1]; *(pg8::f32x4*)p = x0; *(pg8::f32x4*)(p + 4) = x1;
;                     if (emit) { const pg8::f32x4 p0 = *(const pg8::f32x4*)(gpb + col0), p1 = *(const pg8::f32x4*)(gpb + col0 + 4);
;                         ss += x0[0] * x0[0] + x0[1] * x0[1] + x0[2] * x0[2] + x0[3] * x0[3] + x1[0] * x1[0] + x1[1] * x1[1] + x1[2] * x1[2] + x1[3] * x1[3];
;                         st8(H + (size_t)(u.pm * 256 + rit) * 1024 + col0, x0 * p0, x1 * p1); }
;                     __builtin_amdgcn_sched_barrier(0); }
;                 if (emit) { ss += __shfl_xor(ss, 16, 64); ss += __shfl_xor(ss, 32, 64); if (fq == 0) atomicAdd(rs + u.pm * 256 + rit, ss); }
.LBB0_934:
	v_add_u32_e32 v20, 0xb0, v158
	v_add_u32_e32 v18, s2, v20
	s_waitcnt lgkmcnt(0)
	v_ashrrev_i32_e32 v19, 31, v18
	v_add_u32_e32 v20, s6, v20
	v_lshlrev_b64 v[18:19], 12, v[18:19]
	v_ashrrev_i32_e32 v21, 31, v20
	v_lshl_add_u64 v[18:19], s[58:59], 0, v[18:19]
	v_lshlrev_b64 v[36:37], 11, v[20:21]
	v_lshl_add_u64 v[18:19], v[160:161], 2, v[18:19]
	flat_load_dwordx4 v[28:31], v[18:19]
	flat_load_dwordx4 v[32:35], v[18:19] offset:16
	s_and_b64 vcc, exec, s[36:37]
	s_waitcnt vmcnt(0) lgkmcnt(0)
	v_pk_fma_f32 v[14:15], v[14:15], v[208:209], v[28:29]
	v_lshl_add_u64 v[20:21], s[64:65], 0, v[36:37]
	v_pk_fma_f32 v[16:17], v[16:17], v[210:211], v[30:31]
	v_pk_fma_f32 v[12:13], v[12:13], v[214:215], v[34:35]
	v_pk_fma_f32 v[10:11], v[10:11], v[212:213], v[32:33]
	v_mov_b32_e32 v22, 0
	v_lshl_add_u64 v[20:21], v[160:161], 1, v[20:21]
	flat_store_dwordx4 v[18:19], v[14:17]
	flat_store_dwordx4 v[18:19], v[10:13] offset:16
	s_cbranch_vccnz .LBB0_936
	v_pk_mul_f32 v[32:33], v[14:15], v[14:15]
	v_pk_mul_f32 v[22:23], v[16:17], v[16:17]
	v_add_f32_e32 v32, v32, v33
	v_add_f32_e32 v22, v22, v32
	v_pk_mul_f32 v[36:37], v[10:11], v[10:11]
	v_add_f32_e32 v22, v23, v22
	v_add_f32_e32 v22, v36, v22
	v_pk_mul_f32 v[34:35], v[12:13], v[12:13]
	v_add_f32_e32 v22, v37, v22
	v_add_f32_e32 v22, v34, v22
	v_add_f32_e32 v22, v35, v22
	v_pk_mul_f32 v[14:15], v[14:15], v[224:225]
	v_pk_mul_f32 v[24:25], v[12:13], v[230:231]
	v_pk_mul_f32 v[12:13], v[10:11], v[228:229]
	v_pk_mul_f32 v[16:17], v[16:17], v[226:227]
	v_cvt_pk_bf16_f32 v10, v14, v15
	s_nop 0
	v_cvt_pk_bf16_f32 v11, v16, v17
	v_cvt_pk_bf16_f32 v12, v12, v13
	v_cvt_pk_bf16_f32 v13, v24, v25
	flat_store_dwordx4 v[20:21], v[10:13]
.LBB0_936:
	flat_load_dwordx4 v[10:13], v[18:19] offset:512
	s_nop 0
	flat_load_dwordx4 v[28:31], v[18:19] offset:528
	s_and_b64 vcc, exec, s[36:37]
	s_waitcnt vmcnt(0) lgkmcnt(0)
	v_pk_fma_f32 v[8:9], v[8:9], v[218:219], v[12:13]
	v_pk_fma_f32 v[6:7], v[6:7], v[216:217], v[10:11]
	v_pk_fma_f32 v[4:5], v[4:5], v[222:223], v[30:31]
	v_pk_fma_f32 v[2:3], v[2:3], v[220:221], v[28:29]
	flat_store_dwordx4 v[18:19], v[6:9] offset:512
	flat_store_dwordx4 v[18:19], v[2:5] offset:528
	s_cbranch_vccnz .LBB0_938
	v_pk_mul_f32 v[24:25], v[6:7], v[6:7]
	v_pk_mul_f32 v[18:19], v[8:9], v[8:9]
	v_add_f32_e32 v23, v24, v25
	v_add_f32_e32 v18, v18, v23
	v_pk_mul_f32 v[28:29], v[2:3], v[2:3]
	v_add_f32_e32 v18, v19, v18
	v_add_f32_e32 v18, v28, v18
	v_pk_mul_f32 v[26:27], v[4:5], v[4:5]
	v_add_f32_e32 v18, v29, v18
	v_add_f32_e32 v18, v26, v18
	v_add_f32_e32 v18, v27, v18
	v_add_f32_e32 v22, v22, v18
	v_pk_mul_f32 v[6:7], v[6:7], v[232:233]
	v_pk_mul_f32 v[10:11], v[4:5], v[238:239]
	v_pk_mul_f32 v[4:5], v[2:3], v[236:237]
	v_pk_mul_f32 v[8:9], v[8:9], v[234:235]
	v_cvt_pk_bf16_f32 v2, v6, v7
	s_nop 0
	v_cvt_pk_bf16_f32 v3, v8, v9
	v_cvt_pk_bf16_f32 v4, v4, v5
	v_cvt_pk_bf16_f32 v5, v10, v11
	flat_store_dwordx4 v[20:21], v[2:5] offset:256

;     DI void operator()(const pg8::f32x4 (&acc)[2][2][4][2], const pg8::Unit& u, int wr, int wc, int fr, int fq) const {
;         asm volatile("" : "+v"(fr), "+v"(fq));
; #pragma unroll
;         for (int ai = 0; ai < 2; ++ai)
; #pragma unroll
;             for (int m = 0; m < 4; ++m) { const int rit = ai * 128 + wr * 64 + m * 16 + fr;
; #pragma unroll
;                 for (int bj = 0; bj < 2; ++bj) { f(rit, u.pn * 256 + bj * 128 + wc * 32 + 8 * fq, acc[ai][bj][m][0], acc[ai][bj][m][1], u, fq); __builtin_amdgcn_sched_barrier(0); } }
.LBB0_968:
	v_mov_b32_e32 v153, v0
	v_mov_b32_e32 v152, v162
	s_lshl_b32 s4, s64, 8
	s_or_b32 s4, s4, s55
	v_lshl_add_u32 v152, v152, 3, s4
	s_lshl_b32 s4, s20, 8
	s_add_i32 s4, s4, s54
	v_add_u32_e32 v158, s4, v153
	s_mul_hi_i32 s4, s20, 0x38e38e39
	v_ashrrev_i32_e32 v159, 31, v158
	s_lshr_b32 s5, s4, 31
	s_ashr_i32 s4, s4, 1
	v_lshl_add_u64 v[170:171], v[158:159], 2, s[80:81]
	s_add_i32 s4, s4, s5
	flat_load_dword v160, v[170:171]
	s_mul_i32 s5, s4, -9
	s_sub_i32 s14, 0, s20
	s_cmp_lg_u32 s5, s14
	s_cselect_b32 s50, s4, 32
	s_ashr_i32 s51, s50, 31
	s_lshl_b64 s[50:51], s[50:51], 14
	s_add_u32 s50, s44, s50
	s_addc_u32 s51, s45, s51
	v_ashrrev_i32_e32 v153, 31, v152
	v_lshl_add_u64 v[156:157], v[152:153], 2, s[50:51]
	flat_load_dwordx4 v[200:203], v[156:157]
	flat_load_dwordx4 v[204:207], v[156:157] offset:16
	flat_load_dwordx4 v[208:211], v[156:157] offset:512
	flat_load_dwordx4 v[212:215], v[156:157] offset:528
	flat_load_dword v217, v[170:171] offset:64
	flat_load_dword v218, v[170:171] offset:128
	flat_load_dword v219, v[170:171] offset:192
	flat_load_dword v220, v[170:171] offset:512
	flat_load_dword v221, v[170:171] offset:576
	flat_load_dword v222, v[170:171] offset:640
	flat_load_dword v223, v[170:171] offset:704
	v_lshlrev_b64 v[192:193], 13, v[158:159]
	s_waitcnt vmcnt(0) lgkmcnt(0)
	v_mov_b32_e32 v216, v160
	v_fmamk_f32 v159, v160, 0x3a800000, v173
	v_mul_f32_e32 v160, 0x4b800000, v159
	v_cmp_gt_f32_e32 vcc, s3, v159
	s_nop 1
	v_cndmask_b32_e32 v159, v159, v160, vcc
	v_rsq_f32_e32 v159, v159
	v_lshlrev_b64 v[160:161], 1, v[152:153]
	v_lshl_add_u64 v[152:153], s[36:37], 0, v[192:193]
	v_lshl_add_u64 v[152:153], v[152:153], 0, v[160:161]
	v_mul_f32_e32 v165, 0x45800000, v159
	v_cndmask_b32_e32 v192, v159, v165, vcc
	v_pk_fma_f32 v[124:125], v[124:125], v[192:193], v[206:207] op_sel_hi:[1,0,1]
	v_pk_fma_f32 v[128:129], v[128:129], v[192:193], v[202:203] op_sel_hi:[1,0,1]
	v_pk_fma_f32 v[126:127], v[126:127], v[192:193], v[200:201] op_sel_hi:[1,0,1]
	v_pk_fma_f32 v[122:123], v[122:123], v[192:193], v[204:205] op_sel_hi:[1,0,1]
	v_max_f32_e32 v125, 0, v125
	v_max_f32_e32 v126, 0, v126
	v_max_f32_e32 v127, 0, v127
	v_max_f32_e32 v128, 0, v128
	v_max_f32_e32 v129, 0, v129
	v_max_f32_e32 v122, 0, v122
	v_max_f32_e32 v123, 0, v123
	v_max_f32_e32 v124, 0, v124
	v_mul_f32_e32 v125, v125, v125
	v_mul_f32_e32 v126, v126, v126
	v_mul_f32_e32 v127, v127, v127
	v_mul_f32_e32 v128, v128, v128
	v_mul_f32_e32 v129, v129, v129
	v_mul_f32_e32 v159, v122, v122
	v_mul_f32_e32 v165, v123, v123
	v_mul_f32_e32 v166, v124, v124
	v_cvt_pk_bf16_f32 v122, v126, v127
	v_cvt_pk_bf16_f32 v123, v128, v129
	v_cvt_pk_bf16_f32 v124, v159, v165
	v_cvt_pk_bf16_f32 v125, v166, v125
	flat_store_dwordx4 v[152:153], v[122:125]
	v_fmamk_f32 v159, v216, 0x3a800000, v173
	v_mul_f32_e32 v165, 0x4b800000, v159
	v_cmp_gt_f32_e32 vcc, s3, v159
	s_nop 1
	v_cndmask_b32_e32 v159, v159, v165, vcc
	v_rsq_f32_e32 v159, v159
	s_nop 0
	v_mul_f32_e32 v165, 0x45800000, v159
	v_cndmask_b32_e32 v166, v159, v165, vcc
	v_pk_fma_f32 v[116:117], v[116:117], v[166:167], v[214:215] op_sel_hi:[1,0,1]
	v_pk_fma_f32 v[120:121], v[120:121], v[166:167], v[210:211] op_sel_hi:[1,0,1]
	v_pk_fma_f32 v[118:119], v[118:119], v[166:167], v[208:209] op_sel_hi:[1,0,1]
	v_pk_fma_f32 v[114:115], v[114:115], v[166:167], v[212:213] op_sel_hi:[1,0,1]
	v_max_f32_e32 v117, 0, v117
	v_max_f32_e32 v118, 0, v118
	v_max_f32_e32 v119, 0, v119
	v_max_f32_e32 v120, 0, v120
	v_max_f32_e32 v121, 0, v121
	v_max_f32_e32 v114, 0, v114
	v_max_f32_e32 v115, 0, v115
	v_max_f32_e32 v116, 0, v116
	v_mul_f32_e32 v117, v117, v117
	v_mul_f32_e32 v118, v118, v118
	v_mul_f32_e32 v119, v119, v119
	v_mul_f32_e32 v120, v120, v120
	v_mul_f32_e32 v121, v121, v121
	v_mul_f32_e32 v122, v114, v114
	v_mul_f32_e32 v123, v115, v115
	v_mul_f32_e32 v124, v116, v116
	v_cvt_pk_bf16_f32 v114, v118, v119
	v_cvt_pk_bf16_f32 v115, v120, v121
	v_cvt_pk_bf16_f32 v116, v122, v123
	v_cvt_pk_bf16_f32 v117, v124, v117
	flat_store_dwordx4 v[152:153], v[114:117] offset:256
	v_add_u32_e32 v122, 16, v158
	v_ashrrev_i32_e32 v123, 31, v122
	v_lshl_add_u64 v[124:125], v[122:123], 2, s[80:81]
	v_lshlrev_b64 v[122:123], 13, v[122:123]
	v_lshl_add_u64 v[122:123], s[36:37], 0, v[122:123]
	v_lshl_add_u64 v[122:123], v[122:123], 0, v[160:161]
	v_fmamk_f32 v126, v217, 0x3a800000, v173
	v_mul_f32_e32 v127, 0x4b800000, v126
	v_cmp_gt_f32_e32 vcc, s3, v126
	s_nop 1
	v_cndmask_b32_e32 v126, v126, v127, vcc
	v_rsq_f32_e32 v126, v126
	s_nop 0
	v_mul_f32_e32 v127, 0x45800000, v126
	v_cndmask_b32_e32 v126, v126, v127, vcc
	v_pk_fma_f32 v[108:109], v[108:109], v[126:127], v[206:207] op_sel_hi:[1,0,1]
	v_pk_fma_f32 v[112:113], v[112:113], v[126:127], v[202:203] op_sel_hi:[1,0,1]
	v_pk_fma_f32 v[110:111], v[110:111], v[126:127], v[200:201] op_sel_hi:[1,0,1]
	v_pk_fma_f32 v[106:107], v[106:107], v[126:127], v[204:205] op_sel_hi:[1,0,1]
	v_max_f32_e32 v109, 0, v109
	v_max_f32_e32 v110, 0, v110
	v_max_f32_e32 v111, 0, v111
	v_max_f32_e32 v112, 0, v112
	v_max_f32_e32 v113, 0, v113
	v_max_f32_e32 v106, 0, v106
	v_max_f32_e32 v107, 0, v107
	v_max_f32_e32 v108, 0, v108
	v_mul_f32_e32 v109, v109, v109
	v_mul_f32_e32 v110, v110, v110
	v_mul_f32_e32 v111, v111, v111
	v_mul_f32_e32 v112, v112, v112
	v_mul_f32_e32 v113, v113, v113
	v_mul_f32_e32 v114, v106, v106
	v_mul_f32_e32 v115, v107, v107
	v_mul_f32_e32 v116, v108, v108
	v_cvt_pk_bf16_f32 v106, v110, v111
	v_cvt_pk_bf16_f32 v107, v112, v113
	v_cvt_pk_bf16_f32 v108, v114, v115
	v_cvt_pk_bf16_f32 v109, v116, v109
	flat_store_dwordx4 v[122:123], v[106:109]
	v_fmamk_f32 v114, v217, 0x3a800000, v173
	v_mul_f32_e32 v115, 0x4b800000, v114
	v_cmp_gt_f32_e32 vcc, s3, v114
	s_nop 1
	v_cndmask_b32_e32 v114, v114, v115, vcc
	v_rsq_f32_e32 v114, v114
	s_nop 0
	v_mul_f32_e32 v115, 0x45800000, v114
	v_cndmask_b32_e32 v114, v114, v115, vcc
	v_pk_fma_f32 v[100:101], v[100:101], v[114:115], v[214:215] op_sel_hi:[1,0,1]
	v_pk_fma_f32 v[104:105], v[104:105], v[114:115], v[210:211] op_sel_hi:[1,0,1]
	v_pk_fma_f32 v[102:103], v[102:103], v[114:115], v[208:209] op_sel_hi:[1,0,1]
	v_pk_fma_f32 v[98:99], v[98:99], v[114:115], v[212:213] op_sel_hi:[1,0,1]
	v_max_f32_e32 v101, 0, v101
	v_max_f32_e32 v102, 0, v102
	v_max_f32_e32 v103, 0, v103
	v_max_f32_e32 v104, 0, v104
	v_max_f32_e32 v105, 0, v105
	v_max_f32_e32 v98, 0, v98
	v_max_f32_e32 v99, 0, v99
	v_max_f32_e32 v100, 0, v100
	v_mul_f32_e32 v101, v101, v101
	v_mul_f32_e32 v102, v102, v102
	v_mul_f32_e32 v103, v103, v103
	v_mul_f32_e32 v104, v104, v104
	v_mul_f32_e32 v105, v105, v105
	v_mul_f32_e32 v106, v98, v98
	v_mul_f32_e32 v107, v99, v99
	v_mul_f32_e32 v108, v100, v100
	v_cvt_pk_bf16_f32 v98, v102, v103
	v_cvt_pk_bf16_f32 v99, v104, v105
	v_cvt_pk_bf16_f32 v100, v106, v107
	v_cvt_pk_bf16_f32 v101, v108, v101
	flat_store_dwordx4 v[122:123], v[98:101] offset:256
	v_add_u32_e32 v106, 32, v158
	v_ashrrev_i32_e32 v107, 31, v106
	v_lshl_add_u64 v[108:109], v[106:107], 2, s[80:81]
	v_lshlrev_b64 v[106:107], 13, v[106:107]
	v_lshl_add_u64 v[106:107], s[36:37], 0, v[106:107]
	v_lshl_add_u64 v[106:107], v[106:107], 0, v[160:161]
	v_fmamk_f32 v110, v218, 0x3a800000, v173
	v_mul_f32_e32 v111, 0x4b800000, v110
	v_cmp_gt_f32_e32 vcc, s3, v110
	s_nop 1
	v_cndmask_b32_e32 v110, v110, v111, vcc
	v_rsq_f32_e32 v110, v110
	s_nop 0
	v_mul_f32_e32 v111, 0x45800000, v110
	v_cndmask_b32_e32 v110, v110, v111, vcc
	v_pk_fma_f32 v[92:93], v[92:93], v[110:111], v[206:207] op_sel_hi:[1,0,1]
	v_pk_fma_f32 v[96:97], v[96:97], v[110:111], v[202:203] op_sel_hi:[1,0,1]
	v_pk_fma_f32 v[94:95], v[94:95], v[110:111], v[200:201] op_sel_hi:[1,0,1]
	v_pk_fma_f32 v[90:91], v[90:91], v[110:111], v[204:205] op_sel_hi:[1,0,1]
	v_max_f32_e32 v93, 0, v93
	v_max_f32_e32 v94, 0, v94
	v_max_f32_e32 v95, 0, v95
	v_max_f32_e32 v96, 0, v96
	v_max_f32_e32 v97, 0, v97
	v_max_f32_e32 v90, 0, v90
	v_max_f32_e32 v91, 0, v91
	v_max_f32_e32 v92, 0, v92
	v_mul_f32_e32 v93, v93, v93
	v_mul_f32_e32 v94, v94, v94
	v_mul_f32_e32 v95, v95, v95
	v_mul_f32_e32 v96, v96, v96
	v_mul_f32_e32 v97, v97, v97
	v_mul_f32_e32 v98, v90, v90
	v_mul_f32_e32 v99, v91, v91
	v_mul_f32_e32 v100, v92, v92
	v_cvt_pk_bf16_f32 v90, v94, v95
	v_cvt_pk_bf16_f32 v91, v96, v97
	v_cvt_pk_bf16_f32 v92, v98, v99
	v_cvt_pk_bf16_f32 v93, v100, v93
	flat_store_dwordx4 v[106:107], v[90:93]
	v_fmamk_f32 v98, v218, 0x3a800000, v173
	v_mul_f32_e32 v99, 0x4b800000, v98
	v_cmp_gt_f32_e32 vcc, s3, v98
	s_nop 1
	v_cndmask_b32_e32 v98, v98, v99, vcc
	v_rsq_f32_e32 v98, v98
	s_nop 0
	v_mul_f32_e32 v99, 0x45800000, v98
	v_cndmask_b32_e32 v98, v98, v99, vcc
	v_pk_fma_f32 v[84:85], v[84:85], v[98:99], v[214:215] op_sel_hi:[1,0,1]
	v_pk_fma_f32 v[88:89], v[88:89], v[98:99], v[210:211] op_sel_hi:[1,0,1]
	v_pk_fma_f32 v[86:87], v[86:87], v[98:99], v[208:209] op_sel_hi:[1,0,1]
	v_pk_fma_f32 v[82:83], v[82:83], v[98:99], v[212:213] op_sel_hi:[1,0,1]
	v_max_f32_e32 v85, 0, v85
	v_max_f32_e32 v86, 0, v86
	v_max_f32_e32 v87, 0, v87
	v_max_f32_e32 v88, 0, v88
	v_max_f32_e32 v89, 0, v89
	v_max_f32_e32 v82, 0, v82
	v_max_f32_e32 v83, 0, v83
	v_max_f32_e32 v84, 0, v84
	v_mul_f32_e32 v85, v85, v85
	v_mul_f32_e32 v86, v86, v86
	v_mul_f32_e32 v87, v87, v87
	v_mul_f32_e32 v88, v88, v88
	v_mul_f32_e32 v89, v89, v89
	v_mul_f32_e32 v90, v82, v82
	v_mul_f32_e32 v91, v83, v83
	v_mul_f32_e32 v92, v84, v84
	v_cvt_pk_bf16_f32 v82, v86, v87
	v_cvt_pk_bf16_f32 v83, v88, v89
	v_cvt_pk_bf16_f32 v84, v90, v91
	v_cvt_pk_bf16_f32 v85, v92, v85
	flat_store_dwordx4 v[106:107], v[82:85] offset:256
	v_add_u32_e32 v90, 48, v158
	v_ashrrev_i32_e32 v91, 31, v90
	v_lshl_add_u64 v[92:93], v[90:91], 2, s[80:81]
	v_lshlrev_b64 v[90:91], 13, v[90:91]
	v_lshl_add_u64 v[90:91], s[36:37], 0, v[90:91]
	v_lshl_add_u64 v[90:91], v[90:91], 0, v[160:161]
	v_fmamk_f32 v94, v219, 0x3a800000, v173
	v_mul_f32_e32 v95, 0x4b800000, v94
	v_cmp_gt_f32_e32 vcc, s3, v94
	s_nop 1
	v_cndmask_b32_e32 v94, v94, v95, vcc
	v_rsq_f32_e32 v94, v94
	s_nop 0
	v_mul_f32_e32 v95, 0x45800000, v94
	v_cndmask_b32_e32 v94, v94, v95, vcc
	v_pk_fma_f32 v[76:77], v[76:77], v[94:95], v[206:207] op_sel_hi:[1,0,1]
	v_pk_fma_f32 v[80:81], v[80:81], v[94:95], v[202:203] op_sel_hi:[1,0,1]
	v_pk_fma_f32 v[78:79], v[78:79], v[94:95], v[200:201] op_sel_hi:[1,0,1]
	v_pk_fma_f32 v[74:75], v[74:75], v[94:95], v[204:205] op_sel_hi:[1,0,1]
	v_max_f32_e32 v77, 0, v77
	v_max_f32_e32 v78, 0, v78
	v_max_f32_e32 v79, 0, v79
	v_max_f32_e32 v80, 0, v80
	v_max_f32_e32 v81, 0, v81
	v_max_f32_e32 v74, 0, v74
	v_max_f32_e32 v75, 0, v75
	v_max_f32_e32 v76, 0, v76
	v_mul_f32_e32 v77, v77, v77
	v_mul_f32_e32 v78, v78, v78
	v_mul_f32_e32 v79, v79, v79
	v_mul_f32_e32 v80, v80, v80
	v_mul_f32_e32 v81, v81, v81
	v_mul_f32_e32 v82, v74, v74
	v_mul_f32_e32 v83, v75, v75
	v_mul_f32_e32 v84, v76, v76
	v_cvt_pk_bf16_f32 v74, v78, v79
	v_cvt_pk_bf16_f32 v75, v80, v81
	v_cvt_pk_bf16_f32 v76, v82, v83
	v_cvt_pk_bf16_f32 v77, v84, v77
	flat_store_dwordx4 v[90:91], v[74:77]
	v_fmamk_f32 v82, v219, 0x3a800000, v173
	v_mul_f32_e32 v83, 0x4b800000, v82
	v_cmp_gt_f32_e32 vcc, s3, v82
	s_nop 1
	v_cndmask_b32_e32 v82, v82, v83, vcc
	v_rsq_f32_e32 v82, v82
	s_nop 0
	v_mul_f32_e32 v83, 0x45800000, v82
	v_cndmask_b32_e32 v82, v82, v83, vcc
	v_pk_fma_f32 v[68:69], v[68:69], v[82:83], v[214:215] op_sel_hi:[1,0,1]
	v_pk_fma_f32 v[72:73], v[72:73], v[82:83], v[210:211] op_sel_hi:[1,0,1]
	v_pk_fma_f32 v[70:71], v[70:71], v[82:83], v[208:209] op_sel_hi:[1,0,1]
	v_pk_fma_f32 v[66:67], v[66:67], v[82:83], v[212:213] op_sel_hi:[1,0,1]
	v_max_f32_e32 v69, 0, v69
	v_max_f32_e32 v70, 0, v70
	v_max_f32_e32 v71, 0, v71
	v_max_f32_e32 v72, 0, v72
	v_max_f32_e32 v73, 0, v73
	v_max_f32_e32 v66, 0, v66
	v_max_f32_e32 v67, 0, v67
	v_max_f32_e32 v68, 0, v68
	v_mul_f32_e32 v69, v69, v69
	v_mul_f32_e32 v70, v70, v70
	v_mul_f32_e32 v71, v71, v71
	v_mul_f32_e32 v72, v72, v72
	v_mul_f32_e32 v73, v73, v73
	v_mul_f32_e32 v74, v66, v66
	v_mul_f32_e32 v75, v67, v67
	v_mul_f32_e32 v76, v68, v68
	v_cvt_pk_bf16_f32 v66, v70, v71
	v_cvt_pk_bf16_f32 v67, v72, v73
	v_cvt_pk_bf16_f32 v68, v74, v75
	v_cvt_pk_bf16_f32 v69, v76, v69
	flat_store_dwordx4 v[90:91], v[66:69] offset:256
	v_add_u32_e32 v74, 0x80, v158
	v_ashrrev_i32_e32 v75, 31, v74
	v_lshl_add_u64 v[76:77], v[74:75], 2, s[80:81]
	v_lshlrev_b64 v[74:75], 13, v[74:75]
	v_lshl_add_u64 v[74:75], s[36:37], 0, v[74:75]
	v_lshl_add_u64 v[74:75], v[74:75], 0, v[160:161]
	v_fmamk_f32 v78, v220, 0x3a800000, v173
	v_mul_f32_e32 v79, 0x4b800000, v78
	v_cmp_gt_f32_e32 vcc, s3, v78
	s_nop 1
	v_cndmask_b32_e32 v78, v78, v79, vcc
	v_rsq_f32_e32 v78, v78
	s_nop 0
	v_mul_f32_e32 v79, 0x45800000, v78
	v_cndmask_b32_e32 v78, v78, v79, vcc
	v_pk_fma_f32 v[60:61], v[60:61], v[78:79], v[206:207] op_sel_hi:[1,0,1]
	v_pk_fma_f32 v[64:65], v[64:65], v[78:79], v[202:203] op_sel_hi:[1,0,1]
	v_pk_fma_f32 v[62:63], v[62:63], v[78:79], v[200:201] op_sel_hi:[1,0,1]
	v_pk_fma_f32 v[58:59], v[58:59], v[78:79], v[204:205] op_sel_hi:[1,0,1]
	v_max_f32_e32 v61, 0, v61
	v_max_f32_e32 v62, 0, v62
	v_max_f32_e32 v63, 0, v63
	v_max_f32_e32 v64, 0, v64
	v_max_f32_e32 v65, 0, v65
	v_max_f32_e32 v58, 0, v58
	v_max_f32_e32 v59, 0, v59
	v_max_f32_e32 v60, 0, v60
	v_mul_f32_e32 v61, v61, v61
	v_mul_f32_e32 v62, v62, v62
	v_mul_f32_e32 v63, v63, v63
	v_mul_f32_e32 v64, v64, v64
	v_mul_f32_e32 v65, v65, v65
	v_mul_f32_e32 v66, v58, v58
	v_mul_f32_e32 v67, v59, v59
	v_mul_f32_e32 v68, v60, v60
	v_cvt_pk_bf16_f32 v58, v62, v63
	v_cvt_pk_bf16_f32 v59, v64, v65
	v_cvt_pk_bf16_f32 v60, v66, v67
	v_cvt_pk_bf16_f32 v61, v68, v61
	flat_store_dwordx4 v[74:75], v[58:61]
	v_fmamk_f32 v66, v220, 0x3a800000, v173
	v_mul_f32_e32 v67, 0x4b800000, v66
	v_cmp_gt_f32_e32 vcc, s3, v66
	s_nop 1
	v_cndmask_b32_e32 v66, v66, v67, vcc
	v_rsq_f32_e32 v66, v66
	s_nop 0
	v_mul_f32_e32 v67, 0x45800000, v66
	v_cndmask_b32_e32 v66, v66, v67, vcc
	v_pk_fma_f32 v[52:53], v[52:53], v[66:67], v[214:215] op_sel_hi:[1,0,1]
	v_pk_fma_f32 v[56:57], v[56:57], v[66:67], v[210:211] op_sel_hi:[1,0,1]
	v_pk_fma_f32 v[54:55], v[54:55], v[66:67], v[208:209] op_sel_hi:[1,0,1]
	v_pk_fma_f32 v[50:51], v[50:51], v[66:67], v[212:213] op_sel_hi:[1,0,1]
	v_max_f32_e32 v53, 0, v53
	v_max_f32_e32 v54, 0, v54
	v_max_f32_e32 v55, 0, v55
	v_max_f32_e32 v56, 0, v56
	v_max_f32_e32 v57, 0, v57
	v_max_f32_e32 v50, 0, v50
	v_max_f32_e32 v51, 0, v51
	v_max_f32_e32 v52, 0, v52
	v_mul_f32_e32 v53, v53, v53
	v_mul_f32_e32 v54, v54, v54
	v_mul_f32_e32 v55, v55, v55
	v_mul_f32_e32 v56, v56, v56
	v_mul_f32_e32 v57, v57, v57
	v_mul_f32_e32 v58, v50, v50
	v_mul_f32_e32 v59, v51, v51
	v_mul_f32_e32 v60, v52, v52
	v_cvt_pk_bf16_f32 v50, v54, v55
	v_cvt_pk_bf16_f32 v51, v56, v57
	v_cvt_pk_bf16_f32 v52, v58, v59
	v_cvt_pk_bf16_f32 v53, v60, v53
	flat_store_dwordx4 v[74:75], v[50:53] offset:256
	v_add_u32_e32 v58, 0x90, v158
	v_ashrrev_i32_e32 v59, 31, v58
	v_lshl_add_u64 v[60:61], v[58:59], 2, s[80:81]
	v_lshlrev_b64 v[58:59], 13, v[58:59]
	v_lshl_add_u64 v[58:59], s[36:37], 0, v[58:59]
	v_lshl_add_u64 v[58:59], v[58:59], 0, v[160:161]
	v_fmamk_f32 v62, v221, 0x3a800000, v173
	v_mul_f32_e32 v63, 0x4b800000, v62
	v_cmp_gt_f32_e32 vcc, s3, v62
	s_nop 1
	v_cndmask_b32_e32 v62, v62, v63, vcc
	v_rsq_f32_e32 v62, v62
	s_nop 0
	v_mul_f32_e32 v63, 0x45800000, v62
	v_cndmask_b32_e32 v62, v62, v63, vcc
	v_pk_fma_f32 v[44:45], v[44:45], v[62:63], v[206:207] op_sel_hi:[1,0,1]
	v_pk_fma_f32 v[48:49], v[48:49], v[62:63], v[202:203] op_sel_hi:[1,0,1]
	v_pk_fma_f32 v[46:47], v[46:47], v[62:63], v[200:201] op_sel_hi:[1,0,1]
	v_pk_fma_f32 v[42:43], v[42:43], v[62:63], v[204:205] op_sel_hi:[1,0,1]
	v_max_f32_e32 v45, 0, v45
	v_max_f32_e32 v46, 0, v46
	v_max_f32_e32 v47, 0, v47
	v_max_f32_e32 v48, 0, v48
	v_max_f32_e32 v49, 0, v49
	v_max_f32_e32 v42, 0, v42
	v_max_f32_e32 v43, 0, v43
	v_max_f32_e32 v44, 0, v44
	v_mul_f32_e32 v45, v45, v45
	v_mul_f32_e32 v46, v46, v46
	v_mul_f32_e32 v47, v47, v47
	v_mul_f32_e32 v48, v48, v48
	v_mul_f32_e32 v49, v49, v49
	v_mul_f32_e32 v50, v42, v42
	v_mul_f32_e32 v51, v43, v43
	v_mul_f32_e32 v52, v44, v44
	v_cvt_pk_bf16_f32 v42, v46, v47
	v_cvt_pk_bf16_f32 v43, v48, v49
	v_cvt_pk_bf16_f32 v44, v50, v51
	v_cvt_pk_bf16_f32 v45, v52, v45
	flat_store_dwordx4 v[58:59], v[42:45]
	v_fmamk_f32 v50, v221, 0x3a800000, v173
	v_mul_f32_e32 v51, 0x4b800000, v50
	v_cmp_gt_f32_e32 vcc, s3, v50
	s_nop 1
	v_cndmask_b32_e32 v50, v50, v51, vcc
	v_rsq_f32_e32 v50, v50
	s_nop 0
	v_mul_f32_e32 v51, 0x45800000, v50
	v_cndmask_b32_e32 v50, v50, v51, vcc
	v_pk_fma_f32 v[36:37], v[36:37], v[50:51], v[214:215] op_sel_hi:[1,0,1]
	v_pk_fma_f32 v[40:41], v[40:41], v[50:51], v[210:211] op_sel_hi:[1,0,1]
	v_pk_fma_f32 v[38:39], v[38:39], v[50:51], v[208:209] op_sel_hi:[1,0,1]
	v_pk_fma_f32 v[34:35], v[34:35], v[50:51], v[212:213] op_sel_hi:[1,0,1]
	v_max_f32_e32 v37, 0, v37
	v_max_f32_e32 v38, 0, v38
	v_max_f32_e32 v39, 0, v39
	v_max_f32_e32 v40, 0, v40
	v_max_f32_e32 v41, 0, v41
	v_max_f32_e32 v34, 0, v34
	v_max_f32_e32 v35, 0, v35
	v_max_f32_e32 v36, 0, v36
	v_mul_f32_e32 v37, v37, v37
	v_mul_f32_e32 v38, v38, v38
; #define PG8_BAR __builtin_amdgcn_s_barrier()
; template <class Epi, class Sched, bool ALIGN_EPI = false, bool SP2 = false>
; __device__ __forceinline__ void gemm_phase(PG8_LAS unsigned char* lds, const Gemm g, const Sched& S, const Epi& E) {
;     ...
;         if constexpr (ALIGN_EPI) { if (wr == 0) PG8_BAR; }
;         if constexpr (!Epi::AFTER_DRAIN) { E(acc, cur, wr, wc, fr, fq); S.done(cur); }
;         if (!has_next) break;
; #pragma unroll
;         for (int a = 0; a < 2; ++a)
; #pragma unroll
;             for (int b = 0; b < 2; ++b)
; #pragma unroll
;                 for (int m = 0; m < 4; ++m)
; #pragma unroll
;                     for (int n = 0; n < 2; ++n) acc[a][b][m][n] = (f32x4){0.f, 0.f, 0.f, 0.f};
;         cur = nxt; cA = nA; cB = nB; ++ui;
;         if constexpr (ALIGN_EPI) { if (wr == 1) PG8_BAR; }
	v_mul_f32_e32 v39, v39, v39
	v_mul_f32_e32 v40, v40, v40
	v_mul_f32_e32 v41, v41, v41
	v_mul_f32_e32 v42, v34, v34
	v_mul_f32_e32 v43, v35, v35
	v_mul_f32_e32 v44, v36, v36
	v_cvt_pk_bf16_f32 v34, v38, v39
	v_cvt_pk_bf16_f32 v35, v40, v41
	v_cvt_pk_bf16_f32 v36, v42, v43
	v_cvt_pk_bf16_f32 v37, v44, v37
	flat_store_dwordx4 v[58:59], v[34:37] offset:256
	v_add_u32_e32 v42, 0xa0, v158
	v_ashrrev_i32_e32 v43, 31, v42
	v_lshl_add_u64 v[44:45], v[42:43], 2, s[80:81]
	v_lshlrev_b64 v[42:43], 13, v[42:43]
	v_lshl_add_u64 v[42:43], s[36:37], 0, v[42:43]
	v_lshl_add_u64 v[42:43], v[42:43], 0, v[160:161]
	v_fmamk_f32 v46, v222, 0x3a800000, v173
	v_mul_f32_e32 v47, 0x4b800000, v46
	v_cmp_gt_f32_e32 vcc, s3, v46
	s_nop 1
	v_cndmask_b32_e32 v46, v46, v47, vcc
	v_rsq_f32_e32 v46, v46
	s_nop 0
	v_mul_f32_e32 v47, 0x45800000, v46
	v_cndmask_b32_e32 v46, v46, v47, vcc
	v_pk_fma_f32 v[28:29], v[28:29], v[46:47], v[206:207] op_sel_hi:[1,0,1]
	v_pk_fma_f32 v[32:33], v[32:33], v[46:47], v[202:203] op_sel_hi:[1,0,1]
	v_pk_fma_f32 v[30:31], v[30:31], v[46:47], v[200:201] op_sel_hi:[1,0,1]
	v_pk_fma_f32 v[26:27], v[26:27], v[46:47], v[204:205] op_sel_hi:[1,0,1]
	v_max_f32_e32 v29, 0, v29
	v_max_f32_e32 v30, 0, v30
	v_max_f32_e32 v31, 0, v31
	v_max_f32_e32 v32, 0, v32
	v_max_f32_e32 v33, 0, v33
	v_max_f32_e32 v26, 0, v26
	v_max_f32_e32 v27, 0, v27
	v_max_f32_e32 v28, 0, v28
	v_mul_f32_e32 v29, v29, v29
	v_mul_f32_e32 v30, v30, v30
	v_mul_f32_e32 v31, v31, v31
	v_mul_f32_e32 v32, v32, v32
	v_mul_f32_e32 v33, v33, v33
	v_mul_f32_e32 v34, v26, v26
	v_mul_f32_e32 v35, v27, v27
	v_mul_f32_e32 v36, v28, v28
	v_cvt_pk_bf16_f32 v26, v30, v31
	v_cvt_pk_bf16_f32 v27, v32, v33
	v_cvt_pk_bf16_f32 v28, v34, v35
	v_cvt_pk_bf16_f32 v29, v36, v29
	flat_store_dwordx4 v[42:43], v[26:29]
	v_fmamk_f32 v34, v222, 0x3a800000, v173
	v_mul_f32_e32 v35, 0x4b800000, v34
	v_cmp_gt_f32_e32 vcc, s3, v34
	s_nop 1
	v_cndmask_b32_e32 v34, v34, v35, vcc
	v_rsq_f32_e32 v34, v34
	s_nop 0
	v_mul_f32_e32 v35, 0x45800000, v34
	v_cndmask_b32_e32 v34, v34, v35, vcc
	v_pk_fma_f32 v[20:21], v[20:21], v[34:35], v[214:215] op_sel_hi:[1,0,1]
	v_pk_fma_f32 v[24:25], v[24:25], v[34:35], v[210:211] op_sel_hi:[1,0,1]
	v_pk_fma_f32 v[22:23], v[22:23], v[34:35], v[208:209] op_sel_hi:[1,0,1]
	v_pk_fma_f32 v[18:19], v[18:19], v[34:35], v[212:213] op_sel_hi:[1,0,1]
	v_max_f32_e32 v21, 0, v21
	v_max_f32_e32 v22, 0, v22
	v_max_f32_e32 v23, 0, v23
	v_max_f32_e32 v24, 0, v24
	v_max_f32_e32 v25, 0, v25
	v_max_f32_e32 v18, 0, v18
	v_max_f32_e32 v19, 0, v19
	v_max_f32_e32 v20, 0, v20
	v_mul_f32_e32 v21, v21, v21
	v_mul_f32_e32 v22, v22, v22
	v_mul_f32_e32 v23, v23, v23
	v_mul_f32_e32 v24, v24, v24
	v_mul_f32_e32 v25, v25, v25
	v_mul_f32_e32 v26, v18, v18
	v_mul_f32_e32 v27, v19, v19
	v_mul_f32_e32 v28, v20, v20
	v_cvt_pk_bf16_f32 v18, v22, v23
	v_cvt_pk_bf16_f32 v19, v24, v25
	v_cvt_pk_bf16_f32 v20, v26, v27
	v_cvt_pk_bf16_f32 v21, v28, v21
	flat_store_dwordx4 v[42:43], v[18:21] offset:256
	v_add_u32_e32 v26, 0xb0, v158
	v_ashrrev_i32_e32 v27, 31, v26
	v_lshl_add_u64 v[28:29], v[26:27], 2, s[80:81]
	v_lshlrev_b64 v[26:27], 13, v[26:27]
	v_lshl_add_u64 v[26:27], s[36:37], 0, v[26:27]
	v_lshl_add_u64 v[26:27], v[26:27], 0, v[160:161]
	v_fmamk_f32 v30, v223, 0x3a800000, v173
	v_mul_f32_e32 v31, 0x4b800000, v30
	v_cmp_gt_f32_e32 vcc, s3, v30
	s_nop 1
	v_cndmask_b32_e32 v30, v30, v31, vcc
	v_rsq_f32_e32 v30, v30
	s_nop 0
	v_mul_f32_e32 v31, 0x45800000, v30
	v_cndmask_b32_e32 v30, v30, v31, vcc
	v_pk_fma_f32 v[12:13], v[12:13], v[30:31], v[206:207] op_sel_hi:[1,0,1]
	v_pk_fma_f32 v[16:17], v[16:17], v[30:31], v[202:203] op_sel_hi:[1,0,1]
	v_pk_fma_f32 v[14:15], v[14:15], v[30:31], v[200:201] op_sel_hi:[1,0,1]
	v_pk_fma_f32 v[10:11], v[10:11], v[30:31], v[204:205] op_sel_hi:[1,0,1]
	v_max_f32_e32 v13, 0, v13
	v_max_f32_e32 v14, 0, v14
	v_max_f32_e32 v15, 0, v15
	v_max_f32_e32 v16, 0, v16
	v_max_f32_e32 v17, 0, v17
	v_max_f32_e32 v10, 0, v10
	v_max_f32_e32 v11, 0, v11
	v_max_f32_e32 v12, 0, v12
	v_mul_f32_e32 v13, v13, v13
	v_mul_f32_e32 v14, v14, v14
	v_mul_f32_e32 v15, v15, v15
	v_mul_f32_e32 v16, v16, v16
	v_mul_f32_e32 v17, v17, v17
	v_mul_f32_e32 v18, v10, v10
	v_mul_f32_e32 v19, v11, v11
	v_mul_f32_e32 v20, v12, v12
	v_cvt_pk_bf16_f32 v10, v14, v15
	v_cvt_pk_bf16_f32 v11, v16, v17
	v_cvt_pk_bf16_f32 v12, v18, v19
	v_cvt_pk_bf16_f32 v13, v20, v13
	flat_store_dwordx4 v[26:27], v[10:13]
	v_fmamk_f32 v18, v223, 0x3a800000, v173
	v_mul_f32_e32 v19, 0x4b800000, v18
	v_cmp_gt_f32_e32 vcc, s3, v18
	s_nop 1
	v_cndmask_b32_e32 v18, v18, v19, vcc
	v_rsq_f32_e32 v18, v18
	s_nop 0
	v_mul_f32_e32 v19, 0x45800000, v18
	v_cndmask_b32_e32 v18, v18, v19, vcc
	v_pk_fma_f32 v[4:5], v[4:5], v[18:19], v[214:215] op_sel_hi:[1,0,1]
	v_pk_fma_f32 v[8:9], v[8:9], v[18:19], v[210:211] op_sel_hi:[1,0,1]
	v_pk_fma_f32 v[6:7], v[6:7], v[18:19], v[208:209] op_sel_hi:[1,0,1]
	v_pk_fma_f32 v[2:3], v[2:3], v[18:19], v[212:213] op_sel_hi:[1,0,1]
	v_max_f32_e32 v5, 0, v5
	v_max_f32_e32 v6, 0, v6
	v_max_f32_e32 v7, 0, v7
	v_max_f32_e32 v8, 0, v8
	v_max_f32_e32 v9, 0, v9
	v_max_f32_e32 v2, 0, v2
	v_max_f32_e32 v3, 0, v3
	v_max_f32_e32 v4, 0, v4
	v_mul_f32_e32 v5, v5, v5
	v_mul_f32_e32 v6, v6, v6
	v_mul_f32_e32 v7, v7, v7
	v_mul_f32_e32 v8, v8, v8
	v_mul_f32_e32 v9, v9, v9
	v_mul_f32_e32 v10, v2, v2
	v_mul_f32_e32 v11, v3, v3
	v_mul_f32_e32 v12, v4, v4
	v_cvt_pk_bf16_f32 v2, v6, v7
	v_cvt_pk_bf16_f32 v3, v8, v9
	v_cvt_pk_bf16_f32 v4, v10, v11
	v_cvt_pk_bf16_f32 v5, v12, v5
	flat_store_dwordx4 v[26:27], v[2:5] offset:256
	s_andn2_b64 vcc, exec, s[0:1]
	s_mov_b64 s[0:1], -1
	s_cbranch_vccnz .LBB0_959
	s_andn2_b64 vcc, exec, s[6:7]
	s_cbranch_vccnz .LBB0_958
	s_barrier
	s_branch .LBB0_958

; DI void st8(bf16_t* p, const pg8::f32x4& v0, const pg8::f32x4& v1) { u32x4 w; w.x = cvtpk(v0[0], v0[1]); w.y = cvtpk(v0[2], v0[3]); w.z = cvtpk(v1[0], v1[1]); w.w = cvtpk(v1[2], v1[3]); *(u32x4*)p = w; }
;     DI void operator()(const pg8::f32x4 (&acc)[2][2][4][2], const pg8::Unit& u, int wr, int wc, int fr, int fq) const {
;     ...
;         const int b = u.pm / 9, seg = u.pm - b * 9, mrow = seg == 0 ? 32 : b;
;         const float* gbase = mods + (size_t)mrow * 6144 + gidx * 1024; const float* gpb = gp + (size_t)mrow * 1024;
; #pragma unroll
;         for (int ai = 0; ai < 2; ++ai)
; #pragma unroll
;             for (int m = 0; m < 4; ++m) { const int rit = ai * 128 + wr * 64 + m * 16 + fr; float ss = 0.f;
;                 const size_t roff = (seg == 0 ? (size_t)(b * TC + rit) * DM : (size_t)(b * SEQ + (seg - 1) * 256 + rit) * DM);
; #pragma unroll
;                 for (int bj = 0; bj < 2; ++bj) { const int col0 = u.pn * 256 + bj * 128 + wc * 32 + 8 * fq;
;                     float* p = (seg == 0 ? xc : out) + roff + col0; const float* q = (seg == 0 ? sc : sx) + roff + col0;
;                     const pg8::f32x4 g0 = *(const pg8::f32x4*)(gbase + col0), g1 = *(const pg8::f32x4*)(gbase + col0 + 4); pg8::f32x4 x0 = *(const pg8::f32x4*)q, x1 = *(const pg8::f32x4*)(q + 4);
;                     x0 += g0 * acc[ai][bj][m][0]; x1 += g1 * acc[ai][bj][m][1]; *(pg8::f32x4*)p = x0; *(pg8::f32x4*)(p + 4) = x1;
;                     if (emit) { const pg8::f32x4 p0 = *(const pg8::f32x4*)(gpb + col0), p1 = *(const pg8::f32x4*)(gpb + col0 + 4);
;                         ss += x0[0] * x0[0] + x0[1] * x0[1] + x0[2] * x0[2] + x0[3] * x0[3] + x1[0] * x1[0] + x1[1] * x1[1] + x1[2] * x1[2] + x1[3] * x1[3];
;                         st8(H + (size_t)(u.pm * 256 + rit) * 1024 + col0, x0 * p0, x1 * p1); }
;                     __builtin_amdgcn_sched_barrier(0); }
;                 if (emit) { ss += __shfl_xor(ss, 16, 64); ss += __shfl_xor(ss, 32, 64); if (fq == 0) atomicAdd(rs + u.pm * 256 + rit, ss); }
.LBB0_992:
	s_mul_hi_i32 s4, s36, 0x38e38e39
	s_lshr_b32 s5, s4, 31
	s_ashr_i32 s4, s4, 1
	s_add_i32 s4, s4, s5
	s_mul_i32 s5, s4, -9
	s_add_i32 s5, s5, s36
	s_cmp_eq_u32 s5, 0
	s_cselect_b64 s[50:51], -1, 0
	s_and_b64 s[58:59], s[50:51], exec
	s_cselect_b32 s58, 32, s4
	s_ashr_i32 s59, s58, 31
	s_mul_i32 s21, s58, 0x6000
	s_mul_hi_i32 s14, s58, 0x6000
	s_add_u32 s21, s79, s21
	s_addc_u32 s14, s82, s14
	s_add_u32 s70, s21, 0x2000
	s_addc_u32 s71, s14, 0
	s_lshl_b64 s[58:59], s[58:59], 12
	s_add_u32 vcc_lo, s55, s58
	s_addc_u32 vcc_hi, s96, s59
	s_lshl_b32 s14, s20, 8
	v_mov_b32_e32 v157, v0
	v_mov_b32_e32 v152, v166
	s_or_b32 s14, s14, s33
	s_lshl_b32 s5, s5, 8
	v_lshl_add_u32 v158, v157, 3, s14
	s_lshl_b32 s14, s4, 11
	s_lshl_b32 s20, s36, 8
	s_add_i32 s5, s14, s5
	s_addk_i32 s5, 0xff00
	s_lshl_b32 s4, s4, 8
	s_ashr_i32 s21, s20, 31
	s_and_b64 s[36:37], s[50:51], exec
	v_add_u32_e32 v156, s97, v152
	s_cselect_b32 s57, s4, s5
	v_add_u32_e32 v152, s57, v156
	v_ashrrev_i32_e32 v153, 31, v152
	v_lshlrev_b64 v[152:153], 12, v[152:153]
	v_ashrrev_i32_e32 v159, 31, v158
	s_cselect_b32 s59, s91, s89
	s_cselect_b32 s58, s54, s90
	v_lshlrev_b64 v[162:163], 2, v[158:159]
	v_lshl_add_u64 v[160:161], s[58:59], 0, v[152:153]
	v_lshl_add_u64 v[170:171], v[160:161], 0, v[162:163]
	v_lshl_add_u64 v[164:165], s[70:71], 0, v[162:163]
	flat_load_dwordx4 v[188:191], v[170:171]
	flat_load_dwordx4 v[208:211], v[164:165]
	flat_load_dwordx4 v[212:215], v[164:165] offset:16
	flat_load_dwordx4 v[200:203], v[170:171] offset:16
	s_cselect_b32 s61, s88, s63
	s_cselect_b32 s60, s83, s62
	v_lshl_add_u64 v[152:153], s[60:61], 0, v[152:153]
	v_lshl_add_u64 v[152:153], v[152:153], 0, v[162:163]
	v_lshl_add_u64 v[160:161], vcc, 0, v[162:163]
	v_cmp_eq_u32_e32 vcc, 0, v157
	flat_load_dwordx4 v[216:219], v[164:165] offset:512
	flat_load_dwordx4 v[220:223], v[164:165] offset:528
	flat_load_dwordx4 v[224:227], v[160:161]
	flat_load_dwordx4 v[228:231], v[160:161] offset:16
	flat_load_dwordx4 v[232:235], v[160:161] offset:512
	flat_load_dwordx4 v[236:239], v[160:161] offset:528
	s_waitcnt vmcnt(0) lgkmcnt(0)
	v_pk_fma_f32 v[128:129], v[128:129], v[210:211], v[190:191]
	v_pk_fma_f32 v[126:127], v[126:127], v[208:209], v[188:189]
	v_pk_fma_f32 v[124:125], v[124:125], v[214:215], v[202:203]
	v_pk_fma_f32 v[122:123], v[122:123], v[212:213], v[200:201]
	flat_store_dwordx4 v[152:153], v[126:129]
	flat_store_dwordx4 v[152:153], v[122:125] offset:16
	v_mul_f32_e32 v157, v127, v127
	v_fmac_f32_e32 v157, v126, v126
	v_fmac_f32_e32 v157, v128, v128
	v_add_u32_e32 v196, s20, v156
	v_fmac_f32_e32 v157, v129, v129
	v_ashrrev_i32_e32 v197, 31, v196
	v_fmac_f32_e32 v157, v122, v122
	v_lshlrev_b64 v[196:197], 11, v[196:197]
	v_fmac_f32_e32 v157, v123, v123
	v_lshl_add_u64 v[196:197], s[38:39], 0, v[196:197]
	v_fmac_f32_e32 v157, v124, v124
	v_lshl_add_u64 v[200:201], v[158:159], 1, v[196:197]
	v_fmac_f32_e32 v157, v125, v125
	v_pk_mul_f32 v[126:127], v[126:127], v[224:225]
	v_pk_mul_f32 v[188:189], v[124:125], v[230:231]
	v_pk_mul_f32 v[124:125], v[122:123], v[228:229]
	v_pk_mul_f32 v[128:129], v[128:129], v[226:227]
	v_cvt_pk_bf16_f32 v122, v126, v127
	s_nop 0
	v_cvt_pk_bf16_f32 v123, v128, v129
	v_cvt_pk_bf16_f32 v124, v124, v125
	v_cvt_pk_bf16_f32 v125, v188, v189
	flat_store_dwordx4 v[200:201], v[122:125]
	s_nop 1
	v_add_u32_e32 v122, 0x80, v158
	v_ashrrev_i32_e32 v123, 31, v122
	v_lshl_add_u64 v[122:123], v[122:123], 2, s[70:71]
	flat_load_dwordx4 v[188:191], v[170:171] offset:512
	flat_load_dwordx4 v[192:195], v[170:171] offset:528
	s_waitcnt vmcnt(0) lgkmcnt(0)
	v_pk_fma_f32 v[120:121], v[120:121], v[218:219], v[190:191]
	v_pk_fma_f32 v[118:119], v[118:119], v[216:217], v[188:189]
	v_pk_fma_f32 v[116:117], v[116:117], v[222:223], v[194:195]
	v_pk_fma_f32 v[114:115], v[114:115], v[220:221], v[192:193]
	flat_store_dwordx4 v[152:153], v[118:121] offset:512
	flat_store_dwordx4 v[152:153], v[114:117] offset:528
	v_mul_f32_e32 v128, v119, v119
	v_fmac_f32_e32 v128, v118, v118
	v_fmac_f32_e32 v128, v120, v120
	v_fmac_f32_e32 v128, v121, v121
	v_fmac_f32_e32 v128, v114, v114
	v_fmac_f32_e32 v128, v115, v115
	v_fmac_f32_e32 v128, v116, v116
	v_fmac_f32_e32 v128, v117, v117
	v_add_f32_e32 v128, v157, v128
	v_pk_mul_f32 v[118:119], v[118:119], v[232:233]
	v_pk_mul_f32 v[124:125], v[116:117], v[238:239]
	v_pk_mul_f32 v[116:117], v[114:115], v[236:237]
	v_pk_mul_f32 v[120:121], v[120:121], v[234:235]
	v_cvt_pk_bf16_f32 v114, v118, v119
	s_nop 0
	v_cvt_pk_bf16_f32 v115, v120, v121
	v_cvt_pk_bf16_f32 v116, v116, v117
	v_cvt_pk_bf16_f32 v117, v124, v125
	flat_store_dwordx4 v[200:201], v[114:117] offset:256
	v_cmp_lt_i32_e64 s[36:37], v181, v176
	v_ashrrev_i32_e32 v157, 31, v156
	s_nop 0
	v_cndmask_b32_e64 v114, v174, v181, s[36:37]
	v_lshlrev_b32_e32 v114, 2, v114
	ds_bpermute_b32 v115, v114, v128
	v_cmp_lt_i32_e64 s[36:37], v182, v176
	s_waitcnt lgkmcnt(0)
	v_add_f32_e32 v116, v128, v115
	v_cndmask_b32_e64 v117, v174, v182, s[36:37]
	v_lshlrev_b32_e32 v115, 2, v117
	ds_bpermute_b32 v117, v115, v116
	s_and_saveexec_b64 s[36:37], vcc
	s_cbranch_execz .LBB0_994
	s_lshl_b64 s[50:51], s[20:21], 2
	s_add_u32 s50, s80, s50
	s_addc_u32 s51, s81, s51
	v_lshl_add_u64 v[118:119], v[156:157], 2, s[50:51]
	s_waitcnt lgkmcnt(0)
	v_add_f32_e32 v116, v116, v117
	flat_atomic_add_f32 v[118:119], v116
; DI void st8(bf16_t* p, const pg8::f32x4& v0, const pg8::f32x4& v1) { u32x4 w; w.x = cvtpk(v0[0], v0[1]); w.y = cvtpk(v0[2], v0[3]); w.z = cvtpk(v1[0], v1[1]); w.w = cvtpk(v1[2], v1[3]); *(u32x4*)p = w; }
;     DI void operator()(const pg8::f32x4 (&acc)[2][2][4][2], const pg8::Unit& u, int wr, int wc, int fr, int fq) const {
;     ...
;         const int b = u.pm / 9, seg = u.pm - b * 9, mrow = seg == 0 ? 32 : b;
;         const float* gbase = mods + (size_t)mrow * 6144 + gidx * 1024; const float* gpb = gp + (size_t)mrow * 1024;
; #pragma unroll
;         for (int ai = 0; ai < 2; ++ai)
; #pragma unroll
;             for (int m = 0; m < 4; ++m) { const int rit = ai * 128 + wr * 64 + m * 16 + fr; float ss = 0.f;
;                 const size_t roff = (seg == 0 ? (size_t)(b * TC + rit) * DM : (size_t)(b * SEQ + (seg - 1) * 256 + rit) * DM);
; #pragma unroll
;                 for (int bj = 0; bj < 2; ++bj) { const int col0 = u.pn * 256 + bj * 128 + wc * 32 + 8 * fq;
;                     float* p = (seg == 0 ? xc : out) + roff + col0; const float* q = (seg == 0 ? sc : sx) + roff + col0;
;                     const pg8::f32x4 g0 = *(const pg8::f32x4*)(gbase + col0), g1 = *(const pg8::f32x4*)(gbase + col0 + 4); pg8::f32x4 x0 = *(const pg8::f32x4*)q, x1 = *(const pg8::f32x4*)(q + 4);
;                     x0 += g0 * acc[ai][bj][m][0]; x1 += g1 * acc[ai][bj][m][1]; *(pg8::f32x4*)p = x0; *(pg8::f32x4*)(p + 4) = x1;
;                     if (emit) { const pg8::f32x4 p0 = *(const pg8::f32x4*)(gpb + col0), p1 = *(const pg8::f32x4*)(gpb + col0 + 4);
;                         ss += x0[0] * x0[0] + x0[1] * x0[1] + x0[2] * x0[2] + x0[3] * x0[3] + x1[0] * x1[0] + x1[1] * x1[1] + x1[2] * x1[2] + x1[3] * x1[3];
;                         st8(H + (size_t)(u.pm * 256 + rit) * 1024 + col0, x0 * p0, x1 * p1); }
;                     __builtin_amdgcn_sched_barrier(0); }
;                 if (emit) { ss += __shfl_xor(ss, 16, 64); ss += __shfl_xor(ss, 32, 64); if (fq == 0) atomicAdd(rs + u.pm * 256 + rit, ss); }
.LBB0_994:
	s_or_b64 exec, exec, s[36:37]
	v_add_u32_e32 v152, 16, v156
	v_add_u32_e32 v116, s57, v152
	s_waitcnt lgkmcnt(0)
	v_ashrrev_i32_e32 v117, 31, v116
	v_lshlrev_b64 v[120:121], 12, v[116:117]
	v_lshl_add_u64 v[116:117], s[58:59], 0, v[120:121]
	v_lshl_add_u64 v[128:129], v[116:117], 0, v[162:163]
	flat_load_dwordx4 v[116:119], v[128:129]
	flat_load_dwordx4 v[192:195], v[128:129] offset:16
	v_lshl_add_u64 v[120:121], s[60:61], 0, v[120:121]
	v_lshl_add_u64 v[120:121], v[120:121], 0, v[162:163]
	v_add_u32_e32 v152, s20, v152
	v_ashrrev_i32_e32 v153, 31, v152
	v_lshlrev_b64 v[152:153], 11, v[152:153]
	v_lshl_add_u64 v[152:153], s[38:39], 0, v[152:153]
	v_lshl_add_u64 v[152:153], v[158:159], 1, v[152:153]
	s_waitcnt vmcnt(0) lgkmcnt(0)
	v_pk_fma_f32 v[112:113], v[112:113], v[210:211], v[118:119]
	v_pk_fma_f32 v[110:111], v[110:111], v[208:209], v[116:117]
	v_pk_fma_f32 v[108:109], v[108:109], v[214:215], v[194:195]
	v_pk_fma_f32 v[106:107], v[106:107], v[212:213], v[192:193]
	flat_store_dwordx4 v[120:121], v[110:113]
	flat_store_dwordx4 v[120:121], v[106:109] offset:16
	v_mul_f32_e32 v169, v111, v111
	v_fmac_f32_e32 v169, v110, v110
	v_fmac_f32_e32 v169, v112, v112
	v_fmac_f32_e32 v169, v113, v113
	v_fmac_f32_e32 v169, v106, v106
	v_fmac_f32_e32 v169, v107, v107
	v_fmac_f32_e32 v169, v108, v108
	v_fmac_f32_e32 v169, v109, v109
	v_pk_mul_f32 v[110:111], v[110:111], v[224:225]
	v_pk_mul_f32 v[116:117], v[108:109], v[230:231]
	v_pk_mul_f32 v[108:109], v[106:107], v[228:229]
	v_pk_mul_f32 v[112:113], v[112:113], v[226:227]
	v_cvt_pk_bf16_f32 v106, v110, v111
	s_nop 0
	v_cvt_pk_bf16_f32 v107, v112, v113
	v_cvt_pk_bf16_f32 v108, v108, v109
	v_cvt_pk_bf16_f32 v109, v116, v117
	flat_store_dwordx4 v[152:153], v[106:109]
	flat_load_dwordx4 v[106:109], v[128:129] offset:512
	s_nop 0
	flat_load_dwordx4 v[124:127], v[128:129] offset:528
	s_waitcnt vmcnt(0) lgkmcnt(0)
	v_pk_fma_f32 v[104:105], v[104:105], v[218:219], v[108:109]
	v_pk_fma_f32 v[102:103], v[102:103], v[216:217], v[106:107]
	v_pk_fma_f32 v[100:101], v[100:101], v[222:223], v[126:127]
	v_pk_fma_f32 v[98:99], v[98:99], v[220:221], v[124:125]
	flat_store_dwordx4 v[120:121], v[102:105] offset:512
	flat_store_dwordx4 v[120:121], v[98:101] offset:528
	v_mul_f32_e32 v116, v103, v103
	v_fmac_f32_e32 v116, v102, v102
	v_fmac_f32_e32 v116, v104, v104
	v_fmac_f32_e32 v116, v105, v105
	v_fmac_f32_e32 v116, v98, v98
	v_fmac_f32_e32 v116, v99, v99
	v_fmac_f32_e32 v116, v100, v100
	v_fmac_f32_e32 v116, v101, v101
	v_add_f32_e32 v116, v169, v116
	v_pk_mul_f32 v[102:103], v[102:103], v[232:233]
	v_pk_mul_f32 v[106:107], v[100:101], v[238:239]
	v_pk_mul_f32 v[100:101], v[98:99], v[236:237]
	v_pk_mul_f32 v[104:105], v[104:105], v[234:235]
	v_cvt_pk_bf16_f32 v98, v102, v103
	s_nop 0
	v_cvt_pk_bf16_f32 v99, v104, v105
	v_cvt_pk_bf16_f32 v100, v100, v101
	v_cvt_pk_bf16_f32 v101, v106, v107
	flat_store_dwordx4 v[152:153], v[98:101] offset:256
	ds_bpermute_b32 v98, v114, v116
	s_waitcnt lgkmcnt(0)
	v_add_f32_e32 v98, v116, v98
	ds_bpermute_b32 v99, v115, v98
	s_and_saveexec_b64 s[36:37], vcc
	s_cbranch_execz .LBB0_996
	s_lshl_b64 s[50:51], s[20:21], 2
	s_add_u32 s50, s80, s50
	s_addc_u32 s51, s81, s51
	v_lshl_add_u64 v[100:101], v[156:157], 2, s[50:51]
	s_waitcnt lgkmcnt(0)
	v_add_f32_e32 v98, v98, v99
	flat_atomic_add_f32 v[100:101], v98 offset:64
.LBB0_996:
	s_or_b64 exec, exec, s[36:37]
	v_add_u32_e32 v120, 32, v156
	v_add_u32_e32 v98, s57, v120
	s_waitcnt lgkmcnt(0)
	v_ashrrev_i32_e32 v99, 31, v98
	v_lshlrev_b64 v[116:117], 12, v[98:99]
	v_lshl_add_u64 v[98:99], s[58:59], 0, v[116:117]
	v_lshl_add_u64 v[118:119], v[98:99], 0, v[162:163]
	flat_load_dwordx4 v[98:101], v[118:119]
	flat_load_dwordx4 v[110:113], v[118:119] offset:16
	v_lshl_add_u64 v[116:117], s[60:61], 0, v[116:117]
	v_lshl_add_u64 v[116:117], v[116:117], 0, v[162:163]
	s_waitcnt vmcnt(0) lgkmcnt(0)
	v_pk_fma_f32 v[96:97], v[96:97], v[210:211], v[100:101]
	v_pk_fma_f32 v[94:95], v[94:95], v[208:209], v[98:99]
	v_pk_fma_f32 v[92:93], v[92:93], v[214:215], v[112:113]
	v_pk_fma_f32 v[90:91], v[90:91], v[212:213], v[110:111]
	flat_store_dwordx4 v[116:117], v[94:97]
	flat_store_dwordx4 v[116:117], v[90:93] offset:16
	v_mul_f32_e32 v108, v95, v95
	v_fmac_f32_e32 v108, v94, v94
	v_fmac_f32_e32 v108, v96, v96
	v_add_u32_e32 v106, s20, v120
	v_fmac_f32_e32 v108, v97, v97
	v_ashrrev_i32_e32 v107, 31, v106
	v_fmac_f32_e32 v108, v90, v90
	v_lshlrev_b64 v[106:107], 11, v[106:107]
	v_fmac_f32_e32 v108, v91, v91
	v_lshl_add_u64 v[106:107], s[38:39], 0, v[106:107]
	v_fmac_f32_e32 v108, v92, v92
	v_lshl_add_u64 v[106:107], v[158:159], 1, v[106:107]
	v_fmac_f32_e32 v108, v93, v93
	v_pk_mul_f32 v[94:95], v[94:95], v[224:225]
	v_pk_mul_f32 v[98:99], v[92:93], v[230:231]
	v_pk_mul_f32 v[92:93], v[90:91], v[228:229]
	v_pk_mul_f32 v[96:97], v[96:97], v[226:227]
	v_cvt_pk_bf16_f32 v90, v94, v95
	s_nop 0
	v_cvt_pk_bf16_f32 v91, v96, v97
	v_cvt_pk_bf16_f32 v92, v92, v93
	v_cvt_pk_bf16_f32 v93, v98, v99
	flat_store_dwordx4 v[106:107], v[90:93]
	flat_load_dwordx4 v[90:93], v[118:119] offset:512
	s_nop 0
	flat_load_dwordx4 v[102:105], v[118:119] offset:528
	s_waitcnt vmcnt(0) lgkmcnt(0)
	v_pk_fma_f32 v[88:89], v[88:89], v[218:219], v[92:93]
	v_pk_fma_f32 v[86:87], v[86:87], v[216:217], v[90:91]
	v_pk_fma_f32 v[84:85], v[84:85], v[222:223], v[104:105]
	v_pk_fma_f32 v[82:83], v[82:83], v[220:221], v[102:103]
	flat_store_dwordx4 v[116:117], v[86:89] offset:512
	flat_store_dwordx4 v[116:117], v[82:85] offset:528
	v_mul_f32_e32 v98, v87, v87
	v_fmac_f32_e32 v98, v86, v86
	v_fmac_f32_e32 v98, v88, v88
	v_fmac_f32_e32 v98, v89, v89
	v_fmac_f32_e32 v98, v82, v82
	v_fmac_f32_e32 v98, v83, v83
	v_fmac_f32_e32 v98, v84, v84
	v_fmac_f32_e32 v98, v85, v85
	v_add_f32_e32 v98, v108, v98
	v_pk_mul_f32 v[86:87], v[86:87], v[232:233]
	v_pk_mul_f32 v[90:91], v[84:85], v[238:239]
	v_pk_mul_f32 v[84:85], v[82:83], v[236:237]
	v_pk_mul_f32 v[88:89], v[88:89], v[234:235]
	v_cvt_pk_bf16_f32 v82, v86, v87
	s_nop 0
	v_cvt_pk_bf16_f32 v83, v88, v89
	v_cvt_pk_bf16_f32 v84, v84, v85
	v_cvt_pk_bf16_f32 v85, v90, v91
	flat_store_dwordx4 v[106:107], v[82:85] offset:256
	ds_bpermute_b32 v82, v114, v98
	s_waitcnt lgkmcnt(0)
	v_add_f32_e32 v82, v98, v82
	ds_bpermute_b32 v83, v115, v82
	s_and_saveexec_b64 s[36:37], vcc
	s_cbranch_execz .LBB0_998
	s_lshl_b64 s[50:51], s[20:21], 2
	s_add_u32 s50, s80, s50
	s_addc_u32 s51, s81, s51
	v_lshl_add_u64 v[84:85], v[156:157], 2, s[50:51]
	s_waitcnt lgkmcnt(0)
	v_add_f32_e32 v82, v82, v83
	flat_atomic_add_f32 v[84:85], v82 offset:128
; DI void st8(bf16_t* p, const pg8::f32x4& v0, const pg8::f32x4& v1) { u32x4 w; w.x = cvtpk(v0[0], v0[1]); w.y = cvtpk(v0[2], v0[3]); w.z = cvtpk(v1[0], v1[1]); w.w = cvtpk(v1[2], v1[3]); *(u32x4*)p = w; }
;     DI void operator()(const pg8::f32x4 (&acc)[2][2][4][2], const pg8::Unit& u, int wr, int wc, int fr, int fq) const {
;     ...
;         const int b = u.pm / 9, seg = u.pm - b * 9, mrow = seg == 0 ? 32 : b;
;         const float* gbase = mods + (size_t)mrow * 6144 + gidx * 1024; const float* gpb = gp + (size_t)mrow * 1024;
; #pragma unroll
;         for (int ai = 0; ai < 2; ++ai)
; #pragma unroll
;             for (int m = 0; m < 4; ++m) { const int rit = ai * 128 + wr * 64 + m * 16 + fr; float ss = 0.f;
;                 const size_t roff = (seg == 0 ? (size_t)(b * TC + rit) * DM : (size_t)(b * SEQ + (seg - 1) * 256 + rit) * DM);
; #pragma unroll
;                 for (int bj = 0; bj < 2; ++bj) { const int col0 = u.pn * 256 + bj * 128 + wc * 32 + 8 * fq;
;                     float* p = (seg == 0 ? xc : out) + roff + col0; const float* q = (seg == 0 ? sc : sx) + roff + col0;
;                     const pg8::f32x4 g0 = *(const pg8::f32x4*)(gbase + col0), g1 = *(const pg8::f32x4*)(gbase + col0 + 4); pg8::f32x4 x0 = *(const pg8::f32x4*)q, x1 = *(const pg8::f32x4*)(q + 4);
;                     x0 += g0 * acc[ai][bj][m][0]; x1 += g1 * acc[ai][bj][m][1]; *(pg8::f32x4*)p = x0; *(pg8::f32x4*)(p + 4) = x1;
;                     if (emit) { const pg8::f32x4 p0 = *(const pg8::f32x4*)(gpb + col0), p1 = *(const pg8::f32x4*)(gpb + col0 + 4);
;                         ss += x0[0] * x0[0] + x0[1] * x0[1] + x0[2] * x0[2] + x0[3] * x0[3] + x1[0] * x1[0] + x1[1] * x1[1] + x1[2] * x1[2] + x1[3] * x1[3];
;                         st8(H + (size_t)(u.pm * 256 + rit) * 1024 + col0, x0 * p0, x1 * p1); }
;                     __builtin_amdgcn_sched_barrier(0); }
;                 if (emit) { ss += __shfl_xor(ss, 16, 64); ss += __shfl_xor(ss, 32, 64); if (fq == 0) atomicAdd(rs + u.pm * 256 + rit, ss); }
.LBB0_998:
	s_or_b64 exec, exec, s[36:37]
	v_add_u32_e32 v102, 48, v156
	v_add_u32_e32 v82, s57, v102
	s_waitcnt lgkmcnt(0)
	v_ashrrev_i32_e32 v83, 31, v82
	v_lshlrev_b64 v[98:99], 12, v[82:83]
	v_lshl_add_u64 v[82:83], s[58:59], 0, v[98:99]
	v_lshl_add_u64 v[100:101], v[82:83], 0, v[162:163]
	flat_load_dwordx4 v[82:85], v[100:101]
	flat_load_dwordx4 v[94:97], v[100:101] offset:16
	v_lshl_add_u64 v[98:99], s[60:61], 0, v[98:99]
	v_lshl_add_u64 v[98:99], v[98:99], 0, v[162:163]
	s_waitcnt vmcnt(0) lgkmcnt(0)
	v_pk_fma_f32 v[80:81], v[80:81], v[210:211], v[84:85]
	v_pk_fma_f32 v[78:79], v[78:79], v[208:209], v[82:83]
	v_pk_fma_f32 v[76:77], v[76:77], v[214:215], v[96:97]
	v_pk_fma_f32 v[74:75], v[74:75], v[212:213], v[94:95]
	flat_store_dwordx4 v[98:99], v[78:81]
	flat_store_dwordx4 v[98:99], v[74:77] offset:16
	v_mul_f32_e32 v92, v79, v79
	v_fmac_f32_e32 v92, v78, v78
	v_fmac_f32_e32 v92, v80, v80
	v_add_u32_e32 v90, s20, v102
	v_fmac_f32_e32 v92, v81, v81
	v_ashrrev_i32_e32 v91, 31, v90
	v_fmac_f32_e32 v92, v74, v74
	v_lshlrev_b64 v[90:91], 11, v[90:91]
	v_fmac_f32_e32 v92, v75, v75
	v_lshl_add_u64 v[90:91], s[38:39], 0, v[90:91]
	v_fmac_f32_e32 v92, v76, v76
	v_lshl_add_u64 v[90:91], v[158:159], 1, v[90:91]
	v_fmac_f32_e32 v92, v77, v77
	v_pk_mul_f32 v[78:79], v[78:79], v[224:225]
	v_pk_mul_f32 v[82:83], v[76:77], v[230:231]
	v_pk_mul_f32 v[76:77], v[74:75], v[228:229]
	v_pk_mul_f32 v[80:81], v[80:81], v[226:227]
	v_cvt_pk_bf16_f32 v74, v78, v79
	s_nop 0
	v_cvt_pk_bf16_f32 v75, v80, v81
	v_cvt_pk_bf16_f32 v76, v76, v77
	v_cvt_pk_bf16_f32 v77, v82, v83
	flat_store_dwordx4 v[90:91], v[74:77]
	flat_load_dwordx4 v[74:77], v[100:101] offset:512
	s_nop 0
	flat_load_dwordx4 v[86:89], v[100:101] offset:528
	s_waitcnt vmcnt(0) lgkmcnt(0)
	v_pk_fma_f32 v[72:73], v[72:73], v[218:219], v[76:77]
	v_pk_fma_f32 v[70:71], v[70:71], v[216:217], v[74:75]
	v_pk_fma_f32 v[68:69], v[68:69], v[222:223], v[88:89]
	v_pk_fma_f32 v[66:67], v[66:67], v[220:221], v[86:87]
	flat_store_dwordx4 v[98:99], v[70:73] offset:512
	flat_store_dwordx4 v[98:99], v[66:69] offset:528
	v_mul_f32_e32 v82, v71, v71
	v_fmac_f32_e32 v82, v70, v70
	v_fmac_f32_e32 v82, v72, v72
	v_fmac_f32_e32 v82, v73, v73
	v_fmac_f32_e32 v82, v66, v66
	v_fmac_f32_e32 v82, v67, v67
	v_fmac_f32_e32 v82, v68, v68
	v_fmac_f32_e32 v82, v69, v69
	v_add_f32_e32 v82, v92, v82
	v_pk_mul_f32 v[70:71], v[70:71], v[232:233]
	v_pk_mul_f32 v[74:75], v[68:69], v[238:239]
	v_pk_mul_f32 v[68:69], v[66:67], v[236:237]
	v_pk_mul_f32 v[72:73], v[72:73], v[234:235]
	v_cvt_pk_bf16_f32 v66, v70, v71
	s_nop 0
	v_cvt_pk_bf16_f32 v67, v72, v73
	v_cvt_pk_bf16_f32 v68, v68, v69
	v_cvt_pk_bf16_f32 v69, v74, v75
	flat_store_dwordx4 v[90:91], v[66:69] offset:256
	ds_bpermute_b32 v66, v114, v82
	s_waitcnt lgkmcnt(0)
	v_add_f32_e32 v66, v82, v66
	ds_bpermute_b32 v67, v115, v66
	s_and_saveexec_b64 s[36:37], vcc
	s_cbranch_execz .LBB0_1000
	s_lshl_b64 s[50:51], s[20:21], 2
	s_add_u32 s50, s80, s50
	s_addc_u32 s51, s81, s51
	v_lshl_add_u64 v[68:69], v[156:157], 2, s[50:51]
	s_waitcnt lgkmcnt(0)
	v_add_f32_e32 v66, v66, v67
	flat_atomic_add_f32 v[68:69], v66 offset:192
.LBB0_1000:
	s_or_b64 exec, exec, s[36:37]
	v_add_u32_e32 v86, 0x80, v156
	v_add_u32_e32 v66, s57, v86
	s_waitcnt lgkmcnt(0)
	v_ashrrev_i32_e32 v67, 31, v66
	v_lshlrev_b64 v[82:83], 12, v[66:67]
	v_lshl_add_u64 v[66:67], s[58:59], 0, v[82:83]
	v_lshl_add_u64 v[84:85], v[66:67], 0, v[162:163]
	flat_load_dwordx4 v[66:69], v[84:85]
	flat_load_dwordx4 v[78:81], v[84:85] offset:16
	v_lshl_add_u64 v[82:83], s[60:61], 0, v[82:83]
	v_lshl_add_u64 v[82:83], v[82:83], 0, v[162:163]
	s_waitcnt vmcnt(0) lgkmcnt(0)
	v_pk_fma_f32 v[64:65], v[64:65], v[210:211], v[68:69]
	v_pk_fma_f32 v[62:63], v[62:63], v[208:209], v[66:67]
	v_pk_fma_f32 v[60:61], v[60:61], v[214:215], v[80:81]
	v_pk_fma_f32 v[58:59], v[58:59], v[212:213], v[78:79]
	flat_store_dwordx4 v[82:83], v[62:65]
	flat_store_dwordx4 v[82:83], v[58:61] offset:16
	v_mul_f32_e32 v76, v63, v63
	v_fmac_f32_e32 v76, v62, v62
	v_fmac_f32_e32 v76, v64, v64
	v_add_u32_e32 v74, s20, v86
	v_fmac_f32_e32 v76, v65, v65
	v_ashrrev_i32_e32 v75, 31, v74
	v_fmac_f32_e32 v76, v58, v58
	v_lshlrev_b64 v[74:75], 11, v[74:75]
	v_fmac_f32_e32 v76, v59, v59
	v_lshl_add_u64 v[74:75], s[38:39], 0, v[74:75]
	v_fmac_f32_e32 v76, v60, v60
	v_lshl_add_u64 v[74:75], v[158:159], 1, v[74:75]
	v_fmac_f32_e32 v76, v61, v61
	v_pk_mul_f32 v[62:63], v[62:63], v[224:225]
	v_pk_mul_f32 v[66:67], v[60:61], v[230:231]
	v_pk_mul_f32 v[60:61], v[58:59], v[228:229]
	v_pk_mul_f32 v[64:65], v[64:65], v[226:227]
	v_cvt_pk_bf16_f32 v58, v62, v63
	s_nop 0
	v_cvt_pk_bf16_f32 v59, v64, v65
	v_cvt_pk_bf16_f32 v60, v60, v61
	v_cvt_pk_bf16_f32 v61, v66, v67
	flat_store_dwordx4 v[74:75], v[58:61]
	flat_load_dwordx4 v[58:61], v[84:85] offset:512
	s_nop 0
	flat_load_dwordx4 v[70:73], v[84:85] offset:528
	s_waitcnt vmcnt(0) lgkmcnt(0)
	v_pk_fma_f32 v[56:57], v[56:57], v[218:219], v[60:61]
	v_pk_fma_f32 v[54:55], v[54:55], v[216:217], v[58:59]
	v_pk_fma_f32 v[52:53], v[52:53], v[222:223], v[72:73]
	v_pk_fma_f32 v[50:51], v[50:51], v[220:221], v[70:71]
	flat_store_dwordx4 v[82:83], v[54:57] offset:512
	flat_store_dwordx4 v[82:83], v[50:53] offset:528
	v_mul_f32_e32 v66, v55, v55
	v_fmac_f32_e32 v66, v54, v54
	v_fmac_f32_e32 v66, v56, v56
	v_fmac_f32_e32 v66, v57, v57
	v_fmac_f32_e32 v66, v50, v50
	v_fmac_f32_e32 v66, v51, v51
	v_fmac_f32_e32 v66, v52, v52
	v_fmac_f32_e32 v66, v53, v53
	v_add_f32_e32 v66, v76, v66
	v_pk_mul_f32 v[54:55], v[54:55], v[232:233]
	v_pk_mul_f32 v[58:59], v[52:53], v[238:239]
	v_pk_mul_f32 v[52:53], v[50:51], v[236:237]
	v_pk_mul_f32 v[56:57], v[56:57], v[234:235]
	v_cvt_pk_bf16_f32 v50, v54, v55
	s_nop 0
	v_cvt_pk_bf16_f32 v51, v56, v57
	v_cvt_pk_bf16_f32 v52, v52, v53
	v_cvt_pk_bf16_f32 v53, v58, v59
	flat_store_dwordx4 v[74:75], v[50:53] offset:256
	ds_bpermute_b32 v50, v114, v66
	s_waitcnt lgkmcnt(0)
	v_add_f32_e32 v50, v66, v50
	ds_bpermute_b32 v51, v115, v50
	s_and_saveexec_b64 s[36:37], vcc
	s_cbranch_execz .LBB0_1002
	s_lshl_b64 s[50:51], s[20:21], 2
	s_add_u32 s50, s80, s50
	s_addc_u32 s51, s81, s51
	v_lshl_add_u64 v[52:53], v[156:157], 2, s[50:51]
	s_waitcnt lgkmcnt(0)
	v_add_f32_e32 v50, v50, v51
	flat_atomic_add_f32 v[52:53], v50 offset:512
; DI void st8(bf16_t* p, const pg8::f32x4& v0, const pg8::f32x4& v1) { u32x4 w; w.x = cvtpk(v0[0], v0[1]); w.y = cvtpk(v0[2], v0[3]); w.z = cvtpk(v1[0], v1[1]); w.w = cvtpk(v1[2], v1[3]); *(u32x4*)p = w; }
;     DI void operator()(const pg8::f32x4 (&acc)[2][2][4][2], const pg8::Unit& u, int wr, int wc, int fr, int fq) const {
;     ...
;         const int b = u.pm / 9, seg = u.pm - b * 9, mrow = seg == 0 ? 32 : b;
;         const float* gbase = mods + (size_t)mrow * 6144 + gidx * 1024; const float* gpb = gp + (size_t)mrow * 1024;
; #pragma unroll
;         for (int ai = 0; ai < 2; ++ai)
; #pragma unroll
;             for (int m = 0; m < 4; ++m) { const int rit = ai * 128 + wr * 64 + m * 16 + fr; float ss = 0.f;
;                 const size_t roff = (seg == 0 ? (size_t)(b * TC + rit) * DM : (size_t)(b * SEQ + (seg - 1) * 256 + rit) * DM);
; #pragma unroll
;                 for (int bj = 0; bj < 2; ++bj) { const int col0 = u.pn * 256 + bj * 128 + wc * 32 + 8 * fq;
;                     float* p = (seg == 0 ? xc : out) + roff + col0; const float* q = (seg == 0 ? sc : sx) + roff + col0;
;                     const pg8::f32x4 g0 = *(const pg8::f32x4*)(gbase + col0), g1 = *(const pg8::f32x4*)(gbase + col0 + 4); pg8::f32x4 x0 = *(const pg8::f32x4*)q, x1 = *(const pg8::f32x4*)(q + 4);
;                     x0 += g0 * acc[ai][bj][m][0]; x1 += g1 * acc[ai][bj][m][1]; *(pg8::f32x4*)p = x0; *(pg8::f32x4*)(p + 4) = x1;
;                     if (emit) { const pg8::f32x4 p0 = *(const pg8::f32x4*)(gpb + col0), p1 = *(const pg8::f32x4*)(gpb + col0 + 4);
;                         ss += x0[0] * x0[0] + x0[1] * x0[1] + x0[2] * x0[2] + x0[3] * x0[3] + x1[0] * x1[0] + x1[1] * x1[1] + x1[2] * x1[2] + x1[3] * x1[3];
;                         st8(H + (size_t)(u.pm * 256 + rit) * 1024 + col0, x0 * p0, x1 * p1); }
;                     __builtin_amdgcn_sched_barrier(0); }
;                 if (emit) { ss += __shfl_xor(ss, 16, 64); ss += __shfl_xor(ss, 32, 64); if (fq == 0) atomicAdd(rs + u.pm * 256 + rit, ss); }
.LBB0_1002:
	s_or_b64 exec, exec, s[36:37]
	v_add_u32_e32 v70, 0x90, v156
	v_add_u32_e32 v50, s57, v70
	s_waitcnt lgkmcnt(0)
	v_ashrrev_i32_e32 v51, 31, v50
	v_lshlrev_b64 v[66:67], 12, v[50:51]
	v_lshl_add_u64 v[50:51], s[58:59], 0, v[66:67]
	v_lshl_add_u64 v[68:69], v[50:51], 0, v[162:163]
	flat_load_dwordx4 v[50:53], v[68:69]
	flat_load_dwordx4 v[62:65], v[68:69] offset:16
	v_lshl_add_u64 v[66:67], s[60:61], 0, v[66:67]
	v_lshl_add_u64 v[66:67], v[66:67], 0, v[162:163]
	s_waitcnt vmcnt(0) lgkmcnt(0)
	v_pk_fma_f32 v[48:49], v[48:49], v[210:211], v[52:53]
	v_pk_fma_f32 v[46:47], v[46:47], v[208:209], v[50:51]
	v_pk_fma_f32 v[44:45], v[44:45], v[214:215], v[64:65]
	v_pk_fma_f32 v[42:43], v[42:43], v[212:213], v[62:63]
	flat_store_dwordx4 v[66:67], v[46:49]
	flat_store_dwordx4 v[66:67], v[42:45] offset:16
	v_mul_f32_e32 v60, v47, v47
	v_fmac_f32_e32 v60, v46, v46
	v_fmac_f32_e32 v60, v48, v48
	v_add_u32_e32 v58, s20, v70
	v_fmac_f32_e32 v60, v49, v49
	v_ashrrev_i32_e32 v59, 31, v58
	v_fmac_f32_e32 v60, v42, v42
	v_lshlrev_b64 v[58:59], 11, v[58:59]
	v_fmac_f32_e32 v60, v43, v43
	v_lshl_add_u64 v[58:59], s[38:39], 0, v[58:59]
	v_fmac_f32_e32 v60, v44, v44
	v_lshl_add_u64 v[58:59], v[158:159], 1, v[58:59]
	v_fmac_f32_e32 v60, v45, v45
	v_pk_mul_f32 v[46:47], v[46:47], v[224:225]
	v_pk_mul_f32 v[50:51], v[44:45], v[230:231]
	v_pk_mul_f32 v[44:45], v[42:43], v[228:229]
	v_pk_mul_f32 v[48:49], v[48:49], v[226:227]
	v_cvt_pk_bf16_f32 v42, v46, v47
	s_nop 0
	v_cvt_pk_bf16_f32 v43, v48, v49
	v_cvt_pk_bf16_f32 v44, v44, v45
	v_cvt_pk_bf16_f32 v45, v50, v51
	flat_store_dwordx4 v[58:59], v[42:45]
	flat_load_dwordx4 v[42:45], v[68:69] offset:512
	s_nop 0
	flat_load_dwordx4 v[54:57], v[68:69] offset:528
	s_waitcnt vmcnt(0) lgkmcnt(0)
	v_pk_fma_f32 v[40:41], v[40:41], v[218:219], v[44:45]
	v_pk_fma_f32 v[38:39], v[38:39], v[216:217], v[42:43]
	v_pk_fma_f32 v[36:37], v[36:37], v[222:223], v[56:57]
	v_pk_fma_f32 v[34:35], v[34:35], v[220:221], v[54:55]
	flat_store_dwordx4 v[66:67], v[38:41] offset:512
	flat_store_dwordx4 v[66:67], v[34:37] offset:528
	v_mul_f32_e32 v50, v39, v39
	v_fmac_f32_e32 v50, v38, v38
	v_fmac_f32_e32 v50, v40, v40
	v_fmac_f32_e32 v50, v41, v41
	v_fmac_f32_e32 v50, v34, v34
	v_fmac_f32_e32 v50, v35, v35
	v_fmac_f32_e32 v50, v36, v36
	v_fmac_f32_e32 v50, v37, v37
	v_add_f32_e32 v50, v60, v50
	v_pk_mul_f32 v[38:39], v[38:39], v[232:233]
	v_pk_mul_f32 v[42:43], v[36:37], v[238:239]
	v_pk_mul_f32 v[36:37], v[34:35], v[236:237]
	v_pk_mul_f32 v[40:41], v[40:41], v[234:235]
	v_cvt_pk_bf16_f32 v34, v38, v39
	s_nop 0
	v_cvt_pk_bf16_f32 v35, v40, v41
	v_cvt_pk_bf16_f32 v36, v36, v37
	v_cvt_pk_bf16_f32 v37, v42, v43
	flat_store_dwordx4 v[58:59], v[34:37] offset:256
	ds_bpermute_b32 v34, v114, v50
	s_waitcnt lgkmcnt(0)
	v_add_f32_e32 v34, v50, v34
	ds_bpermute_b32 v35, v115, v34
	s_and_saveexec_b64 s[36:37], vcc
	s_cbranch_execz .LBB0_1004
	s_lshl_b64 s[50:51], s[20:21], 2
	s_add_u32 s50, s80, s50
	s_addc_u32 s51, s81, s51
	v_lshl_add_u64 v[36:37], v[156:157], 2, s[50:51]
	s_waitcnt lgkmcnt(0)
	v_add_f32_e32 v34, v34, v35
	flat_atomic_add_f32 v[36:37], v34 offset:576
; DI void st8(bf16_t* p, const pg8::f32x4& v0, const pg8::f32x4& v1) { u32x4 w; w.x = cvtpk(v0[0], v0[1]); w.y = cvtpk(v0[2], v0[3]); w.z = cvtpk(v1[0], v1[1]); w.w = cvtpk(v1[2], v1[3]); *(u32x4*)p = w; }
;     DI void operator()(const pg8::f32x4 (&acc)[2][2][4][2], const pg8::Unit& u, int wr, int wc, int fr, int fq) const {
;     ...
;         const int b = u.pm / 9, seg = u.pm - b * 9, mrow = seg == 0 ? 32 : b;
;         const float* gbase = mods + (size_t)mrow * 6144 + gidx * 1024; const float* gpb = gp + (size_t)mrow * 1024;
; #pragma unroll
;         for (int ai = 0; ai < 2; ++ai)
; #pragma unroll
;             for (int m = 0; m < 4; ++m) { const int rit = ai * 128 + wr * 64 + m * 16 + fr; float ss = 0.f;
;                 const size_t roff = (seg == 0 ? (size_t)(b * TC + rit) * DM : (size_t)(b * SEQ + (seg - 1) * 256 + rit) * DM);
; #pragma unroll
;                 for (int bj = 0; bj < 2; ++bj) { const int col0 = u.pn * 256 + bj * 128 + wc * 32 + 8 * fq;
;                     float* p = (seg == 0 ? xc : out) + roff + col0; const float* q = (seg == 0 ? sc : sx) + roff + col0;
;                     const pg8::f32x4 g0 = *(const pg8::f32x4*)(gbase + col0), g1 = *(const pg8::f32x4*)(gbase + col0 + 4); pg8::f32x4 x0 = *(const pg8::f32x4*)q, x1 = *(const pg8::f32x4*)(q + 4);
;                     x0 += g0 * acc[ai][bj][m][0]; x1 += g1 * acc[ai][bj][m][1]; *(pg8::f32x4*)p = x0; *(pg8::f32x4*)(p + 4) = x1;
;                     if (emit) { const pg8::f32x4 p0 = *(const pg8::f32x4*)(gpb + col0), p1 = *(const pg8::f32x4*)(gpb + col0 + 4);
;                         ss += x0[0] * x0[0] + x0[1] * x0[1] + x0[2] * x0[2] + x0[3] * x0[3] + x1[0] * x1[0] + x1[1] * x1[1] + x1[2] * x1[2] + x1[3] * x1[3];
;                         st8(H + (size_t)(u.pm * 256 + rit) * 1024 + col0, x0 * p0, x1 * p1); }
;                     __builtin_amdgcn_sched_barrier(0); }
;                 if (emit) { ss += __shfl_xor(ss, 16, 64); ss += __shfl_xor(ss, 32, 64); if (fq == 0) atomicAdd(rs + u.pm * 256 + rit, ss); }
.LBB0_1004:
	s_or_b64 exec, exec, s[36:37]
	v_add_u32_e32 v54, 0xa0, v156
	v_add_u32_e32 v34, s57, v54
	s_waitcnt lgkmcnt(0)
	v_ashrrev_i32_e32 v35, 31, v34
	v_lshlrev_b64 v[50:51], 12, v[34:35]
	v_lshl_add_u64 v[34:35], s[58:59], 0, v[50:51]
	v_lshl_add_u64 v[52:53], v[34:35], 0, v[162:163]
	flat_load_dwordx4 v[34:37], v[52:53]
	flat_load_dwordx4 v[46:49], v[52:53] offset:16
	v_lshl_add_u64 v[50:51], s[60:61], 0, v[50:51]
	v_lshl_add_u64 v[50:51], v[50:51], 0, v[162:163]
	s_waitcnt vmcnt(0) lgkmcnt(0)
	v_pk_fma_f32 v[32:33], v[32:33], v[210:211], v[36:37]
	v_pk_fma_f32 v[30:31], v[30:31], v[208:209], v[34:35]
	v_pk_fma_f32 v[28:29], v[28:29], v[214:215], v[48:49]
	v_pk_fma_f32 v[26:27], v[26:27], v[212:213], v[46:47]
	flat_store_dwordx4 v[50:51], v[30:33]
	flat_store_dwordx4 v[50:51], v[26:29] offset:16
	v_mul_f32_e32 v44, v31, v31
	v_fmac_f32_e32 v44, v30, v30
	v_fmac_f32_e32 v44, v32, v32
	v_add_u32_e32 v42, s20, v54
	v_fmac_f32_e32 v44, v33, v33
	v_ashrrev_i32_e32 v43, 31, v42
	v_fmac_f32_e32 v44, v26, v26
	v_lshlrev_b64 v[42:43], 11, v[42:43]
	v_fmac_f32_e32 v44, v27, v27
	v_lshl_add_u64 v[42:43], s[38:39], 0, v[42:43]
	v_fmac_f32_e32 v44, v28, v28
	v_lshl_add_u64 v[42:43], v[158:159], 1, v[42:43]
	v_fmac_f32_e32 v44, v29, v29
	v_pk_mul_f32 v[30:31], v[30:31], v[224:225]
	v_pk_mul_f32 v[34:35], v[28:29], v[230:231]
	v_pk_mul_f32 v[28:29], v[26:27], v[228:229]
	v_pk_mul_f32 v[32:33], v[32:33], v[226:227]
	v_cvt_pk_bf16_f32 v26, v30, v31
	s_nop 0
	v_cvt_pk_bf16_f32 v27, v32, v33
	v_cvt_pk_bf16_f32 v28, v28, v29
	v_cvt_pk_bf16_f32 v29, v34, v35
	flat_store_dwordx4 v[42:43], v[26:29]
	flat_load_dwordx4 v[26:29], v[52:53] offset:512
	s_nop 0
	flat_load_dwordx4 v[38:41], v[52:53] offset:528
	s_waitcnt vmcnt(0) lgkmcnt(0)
	v_pk_fma_f32 v[24:25], v[24:25], v[218:219], v[28:29]
	v_pk_fma_f32 v[22:23], v[22:23], v[216:217], v[26:27]
	v_pk_fma_f32 v[20:21], v[20:21], v[222:223], v[40:41]
	v_pk_fma_f32 v[18:19], v[18:19], v[220:221], v[38:39]
	flat_store_dwordx4 v[50:51], v[22:25] offset:512
	flat_store_dwordx4 v[50:51], v[18:21] offset:528
	v_mul_f32_e32 v34, v23, v23
	v_fmac_f32_e32 v34, v22, v22
	v_fmac_f32_e32 v34, v24, v24
	v_fmac_f32_e32 v34, v25, v25
	v_fmac_f32_e32 v34, v18, v18
	v_fmac_f32_e32 v34, v19, v19
	v_fmac_f32_e32 v34, v20, v20
	v_fmac_f32_e32 v34, v21, v21
	v_add_f32_e32 v34, v44, v34
	v_pk_mul_f32 v[22:23], v[22:23], v[232:233]
	v_pk_mul_f32 v[26:27], v[20:21], v[238:239]
	v_pk_mul_f32 v[20:21], v[18:19], v[236:237]
	v_pk_mul_f32 v[24:25], v[24:25], v[234:235]
	v_cvt_pk_bf16_f32 v18, v22, v23
	s_nop 0
	v_cvt_pk_bf16_f32 v19, v24, v25
	v_cvt_pk_bf16_f32 v20, v20, v21
	v_cvt_pk_bf16_f32 v21, v26, v27
	flat_store_dwordx4 v[42:43], v[18:21] offset:256
	ds_bpermute_b32 v18, v114, v34
	s_waitcnt lgkmcnt(0)
	v_add_f32_e32 v18, v34, v18
	ds_bpermute_b32 v19, v115, v18
	s_and_saveexec_b64 s[36:37], vcc
	s_cbranch_execz .LBB0_1006
	s_lshl_b64 s[50:51], s[20:21], 2
	s_add_u32 s50, s80, s50
	s_addc_u32 s51, s81, s51
	v_lshl_add_u64 v[20:21], v[156:157], 2, s[50:51]
	s_waitcnt lgkmcnt(0)
	v_add_f32_e32 v18, v18, v19
	flat_atomic_add_f32 v[20:21], v18 offset:640
.LBB0_1006:
	s_or_b64 exec, exec, s[36:37]
	v_add_u32_e32 v38, 0xb0, v156
	v_add_u32_e32 v18, s57, v38
	s_waitcnt lgkmcnt(0)
	v_ashrrev_i32_e32 v19, 31, v18
	v_lshlrev_b64 v[34:35], 12, v[18:19]
	v_lshl_add_u64 v[18:19], s[58:59], 0, v[34:35]
	v_lshl_add_u64 v[36:37], v[18:19], 0, v[162:163]
	flat_load_dwordx4 v[18:21], v[36:37]
	flat_load_dwordx4 v[30:33], v[36:37] offset:16
	v_lshl_add_u64 v[34:35], s[60:61], 0, v[34:35]
	v_lshl_add_u64 v[34:35], v[34:35], 0, v[162:163]
	s_waitcnt vmcnt(0) lgkmcnt(0)
	v_pk_fma_f32 v[16:17], v[16:17], v[210:211], v[20:21]
	v_pk_fma_f32 v[14:15], v[14:15], v[208:209], v[18:19]
	v_pk_fma_f32 v[12:13], v[12:13], v[214:215], v[32:33]
	v_pk_fma_f32 v[10:11], v[10:11], v[212:213], v[30:31]
	flat_store_dwordx4 v[34:35], v[14:17]
	flat_store_dwordx4 v[34:35], v[10:13] offset:16
	v_mul_f32_e32 v28, v15, v15
	v_fmac_f32_e32 v28, v14, v14
	v_fmac_f32_e32 v28, v16, v16
	v_add_u32_e32 v26, s20, v38
	v_fmac_f32_e32 v28, v17, v17
	v_ashrrev_i32_e32 v27, 31, v26
	v_fmac_f32_e32 v28, v10, v10
	v_lshlrev_b64 v[26:27], 11, v[26:27]
	v_fmac_f32_e32 v28, v11, v11
	v_lshl_add_u64 v[26:27], s[38:39], 0, v[26:27]
	v_fmac_f32_e32 v28, v12, v12
	v_lshl_add_u64 v[26:27], v[158:159], 1, v[26:27]
	v_fmac_f32_e32 v28, v13, v13
	v_pk_mul_f32 v[14:15], v[14:15], v[224:225]
	v_pk_mul_f32 v[18:19], v[12:13], v[230:231]
	v_pk_mul_f32 v[12:13], v[10:11], v[228:229]
	v_pk_mul_f32 v[16:17], v[16:17], v[226:227]
	v_cvt_pk_bf16_f32 v10, v14, v15
	s_nop 0
	v_cvt_pk_bf16_f32 v11, v16, v17
	v_cvt_pk_bf16_f32 v12, v12, v13
	v_cvt_pk_bf16_f32 v13, v18, v19
	flat_store_dwordx4 v[26:27], v[10:13]
	flat_load_dwordx4 v[10:13], v[36:37] offset:512
	s_nop 0
	flat_load_dwordx4 v[22:25], v[36:37] offset:528
	s_waitcnt vmcnt(0) lgkmcnt(0)
	v_pk_fma_f32 v[8:9], v[8:9], v[218:219], v[12:13]
	v_pk_fma_f32 v[6:7], v[6:7], v[216:217], v[10:11]
	v_pk_fma_f32 v[4:5], v[4:5], v[222:223], v[24:25]
	v_pk_fma_f32 v[2:3], v[2:3], v[220:221], v[22:23]
	flat_store_dwordx4 v[34:35], v[6:9] offset:512
	flat_store_dwordx4 v[34:35], v[2:5] offset:528
	v_mul_f32_e32 v18, v7, v7
	v_fmac_f32_e32 v18, v6, v6
	v_fmac_f32_e32 v18, v8, v8
	v_fmac_f32_e32 v18, v9, v9
	v_fmac_f32_e32 v18, v2, v2
	v_fmac_f32_e32 v18, v3, v3
	v_fmac_f32_e32 v18, v4, v4
	v_fmac_f32_e32 v18, v5, v5
	v_add_f32_e32 v18, v28, v18
	v_pk_mul_f32 v[6:7], v[6:7], v[232:233]
	v_pk_mul_f32 v[10:11], v[4:5], v[238:239]
	v_pk_mul_f32 v[4:5], v[2:3], v[236:237]
	v_pk_mul_f32 v[8:9], v[8:9], v[234:235]
	v_cvt_pk_bf16_f32 v2, v6, v7
	s_nop 0
	v_cvt_pk_bf16_f32 v3, v8, v9
	v_cvt_pk_bf16_f32 v4, v4, v5
	v_cvt_pk_bf16_f32 v5, v10, v11
	flat_store_dwordx4 v[26:27], v[2:5] offset:256
	ds_bpermute_b32 v2, v114, v18
	s_waitcnt lgkmcnt(0)
	v_add_f32_e32 v2, v18, v2
	ds_bpermute_b32 v3, v115, v2
	s_and_saveexec_b64 s[36:37], vcc
	s_cbranch_execz .LBB0_1008
	s_lshl_b64 s[20:21], s[20:21], 2
	s_add_u32 s20, s80, s20
	s_addc_u32 s21, s81, s21
	v_lshl_add_u64 v[4:5], v[156:157], 2, s[20:21]
	s_waitcnt lgkmcnt(0)
	v_add_f32_e32 v2, v2, v3
	flat_atomic_add_f32 v[4:5], v2 offset:704

; DI int ltid() { int t = threadIdx.x; asm volatile("" : "+v"(t)); return t; }
; DI void phase_scan(const bf16_t* R, const bf16_t* Kk, const bf16_t* V, const __half* DEC, const bf16_t* AA, const float* INV, const float* kkp, const float* kap,
;                    bf16_t* MIX, bf16_t* YB, char* lds) {
;     const int tid = ltid(); const bool consumer = tid < 256;
;     float* bufA = (float*)lds; float* ybufA = (float*)(lds + 98304); char* zimg = lds + 114688;
;     if (tid < 32) ((float*)zimg)[tid] = 0.f;
;     constexpr int NCH = TT / 16;
;     for (int s0 = blockIdx.x * 2; s0 < 512; s0 += gridDim.x * 2) {
;         const int p_ = tid & 255, pst = p_ & 15, pj0 = (p_ >> 4) * 4, pw = p_ >> 6;
;         const int cw = tid >> 6, cgrp = (cw >> 1) & 1, ws_ = cw & 1, lane = tid & 63, m = lane & 31, h = lane >> 5, vrow = ws_ * 32 + m;
;         const bool isaq = (m & ~5) == 0;
;         const int fragoff = (m & 1) ? 32 : 0;
;         f32x16 acc0, acc1, zero16;
; #pragma unroll
;         for (int r = 0; r < 16; ++r) { acc0[r] = 0.f; acc1[r] = 0.f; zero16[r] = 0.f; }
;         const int jl_ = pj0 & 31, rem_ = jl_ & 15, imgoff = ((((pj0 >> 5) * 2 + (jl_ >> 4)) * 2 + ((rem_ >> 2) & 1)) * 16 + ((rem_ >> 3) << 2) * 2) >> 2;
.LBB0_2262:
	s_and_b64 vcc, exec, s[0:1]
	s_cbranch_vccz .LBB0_2307
	v_mov_b32_e32 v0, v172
	s_nop 0
	v_cmp_gt_i32_e32 vcc, 32, v0
	s_and_saveexec_b64 s[0:1], vcc
	v_lshl_add_u32 v2, v0, 2, 0
	v_add_u32_e32 v2, 0x1c000, v2
	ds_write_b32 v2, v1
	s_or_b64 exec, exec, s[0:1]
	v_lshl_add_u32 v2, v0, 2, 0
	v_add_u32_e32 v2, 0x1c000, v2
	ds_write_b32 v2, v1
	ds_write_b32 v2, v1 offset:2048
	ds_write_b32 v2, v1 offset:4096
	ds_write_b32 v2, v1 offset:6144
	ds_write_b32 v2, v1 offset:8192
	ds_write_b32 v2, v1 offset:10240
	ds_write_b32 v2, v1 offset:12288
	ds_write_b32 v2, v1 offset:14336
	ds_write_b32 v2, v1 offset:16384
	v_readlane_b32 s0, v253, 12
	v_readlane_b32 s1, v253, 13
	s_andn2_b64 vcc, exec, s[0:1]
	s_cbranch_vccnz .LBB0_2307
	s_add_u32 s6, s22, 0x8900000
	s_addc_u32 s7, s23, 0
	s_add_u32 s8, s22, 0xd100000
	s_addc_u32 s9, s23, 0
	v_readlane_b32 s0, v252, 26
	s_cmp_lt_u32 s0, 12
	s_mov_b32 s0, 0x2400000
	s_cselect_b32 s0, s0, 0x3aa00000
	s_add_u32 s48, s22, s0
	s_addc_u32 s49, s23, 0
	s_add_u32 s62, s22, 0x11900000
	s_addc_u32 s63, s23, 0
	s_add_u32 s64, s22, 0x2d200000
	s_addc_u32 s65, s23, 0
	s_add_u32 s66, s22, 0x8600000
	v_readlane_b32 s0, v252, 29
	s_addc_u32 s67, s23, 0
	v_readlane_b32 s1, v252, 30
	s_lshl_b32 s0, s0, 9
	s_ashr_i32 s1, s0, 31
	s_lshl_b64 s[0:1], s[0:1], 2
	v_readlane_b32 s4, v252, 8
	v_readlane_b32 s5, v252, 9
	s_add_u32 s68, s4, s0
	s_addc_u32 s69, s5, s1
	v_readlane_b32 s4, v252, 14
	v_readlane_b32 s5, v252, 15
	s_add_u32 s70, s4, s0
	s_addc_u32 s71, s5, s1
	v_and_b32_e32 v6, 26, v0
	s_add_u32 s74, s22, 0x1cd00000
	v_lshrrev_b32_e32 v2, 2, v0
	v_and_b32_e32 v122, 31, v0
	v_lshrrev_b32_e32 v5, 1, v0
	v_cmp_eq_u32_e64 s[40:41], 0, v6
	v_lshlrev_b32_e32 v6, 5, v0
	s_addc_u32 s75, s23, 0
	s_movk_i32 s2, 0xff
	v_and_b32_e32 v120, 60, v2
	v_and_or_b32 v123, v5, 32, v122
	v_and_b32_e32 v124, 32, v6
	v_and_b32_e32 v5, 0x60, v5
	v_and_b32_e32 v6, 16, v0
	v_and_b32_e32 v2, 8, v2
	s_add_u32 s38, s22, 0x26600000
	v_cmp_lt_i32_e64 s[36:37], s2, v0
	v_and_b32_e32 v103, 15, v0
	v_or3_b32 v125, v2, v6, v5
	v_bitop3_b32 v126, v0, s2, 15 bitop3:0x6c
	v_and_b32_e32 v2, 48, v0
	s_movk_i32 s2, 0xef
	s_addc_u32 s39, s23, 0
	v_cmp_eq_u32_e64 s[42:43], 0, v2
	v_bitop3_b32 v129, v0, s2, 15 bitop3:0x6c
	v_lshlrev_b32_e32 v2, 8, v103
	s_add_i32 s2, 0, 0x18000
	v_lshlrev_b32_e32 v5, 2, v120
	v_bfe_u32 v3, v0, 7, 1
	v_add3_u32 v131, s2, v2, v5
	s_mov_b32 s2, 0xc000
	v_mad_u32_u24 v132, v3, s2, 0
	s_movk_i32 s2, 0x420
	v_mad_u32_u24 v139, v103, s2, 0
	v_readlane_b32 s2, v254, 34
	v_bfe_u32 v4, v0, 5, 1
	v_lshlrev_b32_e32 v133, 4, v4
	v_add_u32_e32 v157, s2, v5
	s_add_i32 s2, 0, 0x19000
	v_add_u32_e32 v135, -1, v4
	v_lshlrev_b32_e32 v136, 2, v4
	v_mov_b32_e32 v4, 0x8f0
	v_add3_u32 v158, s2, v2, v5
	s_add_i32 s2, 0, 0x1b000
	s_movk_i32 s0, 0x100
	v_mul_u32_u24_e32 v6, 0xc000, v3
	v_bitop3_b32 v138, v103, s15, v4 bitop3:0x36
	v_add3_u32 v159, s2, v2, v5
	v_lshlrev_b32_e32 v2, 1, v0
	v_lshlrev_b32_e32 v4, 2, v122
	v_cmp_gt_i32_e64 s[0:1], s0, v0
	v_bfe_u32 v121, v0, 6, 2
	v_add_u32_e32 v140, v139, v5
	v_add_u32_e32 v156, 0, v5
	v_and_b32_e32 v2, 0x80, v2
	v_or_b32_e32 v5, v6, v4
	v_and_b32_e32 v0, 1, v0
	v_lshlrev_b32_e32 v3, 13, v3
	s_add_i32 s24, 0, 0x1c000
	v_or_b32_e32 v7, v5, v2
	v_lshlrev_b32_e32 v0, 7, v0
	v_mul_u32_u24_e32 v127, 0x420, v103
	v_cmp_eq_u32_e64 s[44:45], 15, v103
	v_or_b32_e32 v128, 16, v103
	v_or_b32_e32 v130, 32, v103
	v_add_u32_e32 v134, s24, v133
	v_or_b32_e32 v137, 0x8f0, v103
	v_lshl_add_u32 v141, v121, 2, v139
	v_or_b32_e32 v160, 0x820, v6
	v_add_u32_e32 v161, 0x720, v7
	v_add_u32_e32 v162, 0x520, v5
	v_or3_b32 v163, v6, v0, v133
	v_or3_b32 v164, v3, v2, v4
	v_readlane_b32 s25, v253, 11
	s_branch .LBB0_2268

.LBB0_2268:
	s_and_saveexec_b64 s[20:21], s[36:37]
	s_cbranch_execz .LBB0_2278
	s_bfe_u32 s2, s25, 0x50003
	s_and_b32 s14, s25, 6
	s_cmpk_lt_u32 s25, 0x100
	s_cselect_b64 vcc, -1, 0
	v_cndmask_b32_e32 v0, v126, v103, vcc
	s_mulk_i32 s2, 0x900
	v_or_b32_e32 v10, s2, v0
	v_lshlrev_b32_e32 v0, 10, v10
	s_lshl_b32 s12, s25, 1
	v_lshl_add_u64 v[2:3], s[6:7], 0, v[0:1]
	v_lshl_add_u64 v[4:5], s[8:9], 0, v[0:1]
	v_lshl_add_u64 v[6:7], s[48:49], 0, v[0:1]
	v_lshlrev_b32_e32 v0, 11, v10
	s_and_b32 s26, s12, 0xfffffe00
	s_lshl_b32 s12, s14, 6
	v_lshl_add_u64 v[8:9], s[64:65], 0, v[0:1]
	v_lshlrev_b32_e32 v10, 5, v10
	v_mov_b32_e32 v11, v1
	v_lshl_add_u64 v[12:13], s[62:63], 0, v[0:1]
	v_or_b32_e32 v0, s12, v120
	v_lshl_add_u64 v[10:11], s[66:67], 0, v[10:11]
	v_lshlrev_b32_e32 v14, 1, v0
	v_mov_b32_e32 v15, v1
	s_lshl_b32 s52, s14, 2
	s_ashr_i32 s27, s26, 31
	v_lshl_add_u64 v[16:17], v[2:3], 0, v[14:15]
	v_lshl_add_u64 v[10:11], v[10:11], 0, s[52:53]
	s_lshl_b64 s[56:57], s[26:27], 1
	flat_load_dwordx2 v[34:35], v[16:17]
	flat_load_dwordx2 v[24:25], v[10:11]
	v_lshl_add_u64 v[16:17], v[4:5], 0, v[14:15]
	v_lshl_add_u64 v[8:9], v[8:9], 0, s[56:57]
	v_lshl_add_u64 v[12:13], v[12:13], 0, s[56:57]
	flat_load_dwordx2 v[36:37], v[16:17]
	v_lshl_add_u64 v[16:17], v[6:7], 0, v[14:15]
	flat_load_dwordx2 v[30:31], v[16:17]
	v_lshl_add_u64 v[16:17], v[8:9], 0, v[14:15]
	v_lshl_add_u64 v[10:11], v[12:13], 0, v[14:15]
	v_or_b32_e32 v15, 64, v0
	flat_load_dwordx2 v[32:33], v[16:17]
	v_lshlrev_b32_e32 v16, 1, v15
	v_mov_b32_e32 v17, v1
	v_lshl_add_u64 v[2:3], v[2:3], 0, v[16:17]
	flat_load_dwordx2 v[22:23], v[2:3]
	v_lshl_add_u64 v[2:3], v[4:5], 0, v[16:17]
	flat_load_dwordx2 v[26:27], v[2:3]
	v_lshl_add_u64 v[2:3], v[6:7], 0, v[16:17]
	flat_load_dwordx2 v[18:19], v[2:3]
	v_lshl_add_u64 v[2:3], v[8:9], 0, v[16:17]
	flat_load_dwordx2 v[20:21], v[2:3]
	v_lshl_add_u64 v[2:3], v[12:13], 0, v[16:17]
	v_cmp_lt_i32_e64 s[46:47], v181, v176
	flat_load_dwordx2 v[28:29], v[2:3]
	v_lshlrev_b32_e32 v0, 2, v0
	v_cndmask_b32_e64 v2, v174, v181, s[46:47]
	v_lshlrev_b32_e32 v15, 2, v2
	flat_load_dwordx2 v[2:3], v[10:11]
	s_waitcnt vmcnt(0) lgkmcnt(0)
	v_cvt_f32_f16_e32 v17, v2
	v_cvt_f32_f16_sdwa v38, v2 dst_sel:DWORD dst_unused:UNUSED_PAD src0_sel:WORD_1
	v_cvt_f32_f16_e32 v39, v3
	v_cvt_f32_f16_sdwa v40, v3 dst_sel:DWORD dst_unused:UNUSED_PAD src0_sel:WORD_1
	v_add_f32_dpp v2, v17, v17 row_shr:1 row_mask:0xf bank_mask:0xf bound_ctrl:1
	s_nop 1
	v_add_f32_dpp v2, v2, v2 row_shr:2 row_mask:0xf bank_mask:0xf bound_ctrl:1
	s_nop 1
	v_add_f32_dpp v2, v2, v2 row_shr:4 row_mask:0xf bank_mask:0xf bound_ctrl:1
	s_nop 1
	v_add_f32_dpp v41, v2, v2 row_shr:8 row_mask:0xf bank_mask:0xf bound_ctrl:1
	v_add_f32_dpp v2, v38, v38 row_shr:1 row_mask:0xf bank_mask:0xf bound_ctrl:1
	s_nop 1
	v_add_f32_dpp v2, v2, v2 row_shr:2 row_mask:0xf bank_mask:0xf bound_ctrl:1
	s_nop 1
	v_add_f32_dpp v2, v2, v2 row_shr:4 row_mask:0xf bank_mask:0xf bound_ctrl:1
	s_nop 1
	v_add_f32_dpp v46, v2, v2 row_shr:8 row_mask:0xf bank_mask:0xf bound_ctrl:1
	v_add_f32_dpp v2, v39, v39 row_shr:1 row_mask:0xf bank_mask:0xf bound_ctrl:1
	s_nop 1
	v_add_f32_dpp v2, v2, v2 row_shr:2 row_mask:0xf bank_mask:0xf bound_ctrl:1
	s_nop 1
	v_add_f32_dpp v2, v2, v2 row_shr:4 row_mask:0xf bank_mask:0xf bound_ctrl:1
	s_nop 1
	v_add_f32_dpp v47, v2, v2 row_shr:8 row_mask:0xf bank_mask:0xf bound_ctrl:1
	v_add_f32_dpp v2, v40, v40 row_shr:1 row_mask:0xf bank_mask:0xf bound_ctrl:1
	v_exp_f32_e32 v4, v47
	s_nop 0
	v_add_f32_dpp v2, v2, v2 row_shr:2 row_mask:0xf bank_mask:0xf bound_ctrl:1
	s_nop 1
	v_add_f32_dpp v2, v2, v2 row_shr:4 row_mask:0xf bank_mask:0xf bound_ctrl:1
	s_nop 1
	v_add_f32_dpp v48, v2, v2 row_shr:8 row_mask:0xf bank_mask:0xf bound_ctrl:1
	v_lshl_add_u64 v[2:3], s[68:69], 0, v[0:1]
	flat_load_dwordx4 v[6:9], v[2:3]
	v_lshl_add_u64 v[2:3], s[70:71], 0, v[0:1]
	flat_load_dwordx4 v[10:13], v[2:3]
	v_sub_f32_e32 v0, v41, v17
	v_exp_f32_e32 v44, v0
	v_sub_f32_e32 v0, v46, v38
	v_exp_f32_e32 v45, v0
	v_sub_f32_e32 v0, v47, v39
	v_exp_f32_e32 v3, v46
	v_exp_f32_e32 v42, v0
	v_sub_f32_e32 v0, v48, v40
	v_exp_f32_e64 v39, -v46
	v_exp_f32_e64 v40, -v47
	v_lshlrev_b32_e32 v46, 16, v36
	v_and_b32_e32 v47, 0xffff0000, v36
	v_exp_f32_e32 v43, v0
	v_exp_f32_e32 v2, v41
	v_exp_f32_e32 v5, v48
	v_exp_f32_e64 v38, -v41
	v_exp_f32_e64 v41, -v48
	v_add_u32_e32 v17, v139, v125
	s_waitcnt vmcnt(0) lgkmcnt(0)
	v_pk_mul_f32 v[6:7], v[6:7], v[46:47]
	s_nop 0
	v_pk_mul_f32 v[6:7], v[24:25], v[6:7] op_sel_hi:[0,1]
	v_pk_mul_f32 v[44:45], v[44:45], v[6:7] neg_lo:[0,1] neg_hi:[0,1]
	s_nop 0
	v_cvt_pk_bf16_f32 v36, v44, v45
	v_lshlrev_b32_e32 v44, 16, v37
	v_and_b32_e32 v45, 0xffff0000, v37
	v_pk_mul_f32 v[8:9], v[8:9], v[44:45]
	s_nop 0
	v_pk_mul_f32 v[8:9], v[24:25], v[8:9] op_sel_hi:[0,1]
	v_pk_mul_f32 v[42:43], v[42:43], v[8:9] neg_lo:[0,1] neg_hi:[0,1]
	s_nop 0
	v_cvt_pk_bf16_f32 v37, v42, v43
	v_lshlrev_b32_e32 v42, 16, v34
	v_and_b32_e32 v43, 0xffff0000, v34
	v_pk_mul_f32 v[48:49], v[2:3], v[42:43]
	s_nop 0
	v_cvt_pk_bf16_f32 v34, v48, v49
	v_lshlrev_b32_e32 v48, 16, v35
	v_and_b32_e32 v49, 0xffff0000, v35
	v_pk_mul_f32 v[50:51], v[4:5], v[48:49]
	s_nop 0
	v_cvt_pk_bf16_f32 v35, v50, v51
	ds_write2_b64 v17, v[36:37], v[34:35] offset1:16
	v_lshlrev_b32_e32 v34, 16, v32
	v_and_b32_e32 v35, 0xffff0000, v32
	v_lshlrev_b32_e32 v32, 16, v33
	v_and_b32_e32 v33, 0xffff0000, v33
	v_pk_mul_f32 v[36:37], v[6:7], v[34:35]
	v_pk_mul_f32 v[50:51], v[8:9], v[32:33]
	v_pk_mul_f32 v[6:7], v[38:39], v[36:37]
	v_pk_mul_f32 v[8:9], v[40:41], v[50:51]
	v_mov_b64_e32 v[210:211], v[6:7]
	v_mov_b64_e32 v[212:213], v[8:9]
	v_pk_add_f32 v[6:7], v[34:35], -1.0 op_sel_hi:[1,0]
	s_nop 0
	v_pk_fma_f32 v[6:7], v[6:7], v[10:11], 1.0 op_sel_hi:[1,1,0]
	s_nop 0
	v_pk_mul_f32 v[10:11], v[6:7], v[46:47]
	v_pk_add_f32 v[6:7], v[32:33], -1.0 op_sel_hi:[1,0]
	s_nop 0
	v_pk_fma_f32 v[6:7], v[6:7], v[12:13], 1.0 op_sel_hi:[1,1,0]
	s_nop 0
	v_pk_mul_f32 v[12:13], v[6:7], v[44:45]
	v_pk_mul_f32 v[6:7], v[38:39], v[10:11]
	v_pk_mul_f32 v[8:9], v[40:41], v[12:13]
	v_cvt_pk_bf16_f32 v214, v210, v6
	v_cvt_pk_bf16_f32 v215, v211, v7
	v_cvt_pk_bf16_f32 v216, v212, v8
	v_cvt_pk_bf16_f32 v217, v213, v9
	ds_write_b128 v140, v[214:217] offset:256
	v_lshlrev_b32_e32 v6, 16, v30
	v_and_b32_e32 v7, 0xffff0000, v30
	v_lshlrev_b32_e32 v8, 16, v31
	v_and_b32_e32 v9, 0xffff0000, v31
	ds_write_b128 v140, v[6:9] offset:768
	v_pk_mul_f32 v[6:7], v[36:37], v[42:43]
	v_pk_mul_f32 v[8:9], v[50:51], v[48:49]
	v_add_f32_e32 v0, v6, v7
	v_add_f32_e32 v0, v8, v0
	v_pk_mul_f32 v[6:7], v[10:11], v[42:43]
	v_add_f32_e32 v0, v9, v0
	v_pk_mul_f32 v[8:9], v[12:13], v[48:49]
	v_add_f32_e32 v6, v6, v7
	v_add_f32_e32 v6, v8, v6
	v_add_f32_e32 v7, v9, v6
	ds_bpermute_b32 v6, v15, v0
	ds_bpermute_b32 v8, v15, v7
	s_waitcnt lgkmcnt(1)
	v_add_f32_e32 v0, v0, v6
	s_waitcnt lgkmcnt(0)
	v_add_f32_e32 v7, v7, v8
	v_mov_b32_e32 v6, v0
	v_mov_b32_e32 v8, v7
	s_nop 0
	v_permlane32_swap_b32_e32 v0, v6
	v_permlane32_swap_b32_e32 v7, v8
	s_and_saveexec_b64 s[46:47], s[42:43]
	v_add_f32_e32 v7, v7, v8
	v_add_f32_e32 v0, v0, v6
	v_add_u32_e32 v6, 0x400, v141
	ds_write2_b32 v6, v0, v7 offset1:4
	s_or_b64 exec, exec, s[46:47]
	s_and_saveexec_b64 s[46:47], s[44:45]
	ds_write_b128 v156, v[2:5] offset:16896
	s_or_b64 exec, exec, s[46:47]
	v_cvt_f32_f16_e32 v10, v28
	v_cvt_f32_f16_sdwa v11, v28 dst_sel:DWORD dst_unused:UNUSED_PAD src0_sel:WORD_1
	v_cvt_f32_f16_e32 v12, v29
	v_cvt_f32_f16_sdwa v13, v29 dst_sel:DWORD dst_unused:UNUSED_PAD src0_sel:WORD_1
	v_add_f32_dpp v0, v10, v10 row_shr:1 row_mask:0xf bank_mask:0xf bound_ctrl:1
	v_lshlrev_b32_e32 v36, 16, v26
	v_and_b32_e32 v37, 0xffff0000, v26
	v_add_f32_dpp v0, v0, v0 row_shr:2 row_mask:0xf bank_mask:0xf bound_ctrl:1
	v_lshlrev_b32_e32 v26, 16, v27
	v_and_b32_e32 v27, 0xffff0000, v27
	v_add_f32_dpp v0, v0, v0 row_shr:4 row_mask:0xf bank_mask:0xf bound_ctrl:1
	v_lshlrev_b32_e32 v40, 16, v20
	v_and_b32_e32 v41, 0xffff0000, v20
	v_add_f32_dpp v32, v0, v0 row_shr:8 row_mask:0xf bank_mask:0xf bound_ctrl:1
	v_add_f32_dpp v0, v11, v11 row_shr:1 row_mask:0xf bank_mask:0xf bound_ctrl:1
	s_nop 1
	v_add_f32_dpp v0, v0, v0 row_shr:2 row_mask:0xf bank_mask:0xf bound_ctrl:1
	s_nop 1
	v_add_f32_dpp v0, v0, v0 row_shr:4 row_mask:0xf bank_mask:0xf bound_ctrl:1
	s_nop 1
	v_add_f32_dpp v33, v0, v0 row_shr:8 row_mask:0xf bank_mask:0xf bound_ctrl:1
	v_add_f32_dpp v0, v12, v12 row_shr:1 row_mask:0xf bank_mask:0xf bound_ctrl:1
	s_nop 1
	v_add_f32_dpp v0, v0, v0 row_shr:2 row_mask:0xf bank_mask:0xf bound_ctrl:1
	s_nop 1
	v_add_f32_dpp v0, v0, v0 row_shr:4 row_mask:0xf bank_mask:0xf bound_ctrl:1
	s_nop 1
	v_add_f32_dpp v34, v0, v0 row_shr:8 row_mask:0xf bank_mask:0xf bound_ctrl:1
	v_add_f32_dpp v0, v13, v13 row_shr:1 row_mask:0xf bank_mask:0xf bound_ctrl:1
	v_exp_f32_e32 v4, v34
	s_nop 0
	v_add_f32_dpp v0, v0, v0 row_shr:2 row_mask:0xf bank_mask:0xf bound_ctrl:1
	s_nop 1
	v_add_f32_dpp v0, v0, v0 row_shr:4 row_mask:0xf bank_mask:0xf bound_ctrl:1
	s_nop 1
	v_add_f32_dpp v35, v0, v0 row_shr:8 row_mask:0xf bank_mask:0xf bound_ctrl:1
	v_add_lshl_u32 v0, s12, v120, 2
	v_lshl_add_u64 v[2:3], s[68:69], 0, v[0:1]
	flat_load_dwordx4 v[6:9], v[2:3] offset:256
	v_lshl_add_u64 v[2:3], s[70:71], 0, v[0:1]
	flat_load_dwordx4 v[28:31], v[2:3] offset:256
	v_sub_f32_e32 v0, v32, v10
	v_exp_f32_e32 v10, v0
	v_sub_f32_e32 v0, v33, v11
	v_exp_f32_e32 v11, v0
	v_sub_f32_e32 v0, v34, v12
	v_exp_f32_e32 v12, v0
	v_sub_f32_e32 v0, v35, v13
	v_exp_f32_e32 v13, v0
	v_exp_f32_e32 v2, v32
	v_exp_f32_e32 v3, v33
	v_exp_f32_e32 v5, v35
	v_exp_f32_e64 v32, -v32
	v_exp_f32_e64 v33, -v33
	v_exp_f32_e64 v34, -v34
	v_exp_f32_e64 v35, -v35
	v_add_u32_e32 v0, 0xc000, v17
	s_waitcnt vmcnt(0) lgkmcnt(0)
	v_pk_mul_f32 v[6:7], v[6:7], v[36:37]
	s_nop 0
	v_pk_mul_f32 v[38:39], v[24:25], v[6:7] op_sel:[1,0]
	s_nop 0
	v_pk_mul_f32 v[6:7], v[10:11], v[38:39] neg_lo:[0,1] neg_hi:[0,1]
	s_nop 0
	v_cvt_pk_bf16_f32 v10, v6, v7
	v_pk_mul_f32 v[6:7], v[8:9], v[26:27]
	s_nop 0
	v_pk_mul_f32 v[24:25], v[24:25], v[6:7] op_sel:[1,0]
	s_nop 0
	v_pk_mul_f32 v[6:7], v[12:13], v[24:25] neg_lo:[0,1] neg_hi:[0,1]
	s_nop 0
	v_cvt_pk_bf16_f32 v11, v6, v7
	v_lshlrev_b32_e32 v6, 16, v22
	v_and_b32_e32 v7, 0xffff0000, v22
	v_pk_mul_f32 v[8:9], v[2:3], v[6:7]
	s_nop 0
	v_cvt_pk_bf16_f32 v12, v8, v9
	v_lshlrev_b32_e32 v8, 16, v23
	v_and_b32_e32 v9, 0xffff0000, v23
	v_pk_mul_f32 v[22:23], v[4:5], v[8:9]
	s_nop 0
	v_cvt_pk_bf16_f32 v13, v22, v23
	ds_write2_b64 v0, v[10:11], v[12:13] offset1:16
	v_pk_mul_f32 v[10:11], v[38:39], v[40:41]
	v_lshlrev_b32_e32 v38, 16, v21
	v_and_b32_e32 v39, 0xffff0000, v21
	v_pk_mul_f32 v[12:13], v[24:25], v[38:39]
	v_pk_mul_f32 v[20:21], v[32:33], v[10:11]
	v_pk_mul_f32 v[22:23], v[34:35], v[12:13]
	v_mov_b64_e32 v[210:211], v[20:21]
	v_mov_b64_e32 v[212:213], v[22:23]
	v_pk_add_f32 v[20:21], v[40:41], -1.0 op_sel_hi:[1,0]
	v_pk_add_f32 v[22:23], v[38:39], -1.0 op_sel_hi:[1,0]
	v_pk_fma_f32 v[20:21], v[20:21], v[28:29], 1.0 op_sel_hi:[1,1,0]
	v_pk_fma_f32 v[22:23], v[22:23], v[30:31], 1.0 op_sel_hi:[1,1,0]
	v_pk_mul_f32 v[20:21], v[20:21], v[36:37]
	v_pk_mul_f32 v[22:23], v[22:23], v[26:27]
	v_pk_mul_f32 v[10:11], v[10:11], v[6:7]
	v_pk_mul_f32 v[6:7], v[20:21], v[6:7]
	v_pk_mul_f32 v[12:13], v[12:13], v[8:9]
	v_add_f32_e32 v0, v10, v11
	v_pk_mul_f32 v[8:9], v[22:23], v[8:9]
	v_add_f32_e32 v6, v6, v7
	v_add_f32_e32 v0, v12, v0
	v_add_f32_e32 v6, v8, v6
	v_add_f32_e32 v0, v13, v0
	v_add_f32_e32 v7, v9, v6
	ds_bpermute_b32 v6, v15, v0
	ds_bpermute_b32 v8, v15, v7
	v_pk_mul_f32 v[24:25], v[32:33], v[20:21]
	v_pk_mul_f32 v[26:27], v[34:35], v[22:23]
	v_cvt_pk_bf16_f32 v214, v210, v24
	v_cvt_pk_bf16_f32 v215, v211, v25
	v_cvt_pk_bf16_f32 v216, v212, v26
	v_cvt_pk_bf16_f32 v217, v213, v27
	ds_write_b128 v140, v[214:217] offset:49408
	s_waitcnt lgkmcnt(2)
; #define LBAR() asm volatile("s_waitcnt lgkmcnt(0)\n\ts_barrier" ::: "memory")
; DI void phase_scan(const bf16_t* R, const bf16_t* Kk, const bf16_t* V, const __half* DEC, const bf16_t* AA, const float* INV, const float* kkp, const float* kap,
;                    bf16_t* MIX, bf16_t* YB, char* lds) {
;     ...
;         if (!consumer) { PLOAD(0); PWRITE(0); PLOAD(1); }
;         LBAR();
;         if (consumer) __builtin_amdgcn_s_setprio(3);
	v_add_f32_e32 v0, v0, v6
	s_waitcnt lgkmcnt(1)
	v_add_f32_e32 v7, v7, v8
	v_mov_b32_e32 v6, v0
	v_mov_b32_e32 v8, v7
	v_lshlrev_b32_e32 v24, 16, v18
	v_and_b32_e32 v25, 0xffff0000, v18
	v_lshlrev_b32_e32 v26, 16, v19
	v_and_b32_e32 v27, 0xffff0000, v19
	v_permlane32_swap_b32_e32 v0, v6
	v_permlane32_swap_b32_e32 v7, v8
	ds_write_b128 v140, v[24:27] offset:49920
	s_and_saveexec_b64 s[46:47], s[42:43]
	v_add_f32_e32 v7, v7, v8
	v_add_f32_e32 v0, v0, v6
	v_add_u32_e32 v6, 0xc400, v141
	ds_write2_b32 v6, v0, v7 offset1:4
	s_or_b64 exec, exec, s[46:47]
	s_and_saveexec_b64 s[46:47], s[44:45]
	ds_write_b128 v157, v[2:5]
	s_or_b64 exec, exec, s[46:47]
	v_cndmask_b32_e32 v0, v129, v128, vcc
	v_or_b32_e32 v10, s2, v0
	v_lshlrev_b32_e32 v0, 10, v10
	v_lshl_add_u64 v[2:3], s[6:7], 0, v[0:1]
	v_lshl_add_u64 v[4:5], s[8:9], 0, v[0:1]
	v_lshl_add_u64 v[6:7], s[48:49], 0, v[0:1]
	v_lshlrev_b32_e32 v0, 11, v10
	v_lshl_add_u64 v[8:9], s[64:65], 0, v[0:1]
	v_lshl_add_u64 v[12:13], s[62:63], 0, v[0:1]
	v_lshl_add_u64 v[8:9], v[8:9], 0, s[56:57]
	v_lshlrev_b32_e32 v10, 5, v10
	v_mov_b32_e32 v11, v1
	v_lshl_add_u64 v[12:13], v[12:13], 0, s[56:57]
	v_mov_b32_e32 v15, v1
	v_lshl_add_u64 v[10:11], s[66:67], 0, v[10:11]
	v_lshl_add_u64 v[18:19], v[2:3], 0, v[14:15]
	v_lshl_add_u64 v[20:21], v[4:5], 0, v[14:15]
	v_lshl_add_u64 v[22:23], v[6:7], 0, v[14:15]
	v_lshl_add_u64 v[24:25], v[8:9], 0, v[14:15]
	v_lshl_add_u64 v[14:15], v[12:13], 0, v[14:15]
	v_mov_b32_e32 v17, v1
	flat_load_dwordx2 v[80:81], v[18:19]
	flat_load_dwordx2 v[82:83], v[20:21]
	flat_load_dwordx2 v[84:85], v[22:23]
	flat_load_dwordx2 v[86:87], v[24:25]
	v_lshl_add_u64 v[10:11], v[10:11], 0, s[52:53]
	v_lshl_add_u64 v[2:3], v[2:3], 0, v[16:17]
	v_lshl_add_u64 v[4:5], v[4:5], 0, v[16:17]
	v_lshl_add_u64 v[6:7], v[6:7], 0, v[16:17]
	flat_load_dwordx2 v[94:95], v[14:15]
	flat_load_dwordx2 v[88:89], v[2:3]
	flat_load_dwordx2 v[90:91], v[4:5]
	flat_load_dwordx2 v[100:101], v[10:11]
	v_lshl_add_u64 v[8:9], v[8:9], 0, v[16:17]
	v_lshl_add_u64 v[2:3], v[12:13], 0, v[16:17]
	flat_load_dwordx2 v[92:93], v[6:7]
	flat_load_dwordx2 v[96:97], v[8:9]
	flat_load_dwordx2 v[98:99], v[2:3]
.LBB0_2278:
	s_or_b64 exec, exec, s[20:21]
	s_waitcnt lgkmcnt(0)
	s_barrier
	s_and_saveexec_b64 s[20:21], s[0:1]
	s_setprio 3
	s_or_b64 exec, exec, s[20:21]
	v_mov_b32_e32 v64, 0
	v_mov_b32_e32 v65, 0
	v_mov_b32_e32 v66, 0
	v_mov_b32_e32 v67, 0
	v_mov_b32_e32 v68, 0
	v_mov_b32_e32 v69, 0
	v_mov_b32_e32 v70, 0
	v_mov_b32_e32 v71, 0
	v_mov_b32_e32 v72, 0
	v_mov_b32_e32 v73, 0
	v_mov_b32_e32 v74, 0
	v_mov_b32_e32 v75, 0
	v_mov_b32_e32 v76, 0
	v_mov_b32_e32 v77, 0
	v_mov_b32_e32 v78, 0
	v_mov_b32_e32 v79, 0
	v_mov_b32_e32 v192, 0
	v_mov_b32_e32 v193, 0
	v_mov_b32_e32 v194, 0
	v_mov_b32_e32 v195, 0
	v_mov_b32_e32 v196, 0
	v_mov_b32_e32 v197, 0
	v_mov_b32_e32 v198, 0
	v_mov_b32_e32 v199, 0
	v_mov_b32_e32 v200, 0
	v_mov_b32_e32 v201, 0
	v_mov_b32_e32 v202, 0
	v_mov_b32_e32 v203, 0
	v_mov_b32_e32 v204, 0
	v_mov_b32_e32 v205, 0
	v_mov_b32_e32 v206, 0
	v_mov_b32_e32 v207, 0
	v_mov_b32_e32 v225, 0
	v_mov_b32_e32 v226, 0
	v_mov_b32_e32 v227, 0
	v_mov_b32_e32 v229, 0
	v_mov_b32_e32 v230, 0
	v_mov_b32_e32 v231, 0
	v_mov_b32_e32 v233, 0
	v_mov_b32_e32 v234, 0
	v_mov_b32_e32 v235, 0
	s_and_b32 s12, s25, 6
	s_bfe_u32 s2, s25, 0x50003
	s_cmpk_lt_u32 s25, 0x100
	s_cselect_b64 s[46:47], -1, 0
	s_cmpk_gt_u32 s25, 0xff
	s_cselect_b64 s[56:57], -1, 0
	s_lshl_b32 s14, s25, 1
	s_and_b32 s20, s14, 0xfffffe00
	s_ashr_i32 s21, s20, 31
	s_lshl_b64 s[20:21], s[20:21], 1
	s_add_u32 s58, s64, s20
	s_addc_u32 s59, s65, s21
	s_add_u32 s60, s62, s20
	v_lshl_or_b32 v102, s12, 6, v120
	s_addc_u32 s61, s63, s21
	v_lshlrev_b32_e32 v0, 2, v102
	s_lshl_b32 s12, s12, 2
	v_mov_b32_e32 v14, v1
	v_mov_b32_e32 v15, v1
	v_lshl_add_u64 v[104:105], s[68:69], 0, v[0:1]
	v_lshl_add_u64 v[106:107], s[70:71], 0, v[0:1]
	global_load_dwordx4 v[236:239], v[104:105], off
	global_load_dwordx4 v[240:243], v[106:107], off
	global_load_dwordx4 v[244:247], v[104:105], off offset:256
	global_load_dwordx4 v[248:251], v[106:107], off offset:256
	s_add_u32 s90, s66, s12
	v_mov_b32_e32 v0, v1
	v_mov_b32_e32 v2, v1
	v_mov_b32_e32 v3, v1
	v_mov_b32_e32 v4, v1
	v_mov_b32_e32 v5, v1
	v_mov_b32_e32 v6, v1
	v_mov_b32_e32 v7, v1
	v_mov_b32_e32 v8, v1
	v_mov_b32_e32 v9, v1
	v_mov_b32_e32 v10, v1
	v_mov_b32_e32 v11, v1
	v_mov_b32_e32 v12, v1
	v_mov_b32_e32 v13, v1
	v_mov_b64_e32 v[30:31], v[14:15]
	v_mov_b64_e32 v[46:47], v[14:15]
	s_mulk_i32 s2, 0x900
	s_addc_u32 s91, s67, 0
	s_mov_b32 s12, 0
	s_mov_b64 s[88:89], 0
	v_mov_b64_e32 v[28:29], v[12:13]
	v_mov_b64_e32 v[26:27], v[10:11]
	v_mov_b64_e32 v[24:25], v[8:9]
	v_mov_b64_e32 v[22:23], v[6:7]
	v_mov_b64_e32 v[20:21], v[4:5]
	v_mov_b64_e32 v[18:19], v[2:3]
	v_mov_b64_e32 v[16:17], v[0:1]
	v_mov_b64_e32 v[44:45], v[12:13]
	v_mov_b64_e32 v[42:43], v[10:11]
	v_mov_b64_e32 v[40:41], v[8:9]
	v_mov_b64_e32 v[38:39], v[6:7]
	v_mov_b64_e32 v[36:37], v[4:5]
	v_mov_b64_e32 v[34:35], v[2:3]
	v_mov_b64_e32 v[32:33], v[0:1]
	s_branch .LBB0_2282

; DI void phase_scan(const bf16_t* R, const bf16_t* Kk, const bf16_t* V, const __half* DEC, const bf16_t* AA, const float* INV, const float* kkp, const float* kap,
;                    bf16_t* MIX, bf16_t* YB, char* lds) {
;     ...
;                 if (c + 1 < NCH) PWRITE((c + 1) & 1);
;                 if (c + 2 < NCH) PLOAD(c + 2);
.LBB0_2282:
	s_and_saveexec_b64 s[20:21], s[36:37]
	s_xor_b64 s[20:21], exec, s[20:21]
	s_cbranch_execz .LBB0_2301
	s_cmp_gt_u32 s12, 1
	s_cbranch_scc1 .Lp_w2
	s_waitcnt vmcnt(0)
	s_branch .Lp_wd
.Lp_w2:
	s_waitcnt vmcnt(2)
.Lp_wd:
	v_mov_b64_e32 v[188:189], v[80:81]
	v_mov_b64_e32 v[190:191], v[82:83]
	v_mov_b64_e32 v[192:193], v[84:85]
	v_mov_b64_e32 v[194:195], v[86:87]
	v_mov_b64_e32 v[196:197], v[88:89]
	v_mov_b64_e32 v[198:199], v[90:91]
	v_mov_b64_e32 v[200:201], v[92:93]
	v_mov_b64_e32 v[202:203], v[94:95]
	v_mov_b64_e32 v[204:205], v[96:97]
	v_mov_b64_e32 v[206:207], v[98:99]
	v_mov_b64_e32 v[208:209], v[100:101]
	s_cmpk_gt_u32 s12, 0x8d
	s_cbranch_scc1 .Lp_noload
	s_cmp_gt_u32 s12, 13
	v_lshl_add_u32 v0, s12, 4, v130
	s_cselect_b32 s14, s15, 0xff
	v_sub_u32_e32 v2, s14, v0
	v_cndmask_b32_e64 v0, v2, v0, s[46:47]
	v_add_u32_e32 v2, s2, v0
	v_ashrrev_i32_e32 v3, 31, v2
	v_lshlrev_b64 v[4:5], 10, v[2:3]
	v_lshl_add_u64 v[6:7], s[6:7], 0, v[4:5]
	v_lshlrev_b64 v[10:11], 11, v[2:3]
	v_lshlrev_b32_e32 v0, 1, v102
	v_lshl_add_u64 v[8:9], s[8:9], 0, v[4:5]
	v_lshl_add_u64 v[4:5], s[48:49], 0, v[4:5]
	v_lshl_add_u64 v[12:13], s[58:59], 0, v[10:11]
	v_lshlrev_b64 v[2:3], 5, v[2:3]
	v_lshl_add_u64 v[10:11], s[60:61], 0, v[10:11]
	v_lshl_add_u64 v[6:7], v[6:7], 0, v[0:1]
	v_lshl_add_u64 v[8:9], v[8:9], 0, v[0:1]
	v_lshl_add_u64 v[4:5], v[4:5], 0, v[0:1]
	v_lshl_add_u64 v[12:13], v[12:13], 0, v[0:1]
	v_lshl_add_u64 v[2:3], s[90:91], 0, v[2:3]
	v_lshl_add_u64 v[10:11], v[10:11], 0, v[0:1]
	global_load_dwordx2 v[80:81], v[6:7], off
	global_load_dwordx2 v[82:83], v[8:9], off
	global_load_dwordx2 v[90:91], v[8:9], off offset:128
	global_load_dwordx2 v[88:89], v[6:7], off offset:128
	global_load_dwordx2 v[84:85], v[4:5], off
	global_load_dwordx2 v[86:87], v[12:13], off
	global_load_dwordx2 v[96:97], v[12:13], off offset:128
	global_load_dwordx2 v[92:93], v[4:5], off offset:128
	global_load_dwordx2 v[94:95], v[10:11], off
	global_load_dwordx2 v[98:99], v[10:11], off offset:128
	global_load_dwordx2 v[100:101], v[2:3], off
.Lp_noload:
	s_cmpk_eq_i32 s12, 0x8f
	s_cbranch_scc1 .Lp_nowrite
	v_mov_b64_e32 v[50:51], v[236:237]
	v_mov_b64_e32 v[52:53], v[238:239]
	v_mov_b64_e32 v[6:7], v[240:241]
	v_mov_b64_e32 v[8:9], v[242:243]
	v_cvt_f32_f16_e32 v10, v202
	v_cvt_f32_f16_sdwa v11, v202 dst_sel:DWORD dst_unused:UNUSED_PAD src0_sel:WORD_1
	v_cvt_f32_f16_e32 v12, v203
	v_cvt_f32_f16_sdwa v13, v203 dst_sel:DWORD dst_unused:UNUSED_PAD src0_sel:WORD_1
	v_add_f32_dpp v2, v10, v10 row_shr:1 row_mask:0xf bank_mask:0xf bound_ctrl:1
	v_lshlrev_b32_e32 v64, 16, v190
	v_and_b32_e32 v65, 0xffff0000, v190
	v_add_f32_dpp v2, v2, v2 row_shr:2 row_mask:0xf bank_mask:0xf bound_ctrl:1
	s_andn2_b32 s14, 1, s12
	s_mulk_i32 s14, 0x6000
	v_add_f32_dpp v2, v2, v2 row_shr:4 row_mask:0xf bank_mask:0xf bound_ctrl:1
	s_add_i32 s14, s14, 0
	v_add_u32_e32 v58, s14, v127
	v_add_f32_dpp v54, v2, v2 row_shr:8 row_mask:0xf bank_mask:0xf bound_ctrl:1
	v_add_f32_dpp v2, v11, v11 row_shr:1 row_mask:0xf bank_mask:0xf bound_ctrl:1
	v_sub_f32_e32 v10, v54, v10
	v_exp_f32_e32 v14, v10
	v_add_f32_dpp v2, v2, v2 row_shr:2 row_mask:0xf bank_mask:0xf bound_ctrl:1
	v_lshlrev_b32_e32 v68, 16, v195
	v_and_b32_e32 v69, 0xffff0000, v195
	v_add_f32_dpp v2, v2, v2 row_shr:4 row_mask:0xf bank_mask:0xf bound_ctrl:1
	v_cmp_lt_i32_e32 vcc, v181, v176
	v_pk_mul_f32 v[50:51], v[50:51], v[64:65]
	v_add_f32_dpp v55, v2, v2 row_shr:8 row_mask:0xf bank_mask:0xf bound_ctrl:1
	v_add_f32_dpp v2, v12, v12 row_shr:1 row_mask:0xf bank_mask:0xf bound_ctrl:1
	v_sub_f32_e32 v10, v55, v11
	v_exp_f32_e32 v15, v10
	v_add_f32_dpp v2, v2, v2 row_shr:2 row_mask:0xf bank_mask:0xf bound_ctrl:1
	v_exp_f32_e32 v3, v55
	v_exp_f32_e64 v11, -v55
	v_add_f32_dpp v2, v2, v2 row_shr:4 row_mask:0xf bank_mask:0xf bound_ctrl:1
	v_cndmask_b32_e32 v0, v174, v181, vcc
	v_lshlrev_b32_e32 v0, 2, v0
	v_add_f32_dpp v56, v2, v2 row_shr:8 row_mask:0xf bank_mask:0xf bound_ctrl:1
	v_add_f32_dpp v2, v13, v13 row_shr:1 row_mask:0xf bank_mask:0xf bound_ctrl:1
	v_sub_f32_e32 v10, v56, v12
	v_exp_f32_e32 v48, v10
	v_add_f32_dpp v2, v2, v2 row_shr:2 row_mask:0xf bank_mask:0xf bound_ctrl:1
	v_exp_f32_e32 v4, v56
	v_exp_f32_e64 v12, -v56
	v_add_f32_dpp v2, v2, v2 row_shr:4 row_mask:0xf bank_mask:0xf bound_ctrl:1
	v_lshl_add_u32 v56, v120, 2, v58
	s_nop 0
	v_add_f32_dpp v57, v2, v2 row_shr:8 row_mask:0xf bank_mask:0xf bound_ctrl:1
	v_sub_f32_e32 v10, v57, v13
	v_exp_f32_e32 v2, v54
	v_exp_f32_e32 v49, v10
	v_exp_f32_e64 v10, -v54
	v_pk_mul_f32 v[54:55], v[208:209], v[50:51] op_sel_hi:[0,1]
	v_pk_mul_f32 v[14:15], v[14:15], v[54:55] neg_lo:[0,1] neg_hi:[0,1]
	v_lshlrev_b32_e32 v50, 16, v191
	v_and_b32_e32 v51, 0xffff0000, v191
	v_cvt_pk_bf16_f32 v60, v14, v15
	v_pk_mul_f32 v[14:15], v[52:53], v[50:51]
	v_exp_f32_e32 v5, v57
	v_pk_mul_f32 v[62:63], v[208:209], v[14:15] op_sel_hi:[0,1]
	v_pk_mul_f32 v[14:15], v[48:49], v[62:63] neg_lo:[0,1] neg_hi:[0,1]
	v_exp_f32_e64 v13, -v57
	v_cvt_pk_bf16_f32 v61, v14, v15
	v_lshlrev_b32_e32 v14, 16, v188
	v_and_b32_e32 v15, 0xffff0000, v188
	v_pk_mul_f32 v[48:49], v[2:3], v[14:15]
	v_add_u32_e32 v57, v58, v125
	v_cvt_pk_bf16_f32 v52, v48, v49
	v_lshlrev_b32_e32 v48, 16, v189
	v_and_b32_e32 v49, 0xffff0000, v189
	v_pk_mul_f32 v[66:67], v[4:5], v[48:49]
	s_nop 0
	v_cvt_pk_bf16_f32 v53, v66, v67
	v_lshlrev_b32_e32 v66, 16, v194
	v_and_b32_e32 v67, 0xffff0000, v194
	ds_write2_b64 v57, v[60:61], v[52:53] offset1:16
	v_pk_mul_f32 v[52:53], v[54:55], v[66:67]
	v_pk_mul_f32 v[54:55], v[62:63], v[68:69]
	v_pk_mul_f32 v[60:61], v[10:11], v[52:53]
	v_pk_mul_f32 v[62:63], v[12:13], v[54:55]
	v_mov_b64_e32 v[210:211], v[60:61]
	v_mov_b64_e32 v[212:213], v[62:63]
	v_pk_add_f32 v[60:61], v[66:67], -1.0 op_sel_hi:[1,0]
	s_nop 0
	v_pk_fma_f32 v[6:7], v[60:61], v[6:7], 1.0 op_sel_hi:[1,1,0]
	v_pk_add_f32 v[60:61], v[68:69], -1.0 op_sel_hi:[1,0]
	v_pk_mul_f32 v[6:7], v[6:7], v[64:65]
	v_pk_fma_f32 v[8:9], v[60:61], v[8:9], 1.0 op_sel_hi:[1,1,0]
	s_nop 0
	v_pk_mul_f32 v[50:51], v[8:9], v[50:51]
	v_pk_mul_f32 v[8:9], v[10:11], v[6:7]
	v_pk_mul_f32 v[10:11], v[12:13], v[50:51]
	v_cvt_pk_bf16_f32 v214, v210, v8
	v_cvt_pk_bf16_f32 v215, v211, v9
	v_cvt_pk_bf16_f32 v216, v212, v10
	v_cvt_pk_bf16_f32 v217, v213, v11
	ds_write_b128 v56, v[214:217] offset:256
	v_lshlrev_b32_e32 v8, 16, v192
	v_and_b32_e32 v9, 0xffff0000, v192
	v_lshlrev_b32_e32 v10, 16, v193
	v_and_b32_e32 v11, 0xffff0000, v193
	ds_write_b128 v56, v[8:11] offset:768
	v_pk_mul_f32 v[8:9], v[52:53], v[14:15]
	v_pk_mul_f32 v[10:11], v[54:55], v[48:49]
	v_add_f32_e32 v8, v8, v9
	v_add_f32_e32 v8, v10, v8
	v_pk_mul_f32 v[6:7], v[6:7], v[14:15]
	v_add_f32_e32 v10, v11, v8
	v_pk_mul_f32 v[8:9], v[50:51], v[48:49]
	v_add_f32_e32 v6, v6, v7
	v_add_f32_e32 v6, v8, v6
	v_add_f32_e32 v8, v9, v6
	ds_bpermute_b32 v6, v0, v10
	ds_bpermute_b32 v9, v0, v8
	v_lshl_add_u32 v50, v121, 2, v58
	s_waitcnt lgkmcnt(1)
	v_add_f32_e32 v6, v10, v6
	s_waitcnt lgkmcnt(0)
	v_add_f32_e32 v8, v8, v9
	v_mov_b32_e32 v7, v6
	v_mov_b32_e32 v9, v8
	s_nop 0
	v_permlane32_swap_b32_e32 v6, v7
	v_permlane32_swap_b32_e32 v8, v9
	s_and_saveexec_b64 vcc, s[42:43]
	v_add_f32_e32 v8, v8, v9
	v_add_f32_e32 v6, v6, v7
	v_add_u32_e32 v7, 0x400, v50
	ds_write2_b32 v7, v6, v8 offset1:4
	s_or_b64 exec, exec, vcc
	v_lshl_add_u32 v51, v120, 2, s14
	s_and_saveexec_b64 vcc, s[44:45]
	ds_write_b128 v51, v[2:5] offset:16896
	s_or_b64 exec, exec, vcc
	v_mov_b64_e32 v[6:7], v[244:245]
	v_mov_b64_e32 v[8:9], v[246:247]
	v_mov_b64_e32 v[12:13], v[248:249]
	v_mov_b64_e32 v[14:15], v[250:251]
	v_cvt_f32_f16_e32 v10, v206
	v_cvt_f32_f16_sdwa v11, v206 dst_sel:DWORD dst_unused:UNUSED_PAD src0_sel:WORD_1
	v_cvt_f32_f16_e32 v48, v207
	v_cvt_f32_f16_sdwa v49, v207 dst_sel:DWORD dst_unused:UNUSED_PAD src0_sel:WORD_1
	v_add_f32_dpp v2, v10, v10 row_shr:1 row_mask:0xf bank_mask:0xf bound_ctrl:1
	v_lshlrev_b32_e32 v62, 16, v198
	v_and_b32_e32 v63, 0xffff0000, v198
	v_add_f32_dpp v2, v2, v2 row_shr:2 row_mask:0xf bank_mask:0xf bound_ctrl:1
	v_lshlrev_b32_e32 v64, 16, v199
	v_and_b32_e32 v65, 0xffff0000, v199
	v_add_f32_dpp v2, v2, v2 row_shr:4 row_mask:0xf bank_mask:0xf bound_ctrl:1
	v_add_u32_e32 v57, 0xc000, v57
	v_lshlrev_b32_e32 v68, 16, v205
	v_add_f32_dpp v52, v2, v2 row_shr:8 row_mask:0xf bank_mask:0xf bound_ctrl:1
	v_add_f32_dpp v2, v11, v11 row_shr:1 row_mask:0xf bank_mask:0xf bound_ctrl:1
	v_sub_f32_e32 v10, v52, v10
	v_exp_f32_e32 v10, v10
	v_add_f32_dpp v2, v2, v2 row_shr:2 row_mask:0xf bank_mask:0xf bound_ctrl:1
	v_exp_f32_e64 v58, -v52
	v_and_b32_e32 v69, 0xffff0000, v205
	v_add_f32_dpp v2, v2, v2 row_shr:4 row_mask:0xf bank_mask:0xf bound_ctrl:1
	s_nop 0
	v_pk_mul_f32 v[6:7], v[6:7], v[62:63]
	v_add_f32_dpp v53, v2, v2 row_shr:8 row_mask:0xf bank_mask:0xf bound_ctrl:1
	v_add_f32_dpp v2, v48, v48 row_shr:1 row_mask:0xf bank_mask:0xf bound_ctrl:1
	v_sub_f32_e32 v11, v53, v11
	v_exp_f32_e32 v11, v11
	v_add_f32_dpp v2, v2, v2 row_shr:2 row_mask:0xf bank_mask:0xf bound_ctrl:1
	v_exp_f32_e32 v3, v53
	v_exp_f32_e64 v59, -v53
	v_add_f32_dpp v2, v2, v2 row_shr:4 row_mask:0xf bank_mask:0xf bound_ctrl:1
	s_nop 1
	v_add_f32_dpp v54, v2, v2 row_shr:8 row_mask:0xf bank_mask:0xf bound_ctrl:1
	v_add_f32_dpp v2, v49, v49 row_shr:1 row_mask:0xf bank_mask:0xf bound_ctrl:1
	v_sub_f32_e32 v48, v54, v48
	v_exp_f32_e32 v48, v48
	v_add_f32_dpp v2, v2, v2 row_shr:2 row_mask:0xf bank_mask:0xf bound_ctrl:1
	v_exp_f32_e32 v4, v54
	v_exp_f32_e64 v60, -v54
	v_add_f32_dpp v2, v2, v2 row_shr:4 row_mask:0xf bank_mask:0xf bound_ctrl:1
	s_nop 1
	v_add_f32_dpp v55, v2, v2 row_shr:8 row_mask:0xf bank_mask:0xf bound_ctrl:1
	v_sub_f32_e32 v49, v55, v49
	v_exp_f32_e32 v2, v52
	v_exp_f32_e32 v49, v49
	v_pk_mul_f32 v[52:53], v[208:209], v[6:7] op_sel:[1,0]
	v_exp_f32_e32 v5, v55
	v_pk_mul_f32 v[6:7], v[10:11], v[52:53] neg_lo:[0,1] neg_hi:[0,1]
	v_exp_f32_e64 v61, -v55
	v_cvt_pk_bf16_f32 v10, v6, v7
	v_pk_mul_f32 v[6:7], v[8:9], v[64:65]
	s_nop 0
	v_pk_mul_f32 v[54:55], v[208:209], v[6:7] op_sel:[1,0]
	s_nop 0
	v_pk_mul_f32 v[6:7], v[48:49], v[54:55] neg_lo:[0,1] neg_hi:[0,1]
	s_nop 0
	v_cvt_pk_bf16_f32 v11, v6, v7
	v_lshlrev_b32_e32 v6, 16, v196
	v_and_b32_e32 v7, 0xffff0000, v196
	v_pk_mul_f32 v[8:9], v[2:3], v[6:7]
	s_nop 0
	v_cvt_pk_bf16_f32 v48, v8, v9
	v_lshlrev_b32_e32 v8, 16, v197
	v_and_b32_e32 v9, 0xffff0000, v197
	v_pk_mul_f32 v[66:67], v[4:5], v[8:9]
	s_nop 0
	v_cvt_pk_bf16_f32 v49, v66, v67
	v_lshlrev_b32_e32 v66, 16, v204
	v_and_b32_e32 v67, 0xffff0000, v204
	ds_write2_b64 v57, v[10:11], v[48:49] offset1:16
	v_pk_mul_f32 v[10:11], v[52:53], v[66:67]
	v_pk_mul_f32 v[48:49], v[54:55], v[68:69]
	v_pk_mul_f32 v[52:53], v[58:59], v[10:11]
	v_pk_mul_f32 v[54:55], v[60:61], v[48:49]
	v_mov_b64_e32 v[210:211], v[52:53]
	v_mov_b64_e32 v[212:213], v[54:55]
	v_pk_add_f32 v[52:53], v[66:67], -1.0 op_sel_hi:[1,0]
	v_pk_mul_f32 v[10:11], v[10:11], v[6:7]
	v_pk_fma_f32 v[12:13], v[52:53], v[12:13], 1.0 op_sel_hi:[1,1,0]
	v_pk_add_f32 v[52:53], v[68:69], -1.0 op_sel_hi:[1,0]
	v_pk_mul_f32 v[12:13], v[12:13], v[62:63]
	v_pk_fma_f32 v[14:15], v[52:53], v[14:15], 1.0 op_sel_hi:[1,1,0]
	v_pk_mul_f32 v[6:7], v[12:13], v[6:7]
	v_pk_mul_f32 v[14:15], v[14:15], v[64:65]
	v_pk_mul_f32 v[48:49], v[48:49], v[8:9]
	v_add_f32_e32 v10, v10, v11
	v_pk_mul_f32 v[8:9], v[14:15], v[8:9]
	v_add_f32_e32 v6, v6, v7
	v_add_f32_e32 v10, v48, v10
	v_add_f32_e32 v6, v8, v6
	v_add_f32_e32 v10, v49, v10
	v_add_f32_e32 v8, v9, v6
	ds_bpermute_b32 v6, v0, v10
	ds_bpermute_b32 v0, v0, v8
	v_pk_mul_f32 v[52:53], v[58:59], v[12:13]
	v_pk_mul_f32 v[54:55], v[60:61], v[14:15]
	v_cvt_pk_bf16_f32 v214, v210, v52
	v_cvt_pk_bf16_f32 v215, v211, v53
	v_cvt_pk_bf16_f32 v216, v212, v54
	v_cvt_pk_bf16_f32 v217, v213, v55
	ds_write_b128 v56, v[214:217] offset:49408
	s_waitcnt lgkmcnt(2)
	v_add_f32_e32 v6, v10, v6
	s_waitcnt lgkmcnt(1)
	v_add_f32_e32 v0, v8, v0
	v_mov_b32_e32 v7, v6
	v_mov_b32_e32 v8, v0
	v_lshlrev_b32_e32 v52, 16, v200
	v_and_b32_e32 v53, 0xffff0000, v200
	v_lshlrev_b32_e32 v54, 16, v201
	v_and_b32_e32 v55, 0xffff0000, v201
	v_permlane32_swap_b32_e32 v6, v7
	v_permlane32_swap_b32_e32 v0, v8
	ds_write_b128 v56, v[52:55] offset:49920
	s_and_saveexec_b64 vcc, s[42:43]
	v_add_f32_e32 v0, v0, v8
	v_add_f32_e32 v6, v6, v7
	v_add_u32_e32 v7, 0xc400, v50
	ds_write2_b32 v7, v6, v0 offset1:4
	s_or_b64 exec, exec, vcc
	s_and_saveexec_b64 vcc, s[44:45]
	v_add_u32_e32 v0, 0x10200, v51
	ds_write_b128 v0, v[2:5]
	s_or_b64 exec, exec, vcc

; DI unsigned cvtpk_n(float lo, float hi) { f32x2 v = {lo, hi}; bf16x2n b = __builtin_convertvector(v, bf16x2n); return __builtin_bit_cast(unsigned, b); }
; DI void scan_ld(ScanStep& t, const float* rec, const char* zimg, int fragoff, bool isaq, int h, int m, int vrow) {
;     const char* fp = isaq ? (const char*)(rec + fragoff) + h * 16 : zimg + h * 16;
; #pragma unroll
;     for (int q = 0; q < 4; ++q) t.f[q] = *(const bf16x8*)(fp + q * 32);
; DI void phase_scan(const bf16_t* R, const bf16_t* Kk, const bf16_t* V, const __half* DEC, const bf16_t* AA, const float* INV, const float* kkp, const float* kap,
;                    bf16_t* MIX, bf16_t* YB, char* lds) {
;     ...
;                 const float* cur = bufA + cgrp * 12288 + (c & 1) * 6144; float* yb = ybufA + cgrp * 2048 + (c & 1) * 1024;
;                 ScanStep t; scan_ld(t, cur, zimg, fragoff, isaq, h, m, vrow);
; #pragma unroll 2
;                 for (int st = 0; st < 16; ++st) {
;                     f32x16 d0 = __builtin_amdgcn_mfma_f32_32x32x16_bf16(t.f[0], pack_acc(acc0, 0), zero16, 0, 0, 0);
;                     d0 = __builtin_amdgcn_mfma_f32_32x32x16_bf16(t.f[1], pack_acc(acc0, 1), d0, 0, 0, 0);
;                     d0 = __builtin_amdgcn_mfma_f32_32x32x16_bf16(t.f[2], pack_acc(acc1, 0), d0, 0, 0, 0);
;                     d0 = __builtin_amdgcn_mfma_f32_32x32x16_bf16(t.f[3], pack_acc(acc1, 1), d0, 0, 0, 0);
;                     __builtin_amdgcn_sched_barrier(0);
;                     ScanStep n; scan_ld(n, cur + (st + 1) * SREC, zimg, fragoff, isaq, h, m, vrow);
;                     __builtin_amdgcn_sched_barrier(0);
;                     const float sa = d0[0], z = d0[1];
;                     yb[st * 64 + vrow] = z + sa * ((t.brp[0] + t.brp[1]) + (t.brp[2] + t.brp[3])) + t.v * ((t.krp[0] + t.krp[1]) + (t.krp[2] + t.krp[3]));
;                     const unsigned hz = h ? 0u : 0xffffffffu;
;                     const u32x4 ua0 = {cvtpk_n(t.b0, t.k0) & hz, 0u, 0u, 0u}, ua1 = {cvtpk_n(t.b1, t.k1) & hz, 0u, 0u, 0u}, ub = {cvtpk_n(sa, t.v) & hz, 0u, 0u, 0u};
;                     acc0 = __builtin_amdgcn_mfma_f32_32x32x16_bf16(__builtin_bit_cast(bf16x8, ua0), __builtin_bit_cast(bf16x8, ub), acc0, 0, 0, 0);
;                     acc1 = __builtin_amdgcn_mfma_f32_32x32x16_bf16(__builtin_bit_cast(bf16x8, ua1), __builtin_bit_cast(bf16x8, ub), acc1, 0, 0, 0);
;                     t = n;
.LBB0_2301:
	s_andn2_saveexec_b64 s[20:21], s[20:21]
	s_cbranch_execz .LBB0_2281
	s_and_b32 s14, s12, 1
	s_mulk_i32 s14, 0x6000
	v_cndmask_b32_e64 v0, 0, 1, s[88:89]
	v_add_u32_e32 v170, s14, v132
	v_mul_lo_u32 v2, v0, s73
	v_lshl_add_u32 v169, v0, 12, v164
	v_add_u32_e32 v191, 0x18000, v169
	v_add_u32_e32 v168, v163, v2
	v_cndmask_b32_e64 v188, v134, v168, s[40:41]
	v_lshl_add_u32 v189, v122, 2, v170
	v_add_u32_e32 v189, 0x100, v189
	v_mov_b32_e32 v0, s24
	v_bfi_b32 v189, v135, v189, v0
	v_lshl_add_u32 v190, v123, 2, v170
	v_add_u32_e32 v190, 0x300, v190
	v_mov_b32_e32 v81, 0
	v_mov_b32_e32 v82, 0
	v_mov_b32_e32 v83, 0
	v_mov_b32_e32 v85, 0
	v_mov_b32_e32 v86, 0
	v_mov_b32_e32 v87, 0
	s_mov_b64 exec, s[40:41]
	ds_read_b128 v[64:67], v188
	ds_read_b128 v[68:71], v188 offset:32
	ds_read_b128 v[72:75], v188 offset:64
	ds_read_b128 v[76:79], v188 offset:96
	s_mov_b64 exec, -1
	ds_read_b32 v224, v189
	ds_read_b32 v228, v189 offset:128
	ds_read_b32 v108, v190
	ds_read_b128 v[4:7], v170 offset:1024
	ds_read_b128 v[8:11], v170 offset:1040
	s_waitcnt lgkmcnt(0)
	s_waitcnt lgkmcnt(1)
	s_mov_b64 exec, s[40:41]
	ds_read_b128 v[192:195], v188 offset:1056
	ds_read_b128 v[196:199], v188 offset:1088
	ds_read_b128 v[200:203], v188 offset:1120
	ds_read_b128 v[204:207], v188 offset:1152
	s_mov_b64 exec, -1
	ds_read_b32 v80, v189 offset:1056
	ds_read_b32 v84, v189 offset:1184
	ds_read_b32 v114, v190 offset:1056
	v_cvt_pk_bf16_f32 v216, v16, v17
	v_cvt_pk_bf16_f32 v217, v18, v19
	v_cvt_pk_bf16_f32 v218, v20, v21
	v_cvt_pk_bf16_f32 v219, v22, v23
	ds_read_b128 v[208:211], v170 offset:2080
	ds_read_b128 v[212:215], v170 offset:2096
	v_mfma_f32_32x32x16_bf16 v[48:63], v[64:67], v[216:219], 0
	v_cvt_pk_bf16_f32 v220, v24, v25
	v_cvt_pk_bf16_f32 v221, v26, v27
	v_cvt_pk_bf16_f32 v222, v28, v29
	v_cvt_pk_bf16_f32 v223, v30, v31
	v_add_f32_e32 v2, v4, v5
	v_add_f32_e32 v3, v8, v9
	v_mfma_f32_32x32x16_bf16 v[48:63], v[68:71], v[220:223], v[48:63]
	v_cvt_pk_bf16_f32 v216, v32, v33
	v_cvt_pk_bf16_f32 v217, v34, v35
	v_cvt_pk_bf16_f32 v218, v36, v37
	v_cvt_pk_bf16_f32 v219, v38, v39
	v_add_f32_e32 v0, v6, v7
	v_add_f32_e32 v14, v10, v11
	v_mfma_f32_32x32x16_bf16 v[48:63], v[72:75], v[216:219], v[48:63]
	v_cvt_pk_bf16_f32 v220, v40, v41
	v_cvt_pk_bf16_f32 v221, v42, v43
	v_cvt_pk_bf16_f32 v222, v44, v45
	v_cvt_pk_bf16_f32 v223, v46, v47
	v_add_f32_e32 v2, v2, v0
	v_add_f32_e32 v3, v3, v14
	v_mfma_f32_32x32x16_bf16 v[48:63], v[76:79], v[220:223], v[48:63]
	s_nop 11
	v_cvt_pk_bf16_f32 v232, v48, v108
	v_fma_f32 v13, v48, v2, v49
	v_fma_f32 v13, v108, v3, v13
	v_mfma_f32_32x32x16_bf16 v[16:31], v[224:227], v[232:235], v[16:31]
	v_mfma_f32_32x32x16_bf16 v[32:47], v[228:231], v[232:235], v[32:47]
	ds_write_b32 v191, v13 offset:0
	s_waitcnt lgkmcnt(1)
	s_mov_b64 exec, s[40:41]
	ds_read_b128 v[64:67], v188 offset:2112
	ds_read_b128 v[68:71], v188 offset:2144
	ds_read_b128 v[72:75], v188 offset:2176
	ds_read_b128 v[76:79], v188 offset:2208
	s_mov_b64 exec, -1
	ds_read_b32 v224, v189 offset:2112
	ds_read_b32 v228, v189 offset:2240
	ds_read_b32 v108, v190 offset:2112
	v_cvt_pk_bf16_f32 v216, v16, v17
	v_cvt_pk_bf16_f32 v217, v18, v19
	v_cvt_pk_bf16_f32 v218, v20, v21
	v_cvt_pk_bf16_f32 v219, v22, v23
	ds_read_b128 v[4:7], v170 offset:3136
	ds_read_b128 v[8:11], v170 offset:3152
	v_mfma_f32_32x32x16_bf16 v[48:63], v[192:195], v[216:219], 0
	v_cvt_pk_bf16_f32 v220, v24, v25
	v_cvt_pk_bf16_f32 v221, v26, v27
	v_cvt_pk_bf16_f32 v222, v28, v29
	v_cvt_pk_bf16_f32 v223, v30, v31
	v_add_f32_e32 v2, v208, v209
	v_add_f32_e32 v3, v212, v213
	v_mfma_f32_32x32x16_bf16 v[48:63], v[196:199], v[220:223], v[48:63]
	v_cvt_pk_bf16_f32 v216, v32, v33
	v_cvt_pk_bf16_f32 v217, v34, v35
	v_cvt_pk_bf16_f32 v218, v36, v37
	v_cvt_pk_bf16_f32 v219, v38, v39
	v_add_f32_e32 v0, v210, v211
	v_add_f32_e32 v14, v214, v215
	v_mfma_f32_32x32x16_bf16 v[48:63], v[200:203], v[216:219], v[48:63]
	v_cvt_pk_bf16_f32 v220, v40, v41
	v_cvt_pk_bf16_f32 v221, v42, v43
	v_cvt_pk_bf16_f32 v222, v44, v45
	v_cvt_pk_bf16_f32 v223, v46, v47
	v_add_f32_e32 v2, v2, v0
	v_add_f32_e32 v3, v3, v14
	v_mfma_f32_32x32x16_bf16 v[48:63], v[204:207], v[220:223], v[48:63]
	s_nop 11
	v_cvt_pk_bf16_f32 v232, v48, v114
	v_fma_f32 v13, v48, v2, v49
	v_fma_f32 v13, v114, v3, v13
	v_mfma_f32_32x32x16_bf16 v[16:31], v[80:83], v[232:235], v[16:31]
	v_mfma_f32_32x32x16_bf16 v[32:47], v[84:87], v[232:235], v[32:47]
	ds_write_b32 v191, v13 offset:256
	s_waitcnt lgkmcnt(1)
	s_mov_b64 exec, s[40:41]
	ds_read_b128 v[192:195], v188 offset:3168
	ds_read_b128 v[196:199], v188 offset:3200
	ds_read_b128 v[200:203], v188 offset:3232
	ds_read_b128 v[204:207], v188 offset:3264
	s_mov_b64 exec, -1
	ds_read_b32 v80, v189 offset:3168
	ds_read_b32 v84, v189 offset:3296
	ds_read_b32 v114, v190 offset:3168
	v_cvt_pk_bf16_f32 v216, v16, v17
	v_cvt_pk_bf16_f32 v217, v18, v19
	v_cvt_pk_bf16_f32 v218, v20, v21
	v_cvt_pk_bf16_f32 v219, v22, v23
	ds_read_b128 v[208:211], v170 offset:4192
	ds_read_b128 v[212:215], v170 offset:4208
	v_mfma_f32_32x32x16_bf16 v[48:63], v[64:67], v[216:219], 0
	v_cvt_pk_bf16_f32 v220, v24, v25
	v_cvt_pk_bf16_f32 v221, v26, v27
	v_cvt_pk_bf16_f32 v222, v28, v29
	v_cvt_pk_bf16_f32 v223, v30, v31
	v_add_f32_e32 v2, v4, v5
	v_add_f32_e32 v3, v8, v9
	v_mfma_f32_32x32x16_bf16 v[48:63], v[68:71], v[220:223], v[48:63]
	v_cvt_pk_bf16_f32 v216, v32, v33
	v_cvt_pk_bf16_f32 v217, v34, v35
	v_cvt_pk_bf16_f32 v218, v36, v37
	v_cvt_pk_bf16_f32 v219, v38, v39
	v_add_f32_e32 v0, v6, v7
	v_add_f32_e32 v14, v10, v11
	v_mfma_f32_32x32x16_bf16 v[48:63], v[72:75], v[216:219], v[48:63]
	v_cvt_pk_bf16_f32 v220, v40, v41
	v_cvt_pk_bf16_f32 v221, v42, v43
	v_cvt_pk_bf16_f32 v222, v44, v45
	v_cvt_pk_bf16_f32 v223, v46, v47
	v_add_f32_e32 v2, v2, v0
	v_add_f32_e32 v3, v3, v14
	v_mfma_f32_32x32x16_bf16 v[48:63], v[76:79], v[220:223], v[48:63]
	s_nop 11
	v_cvt_pk_bf16_f32 v232, v48, v108
	v_fma_f32 v13, v48, v2, v49
	v_fma_f32 v13, v108, v3, v13
	v_mfma_f32_32x32x16_bf16 v[16:31], v[224:227], v[232:235], v[16:31]
	v_mfma_f32_32x32x16_bf16 v[32:47], v[228:231], v[232:235], v[32:47]
	ds_write_b32 v191, v13 offset:512
	s_waitcnt lgkmcnt(1)
; DI unsigned cvtpk_n(float lo, float hi) { f32x2 v = {lo, hi}; bf16x2n b = __builtin_convertvector(v, bf16x2n); return __builtin_bit_cast(unsigned, b); }
; DI void scan_ld(ScanStep& t, const float* rec, const char* zimg, int fragoff, bool isaq, int h, int m, int vrow) {
;     const char* fp = isaq ? (const char*)(rec + fragoff) + h * 16 : zimg + h * 16;
; #pragma unroll
;     for (int q = 0; q < 4; ++q) t.f[q] = *(const bf16x8*)(fp + q * 32);
;     t.b0 = rec[64 + m]; t.k0 = rec[128 + m]; t.b1 = rec[96 + m]; t.k1 = rec[160 + m]; t.v = rec[192 + vrow]; t.brp = *(const f32x4*)(rec + 256); t.krp = *(const f32x4*)(rec + 260);
; }
; DI void phase_scan(const bf16_t* R, const bf16_t* Kk, const bf16_t* V, const __half* DEC, const bf16_t* AA, const float* INV, const float* kkp, const float* kap,
;                    bf16_t* MIX, bf16_t* YB, char* lds) {
;     ...
;                 for (int st = 0; st < 16; ++st) {
;                     f32x16 d0 = __builtin_amdgcn_mfma_f32_32x32x16_bf16(t.f[0], pack_acc(acc0, 0), zero16, 0, 0, 0);
;                     d0 = __builtin_amdgcn_mfma_f32_32x32x16_bf16(t.f[1], pack_acc(acc0, 1), d0, 0, 0, 0);
;                     d0 = __builtin_amdgcn_mfma_f32_32x32x16_bf16(t.f[2], pack_acc(acc1, 0), d0, 0, 0, 0);
;                     d0 = __builtin_amdgcn_mfma_f32_32x32x16_bf16(t.f[3], pack_acc(acc1, 1), d0, 0, 0, 0);
;                     __builtin_amdgcn_sched_barrier(0);
;                     ScanStep n; scan_ld(n, cur + (st + 1) * SREC, zimg, fragoff, isaq, h, m, vrow);
;                     __builtin_amdgcn_sched_barrier(0);
;                     const float sa = d0[0], z = d0[1];
;                     yb[st * 64 + vrow] = z + sa * ((t.brp[0] + t.brp[1]) + (t.brp[2] + t.brp[3])) + t.v * ((t.krp[0] + t.krp[1]) + (t.krp[2] + t.krp[3]));
;                     const unsigned hz = h ? 0u : 0xffffffffu;
;                     const u32x4 ua0 = {cvtpk_n(t.b0, t.k0) & hz, 0u, 0u, 0u}, ua1 = {cvtpk_n(t.b1, t.k1) & hz, 0u, 0u, 0u}, ub = {cvtpk_n(sa, t.v) & hz, 0u, 0u, 0u};
;                     acc0 = __builtin_amdgcn_mfma_f32_32x32x16_bf16(__builtin_bit_cast(bf16x8, ua0), __builtin_bit_cast(bf16x8, ub), acc0, 0, 0, 0);
;                     acc1 = __builtin_amdgcn_mfma_f32_32x32x16_bf16(__builtin_bit_cast(bf16x8, ua1), __builtin_bit_cast(bf16x8, ub), acc1, 0, 0, 0);
;                     t = n;
	s_mov_b64 exec, s[40:41]
	ds_read_b128 v[64:67], v188 offset:4224
	ds_read_b128 v[68:71], v188 offset:4256
	ds_read_b128 v[72:75], v188 offset:4288
	ds_read_b128 v[76:79], v188 offset:4320
	s_mov_b64 exec, -1
	ds_read_b32 v224, v189 offset:4224
	ds_read_b32 v228, v189 offset:4352
	ds_read_b32 v108, v190 offset:4224
	v_cvt_pk_bf16_f32 v216, v16, v17
	v_cvt_pk_bf16_f32 v217, v18, v19
	v_cvt_pk_bf16_f32 v218, v20, v21
	v_cvt_pk_bf16_f32 v219, v22, v23
	ds_read_b128 v[4:7], v170 offset:5248
	ds_read_b128 v[8:11], v170 offset:5264
	v_mfma_f32_32x32x16_bf16 v[48:63], v[192:195], v[216:219], 0
	v_cvt_pk_bf16_f32 v220, v24, v25
	v_cvt_pk_bf16_f32 v221, v26, v27
	v_cvt_pk_bf16_f32 v222, v28, v29
	v_cvt_pk_bf16_f32 v223, v30, v31
	v_add_f32_e32 v2, v208, v209
	v_add_f32_e32 v3, v212, v213
	v_mfma_f32_32x32x16_bf16 v[48:63], v[196:199], v[220:223], v[48:63]
	v_cvt_pk_bf16_f32 v216, v32, v33
	v_cvt_pk_bf16_f32 v217, v34, v35
	v_cvt_pk_bf16_f32 v218, v36, v37
	v_cvt_pk_bf16_f32 v219, v38, v39
	v_add_f32_e32 v0, v210, v211
	v_add_f32_e32 v14, v214, v215
	v_mfma_f32_32x32x16_bf16 v[48:63], v[200:203], v[216:219], v[48:63]
	v_cvt_pk_bf16_f32 v220, v40, v41
	v_cvt_pk_bf16_f32 v221, v42, v43
	v_cvt_pk_bf16_f32 v222, v44, v45
	v_cvt_pk_bf16_f32 v223, v46, v47
	v_add_f32_e32 v2, v2, v0
	v_add_f32_e32 v3, v3, v14
	v_mfma_f32_32x32x16_bf16 v[48:63], v[204:207], v[220:223], v[48:63]
	s_nop 11
	v_cvt_pk_bf16_f32 v232, v48, v114
	v_fma_f32 v13, v48, v2, v49
	v_fma_f32 v13, v114, v3, v13
	v_mfma_f32_32x32x16_bf16 v[16:31], v[80:83], v[232:235], v[16:31]
	v_mfma_f32_32x32x16_bf16 v[32:47], v[84:87], v[232:235], v[32:47]
	ds_write_b32 v191, v13 offset:768
	s_waitcnt lgkmcnt(1)
	s_mov_b64 exec, s[40:41]
	ds_read_b128 v[192:195], v188 offset:5280
	ds_read_b128 v[196:199], v188 offset:5312
	ds_read_b128 v[200:203], v188 offset:5344
	ds_read_b128 v[204:207], v188 offset:5376
	s_mov_b64 exec, -1
	ds_read_b32 v80, v189 offset:5280
	ds_read_b32 v84, v189 offset:5408
	ds_read_b32 v114, v190 offset:5280
	v_cvt_pk_bf16_f32 v216, v16, v17
	v_cvt_pk_bf16_f32 v217, v18, v19
	v_cvt_pk_bf16_f32 v218, v20, v21
	v_cvt_pk_bf16_f32 v219, v22, v23
	ds_read_b128 v[208:211], v170 offset:6304
	ds_read_b128 v[212:215], v170 offset:6320
	v_mfma_f32_32x32x16_bf16 v[48:63], v[64:67], v[216:219], 0
	v_cvt_pk_bf16_f32 v220, v24, v25
	v_cvt_pk_bf16_f32 v221, v26, v27
	v_cvt_pk_bf16_f32 v222, v28, v29
	v_cvt_pk_bf16_f32 v223, v30, v31
	v_add_f32_e32 v2, v4, v5
	v_add_f32_e32 v3, v8, v9
	v_mfma_f32_32x32x16_bf16 v[48:63], v[68:71], v[220:223], v[48:63]
	v_cvt_pk_bf16_f32 v216, v32, v33
	v_cvt_pk_bf16_f32 v217, v34, v35
	v_cvt_pk_bf16_f32 v218, v36, v37
	v_cvt_pk_bf16_f32 v219, v38, v39
	v_add_f32_e32 v0, v6, v7
	v_add_f32_e32 v14, v10, v11
	v_mfma_f32_32x32x16_bf16 v[48:63], v[72:75], v[216:219], v[48:63]
	v_cvt_pk_bf16_f32 v220, v40, v41
	v_cvt_pk_bf16_f32 v221, v42, v43
	v_cvt_pk_bf16_f32 v222, v44, v45
	v_cvt_pk_bf16_f32 v223, v46, v47
	v_add_f32_e32 v2, v2, v0
	v_add_f32_e32 v3, v3, v14
	v_mfma_f32_32x32x16_bf16 v[48:63], v[76:79], v[220:223], v[48:63]
	s_nop 11
	v_cvt_pk_bf16_f32 v232, v48, v108
	v_fma_f32 v13, v48, v2, v49
	v_fma_f32 v13, v108, v3, v13
	v_mfma_f32_32x32x16_bf16 v[16:31], v[224:227], v[232:235], v[16:31]
	v_mfma_f32_32x32x16_bf16 v[32:47], v[228:231], v[232:235], v[32:47]
	ds_write_b32 v191, v13 offset:1024
	s_waitcnt lgkmcnt(1)
	s_mov_b64 exec, s[40:41]
	ds_read_b128 v[64:67], v188 offset:6336
	ds_read_b128 v[68:71], v188 offset:6368
	ds_read_b128 v[72:75], v188 offset:6400
	ds_read_b128 v[76:79], v188 offset:6432
	s_mov_b64 exec, -1
	ds_read_b32 v224, v189 offset:6336
	ds_read_b32 v228, v189 offset:6464
	ds_read_b32 v108, v190 offset:6336
	v_cvt_pk_bf16_f32 v216, v16, v17
	v_cvt_pk_bf16_f32 v217, v18, v19
	v_cvt_pk_bf16_f32 v218, v20, v21
	v_cvt_pk_bf16_f32 v219, v22, v23
	ds_read_b128 v[4:7], v170 offset:7360
	ds_read_b128 v[8:11], v170 offset:7376
	v_mfma_f32_32x32x16_bf16 v[48:63], v[192:195], v[216:219], 0
	v_cvt_pk_bf16_f32 v220, v24, v25
	v_cvt_pk_bf16_f32 v221, v26, v27
	v_cvt_pk_bf16_f32 v222, v28, v29
	v_cvt_pk_bf16_f32 v223, v30, v31
	v_add_f32_e32 v2, v208, v209
	v_add_f32_e32 v3, v212, v213
	v_mfma_f32_32x32x16_bf16 v[48:63], v[196:199], v[220:223], v[48:63]
	v_cvt_pk_bf16_f32 v216, v32, v33
	v_cvt_pk_bf16_f32 v217, v34, v35
	v_cvt_pk_bf16_f32 v218, v36, v37
	v_cvt_pk_bf16_f32 v219, v38, v39
	v_add_f32_e32 v0, v210, v211
	v_add_f32_e32 v14, v214, v215
	v_mfma_f32_32x32x16_bf16 v[48:63], v[200:203], v[216:219], v[48:63]
	v_cvt_pk_bf16_f32 v220, v40, v41
	v_cvt_pk_bf16_f32 v221, v42, v43
	v_cvt_pk_bf16_f32 v222, v44, v45
	v_cvt_pk_bf16_f32 v223, v46, v47
	v_add_f32_e32 v2, v2, v0
	v_add_f32_e32 v3, v3, v14
	v_mfma_f32_32x32x16_bf16 v[48:63], v[204:207], v[220:223], v[48:63]
	s_nop 11
	v_cvt_pk_bf16_f32 v232, v48, v114
	v_fma_f32 v13, v48, v2, v49
	v_fma_f32 v13, v114, v3, v13
	v_mfma_f32_32x32x16_bf16 v[16:31], v[80:83], v[232:235], v[16:31]
	v_mfma_f32_32x32x16_bf16 v[32:47], v[84:87], v[232:235], v[32:47]
	ds_write_b32 v191, v13 offset:1280
	s_waitcnt lgkmcnt(1)
; DI unsigned cvtpk_n(float lo, float hi) { f32x2 v = {lo, hi}; bf16x2n b = __builtin_convertvector(v, bf16x2n); return __builtin_bit_cast(unsigned, b); }
; DI void scan_ld(ScanStep& t, const float* rec, const char* zimg, int fragoff, bool isaq, int h, int m, int vrow) {
;     const char* fp = isaq ? (const char*)(rec + fragoff) + h * 16 : zimg + h * 16;
; #pragma unroll
;     for (int q = 0; q < 4; ++q) t.f[q] = *(const bf16x8*)(fp + q * 32);
;     t.b0 = rec[64 + m]; t.k0 = rec[128 + m]; t.b1 = rec[96 + m]; t.k1 = rec[160 + m]; t.v = rec[192 + vrow]; t.brp = *(const f32x4*)(rec + 256); t.krp = *(const f32x4*)(rec + 260);
; }
; DI void phase_scan(const bf16_t* R, const bf16_t* Kk, const bf16_t* V, const __half* DEC, const bf16_t* AA, const float* INV, const float* kkp, const float* kap,
;                    bf16_t* MIX, bf16_t* YB, char* lds) {
;     ...
;                 for (int st = 0; st < 16; ++st) {
;                     f32x16 d0 = __builtin_amdgcn_mfma_f32_32x32x16_bf16(t.f[0], pack_acc(acc0, 0), zero16, 0, 0, 0);
;                     d0 = __builtin_amdgcn_mfma_f32_32x32x16_bf16(t.f[1], pack_acc(acc0, 1), d0, 0, 0, 0);
;                     d0 = __builtin_amdgcn_mfma_f32_32x32x16_bf16(t.f[2], pack_acc(acc1, 0), d0, 0, 0, 0);
;                     d0 = __builtin_amdgcn_mfma_f32_32x32x16_bf16(t.f[3], pack_acc(acc1, 1), d0, 0, 0, 0);
;                     __builtin_amdgcn_sched_barrier(0);
;                     ScanStep n; scan_ld(n, cur + (st + 1) * SREC, zimg, fragoff, isaq, h, m, vrow);
;                     __builtin_amdgcn_sched_barrier(0);
;                     const float sa = d0[0], z = d0[1];
;                     yb[st * 64 + vrow] = z + sa * ((t.brp[0] + t.brp[1]) + (t.brp[2] + t.brp[3])) + t.v * ((t.krp[0] + t.krp[1]) + (t.krp[2] + t.krp[3]));
;                     const unsigned hz = h ? 0u : 0xffffffffu;
;                     const u32x4 ua0 = {cvtpk_n(t.b0, t.k0) & hz, 0u, 0u, 0u}, ua1 = {cvtpk_n(t.b1, t.k1) & hz, 0u, 0u, 0u}, ub = {cvtpk_n(sa, t.v) & hz, 0u, 0u, 0u};
;                     acc0 = __builtin_amdgcn_mfma_f32_32x32x16_bf16(__builtin_bit_cast(bf16x8, ua0), __builtin_bit_cast(bf16x8, ub), acc0, 0, 0, 0);
;                     acc1 = __builtin_amdgcn_mfma_f32_32x32x16_bf16(__builtin_bit_cast(bf16x8, ua1), __builtin_bit_cast(bf16x8, ub), acc1, 0, 0, 0);
;                     t = n;
	s_mov_b64 exec, s[40:41]
	ds_read_b128 v[192:195], v188 offset:7392
	ds_read_b128 v[196:199], v188 offset:7424
	ds_read_b128 v[200:203], v188 offset:7456
	ds_read_b128 v[204:207], v188 offset:7488
	s_mov_b64 exec, -1
	ds_read_b32 v80, v189 offset:7392
	ds_read_b32 v84, v189 offset:7520
	ds_read_b32 v114, v190 offset:7392
	v_cvt_pk_bf16_f32 v216, v16, v17
	v_cvt_pk_bf16_f32 v217, v18, v19
	v_cvt_pk_bf16_f32 v218, v20, v21
	v_cvt_pk_bf16_f32 v219, v22, v23
	ds_read_b128 v[208:211], v170 offset:8416
	ds_read_b128 v[212:215], v170 offset:8432
	v_mfma_f32_32x32x16_bf16 v[48:63], v[64:67], v[216:219], 0
	v_cvt_pk_bf16_f32 v220, v24, v25
	v_cvt_pk_bf16_f32 v221, v26, v27
	v_cvt_pk_bf16_f32 v222, v28, v29
	v_cvt_pk_bf16_f32 v223, v30, v31
	v_add_f32_e32 v2, v4, v5
	v_add_f32_e32 v3, v8, v9
	v_mfma_f32_32x32x16_bf16 v[48:63], v[68:71], v[220:223], v[48:63]
	v_cvt_pk_bf16_f32 v216, v32, v33
	v_cvt_pk_bf16_f32 v217, v34, v35
	v_cvt_pk_bf16_f32 v218, v36, v37
	v_cvt_pk_bf16_f32 v219, v38, v39
	v_add_f32_e32 v0, v6, v7
	v_add_f32_e32 v14, v10, v11
	v_mfma_f32_32x32x16_bf16 v[48:63], v[72:75], v[216:219], v[48:63]
	v_cvt_pk_bf16_f32 v220, v40, v41
	v_cvt_pk_bf16_f32 v221, v42, v43
	v_cvt_pk_bf16_f32 v222, v44, v45
	v_cvt_pk_bf16_f32 v223, v46, v47
	v_add_f32_e32 v2, v2, v0
	v_add_f32_e32 v3, v3, v14
	v_mfma_f32_32x32x16_bf16 v[48:63], v[76:79], v[220:223], v[48:63]
	s_nop 11
	v_cvt_pk_bf16_f32 v232, v48, v108
	v_fma_f32 v13, v48, v2, v49
	v_fma_f32 v13, v108, v3, v13
	v_mfma_f32_32x32x16_bf16 v[16:31], v[224:227], v[232:235], v[16:31]
	v_mfma_f32_32x32x16_bf16 v[32:47], v[228:231], v[232:235], v[32:47]
	ds_write_b32 v191, v13 offset:1536
	s_waitcnt lgkmcnt(1)
	s_mov_b64 exec, s[40:41]
	ds_read_b128 v[64:67], v188 offset:8448
	ds_read_b128 v[68:71], v188 offset:8480
	ds_read_b128 v[72:75], v188 offset:8512
	ds_read_b128 v[76:79], v188 offset:8544
	s_mov_b64 exec, -1
	ds_read_b32 v224, v189 offset:8448
	ds_read_b32 v228, v189 offset:8576
	ds_read_b32 v108, v190 offset:8448
	v_cvt_pk_bf16_f32 v216, v16, v17
	v_cvt_pk_bf16_f32 v217, v18, v19
	v_cvt_pk_bf16_f32 v218, v20, v21
	v_cvt_pk_bf16_f32 v219, v22, v23
	ds_read_b128 v[4:7], v170 offset:9472
	ds_read_b128 v[8:11], v170 offset:9488
	v_mfma_f32_32x32x16_bf16 v[48:63], v[192:195], v[216:219], 0
	v_cvt_pk_bf16_f32 v220, v24, v25
	v_cvt_pk_bf16_f32 v221, v26, v27
	v_cvt_pk_bf16_f32 v222, v28, v29
	v_cvt_pk_bf16_f32 v223, v30, v31
	v_add_f32_e32 v2, v208, v209
	v_add_f32_e32 v3, v212, v213
	v_mfma_f32_32x32x16_bf16 v[48:63], v[196:199], v[220:223], v[48:63]
	v_cvt_pk_bf16_f32 v216, v32, v33
	v_cvt_pk_bf16_f32 v217, v34, v35
	v_cvt_pk_bf16_f32 v218, v36, v37
	v_cvt_pk_bf16_f32 v219, v38, v39
	v_add_f32_e32 v0, v210, v211
	v_add_f32_e32 v14, v214, v215
	v_mfma_f32_32x32x16_bf16 v[48:63], v[200:203], v[216:219], v[48:63]
	v_cvt_pk_bf16_f32 v220, v40, v41
	v_cvt_pk_bf16_f32 v221, v42, v43
	v_cvt_pk_bf16_f32 v222, v44, v45
	v_cvt_pk_bf16_f32 v223, v46, v47
	v_add_f32_e32 v2, v2, v0
	v_add_f32_e32 v3, v3, v14
	v_mfma_f32_32x32x16_bf16 v[48:63], v[204:207], v[220:223], v[48:63]
	s_nop 11
	v_cvt_pk_bf16_f32 v232, v48, v114
	v_fma_f32 v13, v48, v2, v49
	v_fma_f32 v13, v114, v3, v13
	v_mfma_f32_32x32x16_bf16 v[16:31], v[80:83], v[232:235], v[16:31]
	v_mfma_f32_32x32x16_bf16 v[32:47], v[84:87], v[232:235], v[32:47]
	ds_write_b32 v191, v13 offset:1792
	s_waitcnt lgkmcnt(1)
	s_mov_b64 exec, s[40:41]
	ds_read_b128 v[192:195], v188 offset:9504
	ds_read_b128 v[196:199], v188 offset:9536
	ds_read_b128 v[200:203], v188 offset:9568
	ds_read_b128 v[204:207], v188 offset:9600
	s_mov_b64 exec, -1
	ds_read_b32 v80, v189 offset:9504
	ds_read_b32 v84, v189 offset:9632
	ds_read_b32 v114, v190 offset:9504
	v_cvt_pk_bf16_f32 v216, v16, v17
	v_cvt_pk_bf16_f32 v217, v18, v19
	v_cvt_pk_bf16_f32 v218, v20, v21
	v_cvt_pk_bf16_f32 v219, v22, v23
	ds_read_b128 v[208:211], v170 offset:10528
	ds_read_b128 v[212:215], v170 offset:10544
	v_mfma_f32_32x32x16_bf16 v[48:63], v[64:67], v[216:219], 0
	v_cvt_pk_bf16_f32 v220, v24, v25
	v_cvt_pk_bf16_f32 v221, v26, v27
	v_cvt_pk_bf16_f32 v222, v28, v29
	v_cvt_pk_bf16_f32 v223, v30, v31
	v_add_f32_e32 v2, v4, v5
	v_add_f32_e32 v3, v8, v9
	v_mfma_f32_32x32x16_bf16 v[48:63], v[68:71], v[220:223], v[48:63]
	v_cvt_pk_bf16_f32 v216, v32, v33
	v_cvt_pk_bf16_f32 v217, v34, v35
	v_cvt_pk_bf16_f32 v218, v36, v37
	v_cvt_pk_bf16_f32 v219, v38, v39
	v_add_f32_e32 v0, v6, v7
	v_add_f32_e32 v14, v10, v11
	v_mfma_f32_32x32x16_bf16 v[48:63], v[72:75], v[216:219], v[48:63]
	v_cvt_pk_bf16_f32 v220, v40, v41
	v_cvt_pk_bf16_f32 v221, v42, v43
	v_cvt_pk_bf16_f32 v222, v44, v45
	v_cvt_pk_bf16_f32 v223, v46, v47
	v_add_f32_e32 v2, v2, v0
	v_add_f32_e32 v3, v3, v14
	v_mfma_f32_32x32x16_bf16 v[48:63], v[76:79], v[220:223], v[48:63]
	s_nop 11
	v_cvt_pk_bf16_f32 v232, v48, v108
	v_fma_f32 v13, v48, v2, v49
	v_fma_f32 v13, v108, v3, v13
	v_mfma_f32_32x32x16_bf16 v[16:31], v[224:227], v[232:235], v[16:31]
	v_mfma_f32_32x32x16_bf16 v[32:47], v[228:231], v[232:235], v[32:47]
	ds_write_b32 v191, v13 offset:2048
	s_waitcnt lgkmcnt(1)
; DI unsigned cvtpk_n(float lo, float hi) { f32x2 v = {lo, hi}; bf16x2n b = __builtin_convertvector(v, bf16x2n); return __builtin_bit_cast(unsigned, b); }
; DI void scan_ld(ScanStep& t, const float* rec, const char* zimg, int fragoff, bool isaq, int h, int m, int vrow) {
;     const char* fp = isaq ? (const char*)(rec + fragoff) + h * 16 : zimg + h * 16;
; #pragma unroll
;     for (int q = 0; q < 4; ++q) t.f[q] = *(const bf16x8*)(fp + q * 32);
;     t.b0 = rec[64 + m]; t.k0 = rec[128 + m]; t.b1 = rec[96 + m]; t.k1 = rec[160 + m]; t.v = rec[192 + vrow]; t.brp = *(const f32x4*)(rec + 256); t.krp = *(const f32x4*)(rec + 260);
; }
; DI void phase_scan(const bf16_t* R, const bf16_t* Kk, const bf16_t* V, const __half* DEC, const bf16_t* AA, const float* INV, const float* kkp, const float* kap,
;                    bf16_t* MIX, bf16_t* YB, char* lds) {
;     ...
;                 for (int st = 0; st < 16; ++st) {
;                     f32x16 d0 = __builtin_amdgcn_mfma_f32_32x32x16_bf16(t.f[0], pack_acc(acc0, 0), zero16, 0, 0, 0);
;                     d0 = __builtin_amdgcn_mfma_f32_32x32x16_bf16(t.f[1], pack_acc(acc0, 1), d0, 0, 0, 0);
;                     d0 = __builtin_amdgcn_mfma_f32_32x32x16_bf16(t.f[2], pack_acc(acc1, 0), d0, 0, 0, 0);
;                     d0 = __builtin_amdgcn_mfma_f32_32x32x16_bf16(t.f[3], pack_acc(acc1, 1), d0, 0, 0, 0);
;                     __builtin_amdgcn_sched_barrier(0);
;                     ScanStep n; scan_ld(n, cur + (st + 1) * SREC, zimg, fragoff, isaq, h, m, vrow);
;                     __builtin_amdgcn_sched_barrier(0);
;                     const float sa = d0[0], z = d0[1];
;                     yb[st * 64 + vrow] = z + sa * ((t.brp[0] + t.brp[1]) + (t.brp[2] + t.brp[3])) + t.v * ((t.krp[0] + t.krp[1]) + (t.krp[2] + t.krp[3]));
;                     const unsigned hz = h ? 0u : 0xffffffffu;
;                     const u32x4 ua0 = {cvtpk_n(t.b0, t.k0) & hz, 0u, 0u, 0u}, ua1 = {cvtpk_n(t.b1, t.k1) & hz, 0u, 0u, 0u}, ub = {cvtpk_n(sa, t.v) & hz, 0u, 0u, 0u};
;                     acc0 = __builtin_amdgcn_mfma_f32_32x32x16_bf16(__builtin_bit_cast(bf16x8, ua0), __builtin_bit_cast(bf16x8, ub), acc0, 0, 0, 0);
;                     acc1 = __builtin_amdgcn_mfma_f32_32x32x16_bf16(__builtin_bit_cast(bf16x8, ua1), __builtin_bit_cast(bf16x8, ub), acc1, 0, 0, 0);
;                     t = n;
	s_mov_b64 exec, s[40:41]
	ds_read_b128 v[64:67], v188 offset:10560
	ds_read_b128 v[68:71], v188 offset:10592
	ds_read_b128 v[72:75], v188 offset:10624
	ds_read_b128 v[76:79], v188 offset:10656
	s_mov_b64 exec, -1
	ds_read_b32 v224, v189 offset:10560
	ds_read_b32 v228, v189 offset:10688
	ds_read_b32 v108, v190 offset:10560
	v_cvt_pk_bf16_f32 v216, v16, v17
	v_cvt_pk_bf16_f32 v217, v18, v19
	v_cvt_pk_bf16_f32 v218, v20, v21
	v_cvt_pk_bf16_f32 v219, v22, v23
	ds_read_b128 v[4:7], v170 offset:11584
	ds_read_b128 v[8:11], v170 offset:11600
	v_mfma_f32_32x32x16_bf16 v[48:63], v[192:195], v[216:219], 0
	v_cvt_pk_bf16_f32 v220, v24, v25
	v_cvt_pk_bf16_f32 v221, v26, v27
	v_cvt_pk_bf16_f32 v222, v28, v29
	v_cvt_pk_bf16_f32 v223, v30, v31
	v_add_f32_e32 v2, v208, v209
	v_add_f32_e32 v3, v212, v213
	v_mfma_f32_32x32x16_bf16 v[48:63], v[196:199], v[220:223], v[48:63]
	v_cvt_pk_bf16_f32 v216, v32, v33
	v_cvt_pk_bf16_f32 v217, v34, v35
	v_cvt_pk_bf16_f32 v218, v36, v37
	v_cvt_pk_bf16_f32 v219, v38, v39
	v_add_f32_e32 v0, v210, v211
	v_add_f32_e32 v14, v214, v215
	v_mfma_f32_32x32x16_bf16 v[48:63], v[200:203], v[216:219], v[48:63]
	v_cvt_pk_bf16_f32 v220, v40, v41
	v_cvt_pk_bf16_f32 v221, v42, v43
	v_cvt_pk_bf16_f32 v222, v44, v45
	v_cvt_pk_bf16_f32 v223, v46, v47
	v_add_f32_e32 v2, v2, v0
	v_add_f32_e32 v3, v3, v14
	v_mfma_f32_32x32x16_bf16 v[48:63], v[204:207], v[220:223], v[48:63]
	s_nop 11
	v_cvt_pk_bf16_f32 v232, v48, v114
	v_fma_f32 v13, v48, v2, v49
	v_fma_f32 v13, v114, v3, v13
	v_mfma_f32_32x32x16_bf16 v[16:31], v[80:83], v[232:235], v[16:31]
	v_mfma_f32_32x32x16_bf16 v[32:47], v[84:87], v[232:235], v[32:47]
	ds_write_b32 v191, v13 offset:2304
	s_waitcnt lgkmcnt(1)
	s_mov_b64 exec, s[40:41]
	ds_read_b128 v[192:195], v188 offset:11616
	ds_read_b128 v[196:199], v188 offset:11648
	ds_read_b128 v[200:203], v188 offset:11680
	ds_read_b128 v[204:207], v188 offset:11712
	s_mov_b64 exec, -1
	ds_read_b32 v80, v189 offset:11616
	ds_read_b32 v84, v189 offset:11744
	ds_read_b32 v114, v190 offset:11616
	v_cvt_pk_bf16_f32 v216, v16, v17
	v_cvt_pk_bf16_f32 v217, v18, v19
	v_cvt_pk_bf16_f32 v218, v20, v21
	v_cvt_pk_bf16_f32 v219, v22, v23
	ds_read_b128 v[208:211], v170 offset:12640
	ds_read_b128 v[212:215], v170 offset:12656
	v_mfma_f32_32x32x16_bf16 v[48:63], v[64:67], v[216:219], 0
	v_cvt_pk_bf16_f32 v220, v24, v25
	v_cvt_pk_bf16_f32 v221, v26, v27
	v_cvt_pk_bf16_f32 v222, v28, v29
	v_cvt_pk_bf16_f32 v223, v30, v31
	v_add_f32_e32 v2, v4, v5
	v_add_f32_e32 v3, v8, v9
	v_mfma_f32_32x32x16_bf16 v[48:63], v[68:71], v[220:223], v[48:63]
	v_cvt_pk_bf16_f32 v216, v32, v33
	v_cvt_pk_bf16_f32 v217, v34, v35
	v_cvt_pk_bf16_f32 v218, v36, v37
	v_cvt_pk_bf16_f32 v219, v38, v39
	v_add_f32_e32 v0, v6, v7
	v_add_f32_e32 v14, v10, v11
	v_mfma_f32_32x32x16_bf16 v[48:63], v[72:75], v[216:219], v[48:63]
	v_cvt_pk_bf16_f32 v220, v40, v41
	v_cvt_pk_bf16_f32 v221, v42, v43
	v_cvt_pk_bf16_f32 v222, v44, v45
	v_cvt_pk_bf16_f32 v223, v46, v47
	v_add_f32_e32 v2, v2, v0
	v_add_f32_e32 v3, v3, v14
	v_mfma_f32_32x32x16_bf16 v[48:63], v[76:79], v[220:223], v[48:63]
	s_nop 11
	v_cvt_pk_bf16_f32 v232, v48, v108
	v_fma_f32 v13, v48, v2, v49
	v_fma_f32 v13, v108, v3, v13
	v_mfma_f32_32x32x16_bf16 v[16:31], v[224:227], v[232:235], v[16:31]
	v_mfma_f32_32x32x16_bf16 v[32:47], v[228:231], v[232:235], v[32:47]
	ds_write_b32 v191, v13 offset:2560
	s_waitcnt lgkmcnt(1)
	s_mov_b64 exec, s[40:41]
	ds_read_b128 v[64:67], v188 offset:12672
	ds_read_b128 v[68:71], v188 offset:12704
	ds_read_b128 v[72:75], v188 offset:12736
	ds_read_b128 v[76:79], v188 offset:12768
	s_mov_b64 exec, -1
	ds_read_b32 v224, v189 offset:12672
	ds_read_b32 v228, v189 offset:12800
	ds_read_b32 v108, v190 offset:12672
	v_cvt_pk_bf16_f32 v216, v16, v17
	v_cvt_pk_bf16_f32 v217, v18, v19
	v_cvt_pk_bf16_f32 v218, v20, v21
	v_cvt_pk_bf16_f32 v219, v22, v23
	ds_read_b128 v[4:7], v170 offset:13696
	ds_read_b128 v[8:11], v170 offset:13712
	v_mfma_f32_32x32x16_bf16 v[48:63], v[192:195], v[216:219], 0
	v_cvt_pk_bf16_f32 v220, v24, v25
	v_cvt_pk_bf16_f32 v221, v26, v27
	v_cvt_pk_bf16_f32 v222, v28, v29
	v_cvt_pk_bf16_f32 v223, v30, v31
	v_add_f32_e32 v2, v208, v209
	v_add_f32_e32 v3, v212, v213
	v_mfma_f32_32x32x16_bf16 v[48:63], v[196:199], v[220:223], v[48:63]
	v_cvt_pk_bf16_f32 v216, v32, v33
	v_cvt_pk_bf16_f32 v217, v34, v35
	v_cvt_pk_bf16_f32 v218, v36, v37
	v_cvt_pk_bf16_f32 v219, v38, v39
	v_add_f32_e32 v0, v210, v211
	v_add_f32_e32 v14, v214, v215
	v_mfma_f32_32x32x16_bf16 v[48:63], v[200:203], v[216:219], v[48:63]
	v_cvt_pk_bf16_f32 v220, v40, v41
	v_cvt_pk_bf16_f32 v221, v42, v43
	v_cvt_pk_bf16_f32 v222, v44, v45
	v_cvt_pk_bf16_f32 v223, v46, v47
	v_add_f32_e32 v2, v2, v0
	v_add_f32_e32 v3, v3, v14
	v_mfma_f32_32x32x16_bf16 v[48:63], v[204:207], v[220:223], v[48:63]
	s_nop 11
	v_cvt_pk_bf16_f32 v232, v48, v114
	v_fma_f32 v13, v48, v2, v49
	v_fma_f32 v13, v114, v3, v13
	v_mfma_f32_32x32x16_bf16 v[16:31], v[80:83], v[232:235], v[16:31]
	v_mfma_f32_32x32x16_bf16 v[32:47], v[84:87], v[232:235], v[32:47]
	ds_write_b32 v191, v13 offset:2816
	s_waitcnt lgkmcnt(1)
; DI unsigned cvtpk_n(float lo, float hi) { f32x2 v = {lo, hi}; bf16x2n b = __builtin_convertvector(v, bf16x2n); return __builtin_bit_cast(unsigned, b); }
; DI void scan_ld(ScanStep& t, const float* rec, const char* zimg, int fragoff, bool isaq, int h, int m, int vrow) {
;     const char* fp = isaq ? (const char*)(rec + fragoff) + h * 16 : zimg + h * 16;
; #pragma unroll
;     for (int q = 0; q < 4; ++q) t.f[q] = *(const bf16x8*)(fp + q * 32);
;     t.b0 = rec[64 + m]; t.k0 = rec[128 + m]; t.b1 = rec[96 + m]; t.k1 = rec[160 + m]; t.v = rec[192 + vrow]; t.brp = *(const f32x4*)(rec + 256); t.krp = *(const f32x4*)(rec + 260);
; }
; DI void phase_scan(const bf16_t* R, const bf16_t* Kk, const bf16_t* V, const __half* DEC, const bf16_t* AA, const float* INV, const float* kkp, const float* kap,
;                    bf16_t* MIX, bf16_t* YB, char* lds) {
;     ...
;                 for (int st = 0; st < 16; ++st) {
;                     f32x16 d0 = __builtin_amdgcn_mfma_f32_32x32x16_bf16(t.f[0], pack_acc(acc0, 0), zero16, 0, 0, 0);
;                     d0 = __builtin_amdgcn_mfma_f32_32x32x16_bf16(t.f[1], pack_acc(acc0, 1), d0, 0, 0, 0);
;                     d0 = __builtin_amdgcn_mfma_f32_32x32x16_bf16(t.f[2], pack_acc(acc1, 0), d0, 0, 0, 0);
;                     d0 = __builtin_amdgcn_mfma_f32_32x32x16_bf16(t.f[3], pack_acc(acc1, 1), d0, 0, 0, 0);
;                     __builtin_amdgcn_sched_barrier(0);
;                     ScanStep n; scan_ld(n, cur + (st + 1) * SREC, zimg, fragoff, isaq, h, m, vrow);
;                     __builtin_amdgcn_sched_barrier(0);
;                     const float sa = d0[0], z = d0[1];
;                     yb[st * 64 + vrow] = z + sa * ((t.brp[0] + t.brp[1]) + (t.brp[2] + t.brp[3])) + t.v * ((t.krp[0] + t.krp[1]) + (t.krp[2] + t.krp[3]));
;                     const unsigned hz = h ? 0u : 0xffffffffu;
;                     const u32x4 ua0 = {cvtpk_n(t.b0, t.k0) & hz, 0u, 0u, 0u}, ua1 = {cvtpk_n(t.b1, t.k1) & hz, 0u, 0u, 0u}, ub = {cvtpk_n(sa, t.v) & hz, 0u, 0u, 0u};
;                     acc0 = __builtin_amdgcn_mfma_f32_32x32x16_bf16(__builtin_bit_cast(bf16x8, ua0), __builtin_bit_cast(bf16x8, ub), acc0, 0, 0, 0);
;                     acc1 = __builtin_amdgcn_mfma_f32_32x32x16_bf16(__builtin_bit_cast(bf16x8, ua1), __builtin_bit_cast(bf16x8, ub), acc1, 0, 0, 0);
;                     t = n;
	s_mov_b64 exec, s[40:41]
	ds_read_b128 v[192:195], v188 offset:13728
	ds_read_b128 v[196:199], v188 offset:13760
	ds_read_b128 v[200:203], v188 offset:13792
	ds_read_b128 v[204:207], v188 offset:13824
	s_mov_b64 exec, -1
	ds_read_b32 v80, v189 offset:13728
	ds_read_b32 v84, v189 offset:13856
	ds_read_b32 v114, v190 offset:13728
	v_cvt_pk_bf16_f32 v216, v16, v17
	v_cvt_pk_bf16_f32 v217, v18, v19
	v_cvt_pk_bf16_f32 v218, v20, v21
	v_cvt_pk_bf16_f32 v219, v22, v23
	ds_read_b128 v[208:211], v170 offset:14752
	ds_read_b128 v[212:215], v170 offset:14768
	v_mfma_f32_32x32x16_bf16 v[48:63], v[64:67], v[216:219], 0
	v_cvt_pk_bf16_f32 v220, v24, v25
	v_cvt_pk_bf16_f32 v221, v26, v27
	v_cvt_pk_bf16_f32 v222, v28, v29
	v_cvt_pk_bf16_f32 v223, v30, v31
	v_add_f32_e32 v2, v4, v5
	v_add_f32_e32 v3, v8, v9
	v_mfma_f32_32x32x16_bf16 v[48:63], v[68:71], v[220:223], v[48:63]
	v_cvt_pk_bf16_f32 v216, v32, v33
	v_cvt_pk_bf16_f32 v217, v34, v35
	v_cvt_pk_bf16_f32 v218, v36, v37
	v_cvt_pk_bf16_f32 v219, v38, v39
	v_add_f32_e32 v0, v6, v7
	v_add_f32_e32 v14, v10, v11
	v_mfma_f32_32x32x16_bf16 v[48:63], v[72:75], v[216:219], v[48:63]
	v_cvt_pk_bf16_f32 v220, v40, v41
	v_cvt_pk_bf16_f32 v221, v42, v43
	v_cvt_pk_bf16_f32 v222, v44, v45
	v_cvt_pk_bf16_f32 v223, v46, v47
	v_add_f32_e32 v2, v2, v0
	v_add_f32_e32 v3, v3, v14
	v_mfma_f32_32x32x16_bf16 v[48:63], v[76:79], v[220:223], v[48:63]
	s_nop 11
	v_cvt_pk_bf16_f32 v232, v48, v108
	v_fma_f32 v13, v48, v2, v49
	v_fma_f32 v13, v108, v3, v13
	v_mfma_f32_32x32x16_bf16 v[16:31], v[224:227], v[232:235], v[16:31]
	v_mfma_f32_32x32x16_bf16 v[32:47], v[228:231], v[232:235], v[32:47]
	ds_write_b32 v191, v13 offset:3072
	s_waitcnt lgkmcnt(1)
	s_mov_b64 exec, s[40:41]
	ds_read_b128 v[64:67], v188 offset:14784
	ds_read_b128 v[68:71], v188 offset:14816
	ds_read_b128 v[72:75], v188 offset:14848
	ds_read_b128 v[76:79], v188 offset:14880
	s_mov_b64 exec, -1
	ds_read_b32 v224, v189 offset:14784
	ds_read_b32 v228, v189 offset:14912
	ds_read_b32 v108, v190 offset:14784
	v_cvt_pk_bf16_f32 v216, v16, v17
	v_cvt_pk_bf16_f32 v217, v18, v19
	v_cvt_pk_bf16_f32 v218, v20, v21
	v_cvt_pk_bf16_f32 v219, v22, v23
	ds_read_b128 v[4:7], v170 offset:15808
	ds_read_b128 v[8:11], v170 offset:15824
	v_mfma_f32_32x32x16_bf16 v[48:63], v[192:195], v[216:219], 0
	v_cvt_pk_bf16_f32 v220, v24, v25
	v_cvt_pk_bf16_f32 v221, v26, v27
	v_cvt_pk_bf16_f32 v222, v28, v29
	v_cvt_pk_bf16_f32 v223, v30, v31
	v_add_f32_e32 v2, v208, v209
	v_add_f32_e32 v3, v212, v213
	v_mfma_f32_32x32x16_bf16 v[48:63], v[196:199], v[220:223], v[48:63]
	v_cvt_pk_bf16_f32 v216, v32, v33
	v_cvt_pk_bf16_f32 v217, v34, v35
	v_cvt_pk_bf16_f32 v218, v36, v37
	v_cvt_pk_bf16_f32 v219, v38, v39
	v_add_f32_e32 v0, v210, v211
	v_add_f32_e32 v14, v214, v215
	v_mfma_f32_32x32x16_bf16 v[48:63], v[200:203], v[216:219], v[48:63]
	v_cvt_pk_bf16_f32 v220, v40, v41
	v_cvt_pk_bf16_f32 v221, v42, v43
	v_cvt_pk_bf16_f32 v222, v44, v45
	v_cvt_pk_bf16_f32 v223, v46, v47
	v_add_f32_e32 v2, v2, v0
	v_add_f32_e32 v3, v3, v14
	v_mfma_f32_32x32x16_bf16 v[48:63], v[204:207], v[220:223], v[48:63]
	s_nop 11
	v_cvt_pk_bf16_f32 v232, v48, v114
	v_fma_f32 v13, v48, v2, v49
	v_fma_f32 v13, v114, v3, v13
	v_mfma_f32_32x32x16_bf16 v[16:31], v[80:83], v[232:235], v[16:31]
	v_mfma_f32_32x32x16_bf16 v[32:47], v[84:87], v[232:235], v[32:47]
	ds_write_b32 v191, v13 offset:3328
	s_waitcnt lgkmcnt(1)
; DI unsigned cvtpk_n(float lo, float hi) { f32x2 v = {lo, hi}; bf16x2n b = __builtin_convertvector(v, bf16x2n); return __builtin_bit_cast(unsigned, b); }
; DI void phase_scan(const bf16_t* R, const bf16_t* Kk, const bf16_t* V, const __half* DEC, const bf16_t* AA, const float* INV, const float* kkp, const float* kap,
;                    bf16_t* MIX, bf16_t* YB, char* lds) {
;     ...
;                 for (int st = 0; st < 16; ++st) {
;                     f32x16 d0 = __builtin_amdgcn_mfma_f32_32x32x16_bf16(t.f[0], pack_acc(acc0, 0), zero16, 0, 0, 0);
;                     d0 = __builtin_amdgcn_mfma_f32_32x32x16_bf16(t.f[1], pack_acc(acc0, 1), d0, 0, 0, 0);
;                     d0 = __builtin_amdgcn_mfma_f32_32x32x16_bf16(t.f[2], pack_acc(acc1, 0), d0, 0, 0, 0);
;                     d0 = __builtin_amdgcn_mfma_f32_32x32x16_bf16(t.f[3], pack_acc(acc1, 1), d0, 0, 0, 0);
;                     __builtin_amdgcn_sched_barrier(0);
;                     ScanStep n; scan_ld(n, cur + (st + 1) * SREC, zimg, fragoff, isaq, h, m, vrow);
;                     __builtin_amdgcn_sched_barrier(0);
;                     const float sa = d0[0], z = d0[1];
;                     yb[st * 64 + vrow] = z + sa * ((t.brp[0] + t.brp[1]) + (t.brp[2] + t.brp[3])) + t.v * ((t.krp[0] + t.krp[1]) + (t.krp[2] + t.krp[3]));
;                     const unsigned hz = h ? 0u : 0xffffffffu;
;                     const u32x4 ua0 = {cvtpk_n(t.b0, t.k0) & hz, 0u, 0u, 0u}, ua1 = {cvtpk_n(t.b1, t.k1) & hz, 0u, 0u, 0u}, ub = {cvtpk_n(sa, t.v) & hz, 0u, 0u, 0u};
;                     acc0 = __builtin_amdgcn_mfma_f32_32x32x16_bf16(__builtin_bit_cast(bf16x8, ua0), __builtin_bit_cast(bf16x8, ub), acc0, 0, 0, 0);
;                     acc1 = __builtin_amdgcn_mfma_f32_32x32x16_bf16(__builtin_bit_cast(bf16x8, ua1), __builtin_bit_cast(bf16x8, ub), acc1, 0, 0, 0);
;                     t = n;
;                 }
;                 const float* wc = cur + 16 * SREC;
; #pragma unroll
;                 for (int g_ = 0; g_ < 4; ++g_) { const f32x4 w0 = *(const f32x4*)(wc + 8 * g_ + 4 * h), w1 = *(const f32x4*)(wc + 32 + 8 * g_ + 4 * h);
; #pragma unroll
;                     for (int e = 0; e < 4; ++e) { acc0[4 * g_ + e] *= w0[e]; acc1[4 * g_ + e] *= w1[e]; } }
	s_mov_b64 exec, s[40:41]
	ds_read_b128 v[192:195], v188 offset:15840
	ds_read_b128 v[196:199], v188 offset:15872
	ds_read_b128 v[200:203], v188 offset:15904
	ds_read_b128 v[204:207], v188 offset:15936
	s_mov_b64 exec, -1
	ds_read_b32 v80, v189 offset:15840
	ds_read_b32 v84, v189 offset:15968
	ds_read_b32 v114, v190 offset:15840
	v_cvt_pk_bf16_f32 v216, v16, v17
	v_cvt_pk_bf16_f32 v217, v18, v19
	v_cvt_pk_bf16_f32 v218, v20, v21
	v_cvt_pk_bf16_f32 v219, v22, v23
	ds_read_b128 v[208:211], v170 offset:16864
	ds_read_b128 v[212:215], v170 offset:16880
	v_mfma_f32_32x32x16_bf16 v[48:63], v[64:67], v[216:219], 0
	v_cvt_pk_bf16_f32 v220, v24, v25
	v_cvt_pk_bf16_f32 v221, v26, v27
	v_cvt_pk_bf16_f32 v222, v28, v29
	v_cvt_pk_bf16_f32 v223, v30, v31
	v_add_f32_e32 v2, v4, v5
	v_add_f32_e32 v3, v8, v9
	v_mfma_f32_32x32x16_bf16 v[48:63], v[68:71], v[220:223], v[48:63]
	v_cvt_pk_bf16_f32 v216, v32, v33
	v_cvt_pk_bf16_f32 v217, v34, v35
	v_cvt_pk_bf16_f32 v218, v36, v37
	v_cvt_pk_bf16_f32 v219, v38, v39
	v_add_f32_e32 v0, v6, v7
	v_add_f32_e32 v14, v10, v11
	v_mfma_f32_32x32x16_bf16 v[48:63], v[72:75], v[216:219], v[48:63]
	v_cvt_pk_bf16_f32 v220, v40, v41
	v_cvt_pk_bf16_f32 v221, v42, v43
	v_cvt_pk_bf16_f32 v222, v44, v45
	v_cvt_pk_bf16_f32 v223, v46, v47
	v_add_f32_e32 v2, v2, v0
	v_add_f32_e32 v3, v3, v14
	v_mfma_f32_32x32x16_bf16 v[48:63], v[76:79], v[220:223], v[48:63]
	s_nop 11
	v_cvt_pk_bf16_f32 v232, v48, v108
	v_fma_f32 v13, v48, v2, v49
	v_fma_f32 v13, v108, v3, v13
	v_mfma_f32_32x32x16_bf16 v[16:31], v[224:227], v[232:235], v[16:31]
	v_mfma_f32_32x32x16_bf16 v[32:47], v[228:231], v[232:235], v[32:47]
	ds_write_b32 v191, v13 offset:3584
	s_waitcnt lgkmcnt(1)
	s_nop 8
	v_cvt_pk_bf16_f32 v216, v16, v17
	v_cvt_pk_bf16_f32 v217, v18, v19
	v_cvt_pk_bf16_f32 v218, v20, v21
	v_cvt_pk_bf16_f32 v219, v22, v23
	s_nop 1
	v_mfma_f32_32x32x16_bf16 v[48:63], v[192:195], v[216:219], 0
	v_cvt_pk_bf16_f32 v220, v24, v25
	v_cvt_pk_bf16_f32 v221, v26, v27
	v_cvt_pk_bf16_f32 v222, v28, v29
	v_cvt_pk_bf16_f32 v223, v30, v31
	v_add_f32_e32 v2, v208, v209
	v_add_f32_e32 v3, v212, v213
	v_mfma_f32_32x32x16_bf16 v[48:63], v[196:199], v[220:223], v[48:63]
	v_cvt_pk_bf16_f32 v216, v32, v33
	v_cvt_pk_bf16_f32 v217, v34, v35
	v_cvt_pk_bf16_f32 v218, v36, v37
	v_cvt_pk_bf16_f32 v219, v38, v39
	v_add_f32_e32 v0, v210, v211
	v_add_f32_e32 v14, v214, v215
	v_mfma_f32_32x32x16_bf16 v[48:63], v[200:203], v[216:219], v[48:63]
	v_cvt_pk_bf16_f32 v220, v40, v41
	v_cvt_pk_bf16_f32 v221, v42, v43
	v_cvt_pk_bf16_f32 v222, v44, v45
	v_cvt_pk_bf16_f32 v223, v46, v47
	v_add_f32_e32 v2, v2, v0
	v_add_f32_e32 v3, v3, v14
	v_mfma_f32_32x32x16_bf16 v[48:63], v[204:207], v[220:223], v[48:63]
	s_nop 11
	v_cvt_pk_bf16_f32 v232, v48, v114
	v_fma_f32 v13, v48, v2, v49
	v_fma_f32 v13, v114, v3, v13
	v_mfma_f32_32x32x16_bf16 v[16:31], v[80:83], v[232:235], v[16:31]
	v_mfma_f32_32x32x16_bf16 v[32:47], v[84:87], v[232:235], v[32:47]
	ds_write_b32 v191, v13 offset:3840
	v_lshl_add_u32 v0, v136, 2, v170
	ds_read_b128 v[2:5], v0 offset:16896
	ds_read_b128 v[6:9], v0 offset:16928
	s_waitcnt lgkmcnt(0)
	ds_read_b128 v[10:13], v0 offset:16960
	ds_read_b128 v[48:51], v0 offset:16992
	ds_read_b128 v[52:55], v0 offset:17024
	ds_read_b128 v[56:59], v0 offset:17056
	ds_read_b128 v[60:63], v0 offset:17088
	ds_read_b128 v[88:91], v0 offset:17120
	s_waitcnt lgkmcnt(0)
	v_pk_mul_f32 v[30:31], v[30:31], v[50:51]
	v_pk_mul_f32 v[26:27], v[26:27], v[12:13]
	v_pk_mul_f32 v[22:23], v[22:23], v[8:9]
	v_pk_mul_f32 v[18:19], v[18:19], v[4:5]
	v_pk_mul_f32 v[28:29], v[28:29], v[48:49]
	v_pk_mul_f32 v[24:25], v[24:25], v[10:11]
	v_pk_mul_f32 v[20:21], v[20:21], v[6:7]
	v_pk_mul_f32 v[16:17], v[16:17], v[2:3]
	v_pk_mul_f32 v[46:47], v[46:47], v[90:91]
	v_pk_mul_f32 v[42:43], v[42:43], v[62:63]
	v_pk_mul_f32 v[38:39], v[38:39], v[58:59]
	v_pk_mul_f32 v[34:35], v[34:35], v[54:55]
	v_pk_mul_f32 v[44:45], v[44:45], v[88:89]
	v_pk_mul_f32 v[40:41], v[40:41], v[60:61]
	v_pk_mul_f32 v[36:37], v[36:37], v[56:57]
	v_pk_mul_f32 v[32:33], v[32:33], v[52:53]
	s_branch .LBB0_2281

;     DI void operator()(const pg8::f32x4 (&acc)[2][2][4][2], const pg8::Unit& u, int wr, int wc, int fr, int fq) const {
;     ...
;         for (int ai = 0; ai < 2; ++ai)
; #pragma unroll
;             for (int m = 0; m < 4; ++m) { const int rit = ai * 128 + wr * 64 + m * 16 + fr;
; #pragma unroll
;                 for (int bj = 0; bj < 2; ++bj) { f(rit, u.pn * 256 + bj * 128 + wc * 32 + 8 * fq, acc[ai][bj][m][0], acc[ai][bj][m][1], u, fq); __builtin_amdgcn_sched_barrier(0); } }
.LBB0_3939:
	s_lshl_b32 s2, s2, 8
	v_mov_b32_e32 v152, v160
	v_mov_b32_e32 v153, v0
	s_or_b32 s2, s2, s34
	s_nop 0
	v_add_u32_e32 v163, s60, v153
	v_lshl_add_u32 v156, v152, 3, s2
	s_movk_i32 s2, 0x940
	v_cmp_gt_i32_e32 vcc, s2, v156
	s_mul_hi_i32 s2, s63, 0x38e38e39
	v_ashrrev_i32_e32 v157, 31, v156
	v_lshl_add_u32 v158, s63, 8, v163
	s_and_saveexec_b64 s[20:21], vcc
	s_cbranch_execz .LBB0_3941
	v_ashrrev_i32_e32 v159, 31, v158
	v_lshl_add_u64 v[164:165], v[158:159], 2, s[70:71]
	flat_load_dword v152, v[164:165]
	s_lshr_b32 s12, s2, 31
	s_ashr_i32 s14, s2, 1
	s_add_i32 s12, s14, s12
	s_mul_i32 s14, s12, -9
	s_sub_i32 s33, 0, s63
	s_cmp_lg_u32 s14, s33
	s_cselect_b32 s12, s12, 32
	s_mul_hi_i32 s14, s12, 0x2800
	s_mulk_i32 s12, 0x2800
	v_mov_b64_e32 v[190:191], s[8:9]
	s_movk_i32 s4, 0x1280
	s_add_u32 s100, s58, s12
	s_addc_u32 s101, s59, s14
	v_lshl_add_u64 v[224:225], v[156:157], 2, s[100:101]
	flat_load_dwordx4 v[200:203], v[224:225]
	flat_load_dwordx4 v[204:207], v[224:225] offset:16
	flat_load_dwordx4 v[208:211], v[224:225] offset:512
	flat_load_dwordx4 v[212:215], v[224:225] offset:528
	flat_load_dword v217, v[164:165] offset:64
	flat_load_dword v218, v[164:165] offset:128
	flat_load_dword v219, v[164:165] offset:192
	flat_load_dword v220, v[164:165] offset:512
	flat_load_dword v221, v[164:165] offset:576
	flat_load_dword v222, v[164:165] offset:640
	flat_load_dword v223, v[164:165] offset:704
	s_waitcnt vmcnt(0) lgkmcnt(0)
	v_mov_b32_e32 v216, v152
	v_fmamk_f32 v152, v152, 0x3a800000, v173
	v_cmp_gt_f32_e64 s[36:37], s3, v152
	v_mul_f32_e32 v153, 0x4b800000, v152
	s_nop 0
	v_cndmask_b32_e64 v152, v152, v153, s[36:37]
	v_rsq_f32_e32 v152, v152
	s_nop 0
	v_mul_f32_e32 v153, 0x45800000, v152
	v_cndmask_b32_e64 v188, v152, v153, s[36:37]
	s_add_u32 s36, s58, s12
	s_addc_u32 s37, s59, s14
	v_lshl_add_u64 v[168:169], v[156:157], 2, s[36:37]
	v_mad_i64_i32 v[190:191], s[36:37], v158, s4, v[190:191]
	v_lshl_add_u64 v[190:191], v[156:157], 1, v[190:191]
	v_pk_fma_f32 v[126:127], v[126:127], v[188:189], v[200:201] op_sel_hi:[1,0,1]
	v_pk_fma_f32 v[164:165], v[124:125], v[188:189], v[206:207] op_sel_hi:[1,0,1]
	v_pk_fma_f32 v[124:125], v[122:123], v[188:189], v[204:205] op_sel_hi:[1,0,1]
	v_pk_fma_f32 v[128:129], v[128:129], v[188:189], v[202:203] op_sel_hi:[1,0,1]
	v_cvt_pk_bf16_f32 v122, v126, v127
	s_nop 0
	v_cvt_pk_bf16_f32 v123, v128, v129
	v_cvt_pk_bf16_f32 v124, v124, v125
	v_cvt_pk_bf16_f32 v125, v164, v165
	flat_store_dwordx4 v[190:191], v[122:125]
.LBB0_3941:
	s_or_b64 exec, exec, s[20:21]
	s_nop 0
	v_add_u32_e32 v122, 0x80, v156
	s_movk_i32 s4, 0x940
	v_cmp_gt_i32_e64 s[36:37], s4, v122
	s_and_saveexec_b64 s[20:21], s[36:37]
	s_cbranch_execz .LBB0_3943
	v_ashrrev_i32_e32 v159, 31, v158
	v_lshl_add_u64 v[122:123], v[158:159], 2, s[70:71]
	s_lshr_b32 s12, s2, 31
	s_ashr_i32 s14, s2, 1
	s_add_i32 s12, s14, s12
	s_mul_i32 s14, s12, -9
	s_sub_i32 s33, 0, s63
	s_cmp_lg_u32 s14, s33
	s_cselect_b32 s12, s12, 32
	s_mul_hi_i32 s14, s12, 0x2800
	s_mulk_i32 s12, 0x2800
	v_mov_b64_e32 v[166:167], s[8:9]
	s_movk_i32 s4, 0x1280
	v_fmamk_f32 v122, v216, 0x3a800000, v173
	v_cmp_gt_f32_e64 s[40:41], s3, v122
	v_mul_f32_e32 v123, 0x4b800000, v122
	s_nop 0
	v_cndmask_b32_e64 v122, v122, v123, s[40:41]
	v_rsq_f32_e32 v122, v122
	s_nop 0
	v_mul_f32_e32 v123, 0x45800000, v122
	v_cndmask_b32_e64 v164, v122, v123, s[40:41]
	s_add_u32 s40, s58, s12
	s_addc_u32 s41, s59, s14
	v_lshl_add_u64 v[126:127], v[156:157], 2, s[40:41]
	v_mad_i64_i32 v[158:159], s[40:41], v158, s4, v[166:167]
	v_lshl_add_u64 v[158:159], v[156:157], 1, v[158:159]
	v_pk_fma_f32 v[118:119], v[118:119], v[164:165], v[208:209] op_sel_hi:[1,0,1]
	v_pk_fma_f32 v[122:123], v[116:117], v[164:165], v[214:215] op_sel_hi:[1,0,1]
	v_pk_fma_f32 v[116:117], v[114:115], v[164:165], v[212:213] op_sel_hi:[1,0,1]
	v_pk_fma_f32 v[120:121], v[120:121], v[164:165], v[210:211] op_sel_hi:[1,0,1]
	v_cvt_pk_bf16_f32 v114, v118, v119
	s_nop 0
	v_cvt_pk_bf16_f32 v115, v120, v121
	v_cvt_pk_bf16_f32 v116, v116, v117
	v_cvt_pk_bf16_f32 v117, v122, v123
	flat_store_dwordx4 v[158:159], v[114:117] offset:256
.LBB0_3943:
	s_or_b64 exec, exec, s[20:21]
	s_nop 0
	v_add_u32_e32 v114, 16, v163
	v_lshl_add_u32 v114, s63, 8, v114
	s_and_saveexec_b64 s[20:21], vcc
	s_cbranch_execz .LBB0_3945
	v_ashrrev_i32_e32 v115, 31, v114
	v_lshl_add_u64 v[116:117], v[114:115], 2, s[70:71]
	s_lshr_b32 s12, s2, 31
	s_ashr_i32 s14, s2, 1
	s_add_i32 s12, s14, s12
	s_mul_i32 s14, s12, -9
	s_sub_i32 s33, 0, s63
	s_cmp_lg_u32 s14, s33
	s_cselect_b32 s12, s12, 32
	s_mul_hi_i32 s14, s12, 0x2800
	s_mulk_i32 s12, 0x2800
	v_mov_b64_e32 v[126:127], s[8:9]
	s_movk_i32 s4, 0x1280
	v_fmamk_f32 v115, v217, 0x3a800000, v173
	v_cmp_gt_f32_e64 s[40:41], s3, v115
	v_mul_f32_e32 v116, 0x4b800000, v115
	s_nop 0
	v_cndmask_b32_e64 v115, v115, v116, s[40:41]
	v_rsq_f32_e32 v115, v115
	s_nop 0
	v_mul_f32_e32 v116, 0x45800000, v115
	v_cndmask_b32_e64 v124, v115, v116, s[40:41]
	s_add_u32 s40, s58, s12
	s_addc_u32 s41, s59, s14
	v_lshl_add_u64 v[120:121], v[156:157], 2, s[40:41]
	v_mad_i64_i32 v[126:127], s[40:41], v114, s4, v[126:127]
	v_lshl_add_u64 v[126:127], v[156:157], 1, v[126:127]
	v_pk_fma_f32 v[110:111], v[110:111], v[124:125], v[200:201] op_sel_hi:[1,0,1]
	v_pk_fma_f32 v[116:117], v[108:109], v[124:125], v[206:207] op_sel_hi:[1,0,1]
	v_pk_fma_f32 v[108:109], v[106:107], v[124:125], v[204:205] op_sel_hi:[1,0,1]
	v_pk_fma_f32 v[112:113], v[112:113], v[124:125], v[202:203] op_sel_hi:[1,0,1]
	v_cvt_pk_bf16_f32 v106, v110, v111
	s_nop 0
	v_cvt_pk_bf16_f32 v107, v112, v113
	v_cvt_pk_bf16_f32 v108, v108, v109
	v_cvt_pk_bf16_f32 v109, v116, v117
	flat_store_dwordx4 v[126:127], v[106:109]
;     DI void operator()(const pg8::f32x4 (&acc)[2][2][4][2], const pg8::Unit& u, int wr, int wc, int fr, int fq) const {
;     ...
;         for (int ai = 0; ai < 2; ++ai)
; #pragma unroll
;             for (int m = 0; m < 4; ++m) { const int rit = ai * 128 + wr * 64 + m * 16 + fr;
; #pragma unroll
;                 for (int bj = 0; bj < 2; ++bj) { f(rit, u.pn * 256 + bj * 128 + wc * 32 + 8 * fq, acc[ai][bj][m][0], acc[ai][bj][m][1], u, fq); __builtin_amdgcn_sched_barrier(0); } }
.LBB0_3945:
	s_or_b64 exec, exec, s[20:21]
	s_and_saveexec_b64 s[20:21], s[36:37]
	s_cbranch_execz .LBB0_3947
	v_ashrrev_i32_e32 v115, 31, v114
	v_lshl_add_u64 v[106:107], v[114:115], 2, s[70:71]
	s_lshr_b32 s12, s2, 31
	s_ashr_i32 s14, s2, 1
	s_add_i32 s12, s14, s12
	s_mul_i32 s14, s12, -9
	s_sub_i32 s33, 0, s63
	s_cmp_lg_u32 s14, s33
	s_cselect_b32 s12, s12, 32
	s_mul_hi_i32 s14, s12, 0x2800
	s_mulk_i32 s12, 0x2800
	v_mov_b64_e32 v[118:119], s[8:9]
	s_movk_i32 s4, 0x1280
	v_fmamk_f32 v106, v217, 0x3a800000, v173
	v_cmp_gt_f32_e64 s[40:41], s3, v106
	v_mul_f32_e32 v107, 0x4b800000, v106
	s_nop 0
	v_cndmask_b32_e64 v106, v106, v107, s[40:41]
	v_rsq_f32_e32 v106, v106
	s_nop 0
	v_mul_f32_e32 v107, 0x45800000, v106
	v_cndmask_b32_e64 v116, v106, v107, s[40:41]
	s_add_u32 s40, s58, s12
	s_addc_u32 s41, s59, s14
	v_lshl_add_u64 v[110:111], v[156:157], 2, s[40:41]
	v_mad_i64_i32 v[114:115], s[40:41], v114, s4, v[118:119]
	v_lshl_add_u64 v[114:115], v[156:157], 1, v[114:115]
	v_pk_fma_f32 v[102:103], v[102:103], v[116:117], v[208:209] op_sel_hi:[1,0,1]
	v_pk_fma_f32 v[106:107], v[100:101], v[116:117], v[214:215] op_sel_hi:[1,0,1]
	v_pk_fma_f32 v[100:101], v[98:99], v[116:117], v[212:213] op_sel_hi:[1,0,1]
	v_pk_fma_f32 v[104:105], v[104:105], v[116:117], v[210:211] op_sel_hi:[1,0,1]
	v_cvt_pk_bf16_f32 v98, v102, v103
	s_nop 0
	v_cvt_pk_bf16_f32 v99, v104, v105
	v_cvt_pk_bf16_f32 v100, v100, v101
	v_cvt_pk_bf16_f32 v101, v106, v107
	flat_store_dwordx4 v[114:115], v[98:101] offset:256
.LBB0_3947:
	s_or_b64 exec, exec, s[20:21]
	s_nop 0
	v_add_u32_e32 v98, 32, v163
	v_lshl_add_u32 v98, s63, 8, v98
	s_and_saveexec_b64 s[20:21], vcc
	s_cbranch_execz .LBB0_3949
	v_ashrrev_i32_e32 v99, 31, v98
	v_lshl_add_u64 v[100:101], v[98:99], 2, s[70:71]
	s_lshr_b32 s12, s2, 31
	s_ashr_i32 s14, s2, 1
	s_add_i32 s12, s14, s12
	s_mul_i32 s14, s12, -9
	s_sub_i32 s33, 0, s63
	s_cmp_lg_u32 s14, s33
	s_cselect_b32 s12, s12, 32
	s_mul_hi_i32 s14, s12, 0x2800
	s_mulk_i32 s12, 0x2800
	v_mov_b64_e32 v[110:111], s[8:9]
	s_movk_i32 s4, 0x1280
	v_fmamk_f32 v99, v218, 0x3a800000, v173
	v_cmp_gt_f32_e64 s[40:41], s3, v99
	v_mul_f32_e32 v100, 0x4b800000, v99
	s_nop 0
	v_cndmask_b32_e64 v99, v99, v100, s[40:41]
	v_rsq_f32_e32 v99, v99
	s_nop 0
	v_mul_f32_e32 v100, 0x45800000, v99
	v_cndmask_b32_e64 v108, v99, v100, s[40:41]
	s_add_u32 s40, s58, s12
	s_addc_u32 s41, s59, s14
	v_lshl_add_u64 v[104:105], v[156:157], 2, s[40:41]
	v_mad_i64_i32 v[110:111], s[40:41], v98, s4, v[110:111]
	v_lshl_add_u64 v[110:111], v[156:157], 1, v[110:111]
	v_pk_fma_f32 v[94:95], v[94:95], v[108:109], v[200:201] op_sel_hi:[1,0,1]
	v_pk_fma_f32 v[100:101], v[92:93], v[108:109], v[206:207] op_sel_hi:[1,0,1]
	v_pk_fma_f32 v[92:93], v[90:91], v[108:109], v[204:205] op_sel_hi:[1,0,1]
	v_pk_fma_f32 v[96:97], v[96:97], v[108:109], v[202:203] op_sel_hi:[1,0,1]
	v_cvt_pk_bf16_f32 v90, v94, v95
	s_nop 0
	v_cvt_pk_bf16_f32 v91, v96, v97
	v_cvt_pk_bf16_f32 v92, v92, v93
	v_cvt_pk_bf16_f32 v93, v100, v101
	flat_store_dwordx4 v[110:111], v[90:93]
.LBB0_3949:
	s_or_b64 exec, exec, s[20:21]
	s_and_saveexec_b64 s[20:21], s[36:37]
	s_cbranch_execz .LBB0_3951
	v_ashrrev_i32_e32 v99, 31, v98
	v_lshl_add_u64 v[90:91], v[98:99], 2, s[70:71]
	s_lshr_b32 s12, s2, 31
	s_ashr_i32 s14, s2, 1
	s_add_i32 s12, s14, s12
	s_mul_i32 s14, s12, -9
	s_sub_i32 s33, 0, s63
	s_cmp_lg_u32 s14, s33
	s_cselect_b32 s12, s12, 32
	s_mul_hi_i32 s14, s12, 0x2800
	s_mulk_i32 s12, 0x2800
	v_mov_b64_e32 v[102:103], s[8:9]
	s_movk_i32 s4, 0x1280
	v_fmamk_f32 v90, v218, 0x3a800000, v173
	v_cmp_gt_f32_e64 s[40:41], s3, v90
	v_mul_f32_e32 v91, 0x4b800000, v90
	s_nop 0
	v_cndmask_b32_e64 v90, v90, v91, s[40:41]
	v_rsq_f32_e32 v90, v90
	s_nop 0
	v_mul_f32_e32 v91, 0x45800000, v90
	v_cndmask_b32_e64 v100, v90, v91, s[40:41]
	s_add_u32 s40, s58, s12
	s_addc_u32 s41, s59, s14
	v_lshl_add_u64 v[94:95], v[156:157], 2, s[40:41]
	v_mad_i64_i32 v[98:99], s[40:41], v98, s4, v[102:103]
	v_lshl_add_u64 v[98:99], v[156:157], 1, v[98:99]
	v_pk_fma_f32 v[86:87], v[86:87], v[100:101], v[208:209] op_sel_hi:[1,0,1]
	v_pk_fma_f32 v[90:91], v[84:85], v[100:101], v[214:215] op_sel_hi:[1,0,1]
	v_pk_fma_f32 v[84:85], v[82:83], v[100:101], v[212:213] op_sel_hi:[1,0,1]
	v_pk_fma_f32 v[88:89], v[88:89], v[100:101], v[210:211] op_sel_hi:[1,0,1]
	v_cvt_pk_bf16_f32 v82, v86, v87
	s_nop 0
	v_cvt_pk_bf16_f32 v83, v88, v89
	v_cvt_pk_bf16_f32 v84, v84, v85
	v_cvt_pk_bf16_f32 v85, v90, v91
	flat_store_dwordx4 v[98:99], v[82:85] offset:256
.LBB0_3951:
	s_or_b64 exec, exec, s[20:21]
	s_nop 0
	v_add_u32_e32 v82, 48, v163
	v_lshl_add_u32 v82, s63, 8, v82
	s_and_saveexec_b64 s[20:21], vcc
	s_cbranch_execz .LBB0_3953
	v_ashrrev_i32_e32 v83, 31, v82
	v_lshl_add_u64 v[84:85], v[82:83], 2, s[70:71]
	s_lshr_b32 s12, s2, 31
	s_ashr_i32 s14, s2, 1
	s_add_i32 s12, s14, s12
	s_mul_i32 s14, s12, -9
	s_sub_i32 s33, 0, s63
	s_cmp_lg_u32 s14, s33
	s_cselect_b32 s12, s12, 32
	s_mul_hi_i32 s14, s12, 0x2800
	s_mulk_i32 s12, 0x2800
	v_mov_b64_e32 v[94:95], s[8:9]
	s_movk_i32 s4, 0x1280
	v_fmamk_f32 v83, v219, 0x3a800000, v173
	v_cmp_gt_f32_e64 s[40:41], s3, v83
	v_mul_f32_e32 v84, 0x4b800000, v83
	s_nop 0
	v_cndmask_b32_e64 v83, v83, v84, s[40:41]
	v_rsq_f32_e32 v83, v83
	s_nop 0
	v_mul_f32_e32 v84, 0x45800000, v83
	v_cndmask_b32_e64 v92, v83, v84, s[40:41]
	s_add_u32 s40, s58, s12
	s_addc_u32 s41, s59, s14
	v_lshl_add_u64 v[88:89], v[156:157], 2, s[40:41]
	v_mad_i64_i32 v[94:95], s[40:41], v82, s4, v[94:95]
	v_lshl_add_u64 v[94:95], v[156:157], 1, v[94:95]
	v_pk_fma_f32 v[78:79], v[78:79], v[92:93], v[200:201] op_sel_hi:[1,0,1]
	v_pk_fma_f32 v[84:85], v[76:77], v[92:93], v[206:207] op_sel_hi:[1,0,1]
	v_pk_fma_f32 v[76:77], v[74:75], v[92:93], v[204:205] op_sel_hi:[1,0,1]
	v_pk_fma_f32 v[80:81], v[80:81], v[92:93], v[202:203] op_sel_hi:[1,0,1]
	v_cvt_pk_bf16_f32 v74, v78, v79
	s_nop 0
	v_cvt_pk_bf16_f32 v75, v80, v81
	v_cvt_pk_bf16_f32 v76, v76, v77
	v_cvt_pk_bf16_f32 v77, v84, v85
	flat_store_dwordx4 v[94:95], v[74:77]
;     DI void operator()(const pg8::f32x4 (&acc)[2][2][4][2], const pg8::Unit& u, int wr, int wc, int fr, int fq) const {
;     ...
;         for (int ai = 0; ai < 2; ++ai)
; #pragma unroll
;             for (int m = 0; m < 4; ++m) { const int rit = ai * 128 + wr * 64 + m * 16 + fr;
; #pragma unroll
;                 for (int bj = 0; bj < 2; ++bj) { f(rit, u.pn * 256 + bj * 128 + wc * 32 + 8 * fq, acc[ai][bj][m][0], acc[ai][bj][m][1], u, fq); __builtin_amdgcn_sched_barrier(0); } }
.LBB0_3953:
	s_or_b64 exec, exec, s[20:21]
	s_and_saveexec_b64 s[20:21], s[36:37]
	s_cbranch_execz .LBB0_3955
	v_ashrrev_i32_e32 v83, 31, v82
	v_lshl_add_u64 v[74:75], v[82:83], 2, s[70:71]
	s_lshr_b32 s12, s2, 31
	s_ashr_i32 s14, s2, 1
	s_add_i32 s12, s14, s12
	s_mul_i32 s14, s12, -9
	s_sub_i32 s33, 0, s63
	s_cmp_lg_u32 s14, s33
	s_cselect_b32 s12, s12, 32
	s_mul_hi_i32 s14, s12, 0x2800
	s_mulk_i32 s12, 0x2800
	v_mov_b64_e32 v[86:87], s[8:9]
	s_movk_i32 s4, 0x1280
	v_fmamk_f32 v74, v219, 0x3a800000, v173
	v_cmp_gt_f32_e64 s[40:41], s3, v74
	v_mul_f32_e32 v75, 0x4b800000, v74
	s_nop 0
	v_cndmask_b32_e64 v74, v74, v75, s[40:41]
	v_rsq_f32_e32 v74, v74
	s_nop 0
	v_mul_f32_e32 v75, 0x45800000, v74
	v_cndmask_b32_e64 v84, v74, v75, s[40:41]
	s_add_u32 s40, s58, s12
	s_addc_u32 s41, s59, s14
	v_lshl_add_u64 v[78:79], v[156:157], 2, s[40:41]
	v_mad_i64_i32 v[82:83], s[40:41], v82, s4, v[86:87]
	v_lshl_add_u64 v[82:83], v[156:157], 1, v[82:83]
	v_pk_fma_f32 v[70:71], v[70:71], v[84:85], v[208:209] op_sel_hi:[1,0,1]
	v_pk_fma_f32 v[74:75], v[68:69], v[84:85], v[214:215] op_sel_hi:[1,0,1]
	v_pk_fma_f32 v[68:69], v[66:67], v[84:85], v[212:213] op_sel_hi:[1,0,1]
	v_pk_fma_f32 v[72:73], v[72:73], v[84:85], v[210:211] op_sel_hi:[1,0,1]
	v_cvt_pk_bf16_f32 v66, v70, v71
	s_nop 0
	v_cvt_pk_bf16_f32 v67, v72, v73
	v_cvt_pk_bf16_f32 v68, v68, v69
	v_cvt_pk_bf16_f32 v69, v74, v75
	flat_store_dwordx4 v[82:83], v[66:69] offset:256
.LBB0_3955:
	s_or_b64 exec, exec, s[20:21]
	s_nop 0
	v_add_u32_e32 v66, 0x80, v163
	v_lshl_add_u32 v66, s63, 8, v66
	s_and_saveexec_b64 s[20:21], vcc
	s_cbranch_execz .LBB0_3957
	v_ashrrev_i32_e32 v67, 31, v66
	v_lshl_add_u64 v[68:69], v[66:67], 2, s[70:71]
	s_lshr_b32 s12, s2, 31
	s_ashr_i32 s14, s2, 1
	s_add_i32 s12, s14, s12
	s_mul_i32 s14, s12, -9
	s_sub_i32 s33, 0, s63
	s_cmp_lg_u32 s14, s33
	s_cselect_b32 s12, s12, 32
	s_mul_hi_i32 s14, s12, 0x2800
	s_mulk_i32 s12, 0x2800
	v_mov_b64_e32 v[78:79], s[8:9]
	s_movk_i32 s4, 0x1280
	v_fmamk_f32 v67, v220, 0x3a800000, v173
	v_cmp_gt_f32_e64 s[40:41], s3, v67
	v_mul_f32_e32 v68, 0x4b800000, v67
	s_nop 0
	v_cndmask_b32_e64 v67, v67, v68, s[40:41]
	v_rsq_f32_e32 v67, v67
	s_nop 0
	v_mul_f32_e32 v68, 0x45800000, v67
	v_cndmask_b32_e64 v76, v67, v68, s[40:41]
	s_add_u32 s40, s58, s12
	s_addc_u32 s41, s59, s14
	v_lshl_add_u64 v[72:73], v[156:157], 2, s[40:41]
	v_mad_i64_i32 v[78:79], s[40:41], v66, s4, v[78:79]
	v_lshl_add_u64 v[78:79], v[156:157], 1, v[78:79]
	v_pk_fma_f32 v[62:63], v[62:63], v[76:77], v[200:201] op_sel_hi:[1,0,1]
	v_pk_fma_f32 v[68:69], v[60:61], v[76:77], v[206:207] op_sel_hi:[1,0,1]
	v_pk_fma_f32 v[60:61], v[58:59], v[76:77], v[204:205] op_sel_hi:[1,0,1]
	v_pk_fma_f32 v[64:65], v[64:65], v[76:77], v[202:203] op_sel_hi:[1,0,1]
	v_cvt_pk_bf16_f32 v58, v62, v63
	s_nop 0
	v_cvt_pk_bf16_f32 v59, v64, v65
	v_cvt_pk_bf16_f32 v60, v60, v61
	v_cvt_pk_bf16_f32 v61, v68, v69
	flat_store_dwordx4 v[78:79], v[58:61]
.LBB0_3957:
	s_or_b64 exec, exec, s[20:21]
	s_and_saveexec_b64 s[20:21], s[36:37]
	s_cbranch_execz .LBB0_3959
	v_ashrrev_i32_e32 v67, 31, v66
	v_lshl_add_u64 v[58:59], v[66:67], 2, s[70:71]
	s_lshr_b32 s12, s2, 31
	s_ashr_i32 s14, s2, 1
	s_add_i32 s12, s14, s12
	s_mul_i32 s14, s12, -9
	s_sub_i32 s33, 0, s63
	s_cmp_lg_u32 s14, s33
	s_cselect_b32 s12, s12, 32
	s_mul_hi_i32 s14, s12, 0x2800
	s_mulk_i32 s12, 0x2800
	v_mov_b64_e32 v[70:71], s[8:9]
	s_movk_i32 s4, 0x1280
	v_fmamk_f32 v58, v220, 0x3a800000, v173
	v_cmp_gt_f32_e64 s[40:41], s3, v58
	v_mul_f32_e32 v59, 0x4b800000, v58
	s_nop 0
	v_cndmask_b32_e64 v58, v58, v59, s[40:41]
	v_rsq_f32_e32 v58, v58
	s_nop 0
	v_mul_f32_e32 v59, 0x45800000, v58
	v_cndmask_b32_e64 v68, v58, v59, s[40:41]
	s_add_u32 s40, s58, s12
	s_addc_u32 s41, s59, s14
	v_lshl_add_u64 v[62:63], v[156:157], 2, s[40:41]
	v_mad_i64_i32 v[66:67], s[40:41], v66, s4, v[70:71]
	v_lshl_add_u64 v[66:67], v[156:157], 1, v[66:67]
	v_pk_fma_f32 v[54:55], v[54:55], v[68:69], v[208:209] op_sel_hi:[1,0,1]
	v_pk_fma_f32 v[58:59], v[52:53], v[68:69], v[214:215] op_sel_hi:[1,0,1]
	v_pk_fma_f32 v[52:53], v[50:51], v[68:69], v[212:213] op_sel_hi:[1,0,1]
	v_pk_fma_f32 v[56:57], v[56:57], v[68:69], v[210:211] op_sel_hi:[1,0,1]
	v_cvt_pk_bf16_f32 v50, v54, v55
	s_nop 0
	v_cvt_pk_bf16_f32 v51, v56, v57
	v_cvt_pk_bf16_f32 v52, v52, v53
	v_cvt_pk_bf16_f32 v53, v58, v59
	flat_store_dwordx4 v[66:67], v[50:53] offset:256
.LBB0_3959:
	s_or_b64 exec, exec, s[20:21]
	s_nop 0
	v_add_u32_e32 v50, 0x90, v163
	v_lshl_add_u32 v50, s63, 8, v50
	s_and_saveexec_b64 s[20:21], vcc
	s_cbranch_execz .LBB0_3961
	v_ashrrev_i32_e32 v51, 31, v50
	v_lshl_add_u64 v[52:53], v[50:51], 2, s[70:71]
	s_lshr_b32 s12, s2, 31
	s_ashr_i32 s14, s2, 1
	s_add_i32 s12, s14, s12
	s_mul_i32 s14, s12, -9
	s_sub_i32 s33, 0, s63
	s_cmp_lg_u32 s14, s33
	s_cselect_b32 s12, s12, 32
	s_mul_hi_i32 s14, s12, 0x2800
	s_mulk_i32 s12, 0x2800
	v_mov_b64_e32 v[62:63], s[8:9]
	s_movk_i32 s4, 0x1280
	v_fmamk_f32 v51, v221, 0x3a800000, v173
	v_cmp_gt_f32_e64 s[40:41], s3, v51
	v_mul_f32_e32 v52, 0x4b800000, v51
	s_nop 0
	v_cndmask_b32_e64 v51, v51, v52, s[40:41]
	v_rsq_f32_e32 v51, v51
	s_nop 0
	v_mul_f32_e32 v52, 0x45800000, v51
	v_cndmask_b32_e64 v60, v51, v52, s[40:41]
	s_add_u32 s40, s58, s12
	s_addc_u32 s41, s59, s14
	v_lshl_add_u64 v[56:57], v[156:157], 2, s[40:41]
	v_mad_i64_i32 v[62:63], s[40:41], v50, s4, v[62:63]
	v_lshl_add_u64 v[62:63], v[156:157], 1, v[62:63]
	v_pk_fma_f32 v[46:47], v[46:47], v[60:61], v[200:201] op_sel_hi:[1,0,1]
	v_pk_fma_f32 v[52:53], v[44:45], v[60:61], v[206:207] op_sel_hi:[1,0,1]
	v_pk_fma_f32 v[44:45], v[42:43], v[60:61], v[204:205] op_sel_hi:[1,0,1]
	v_pk_fma_f32 v[48:49], v[48:49], v[60:61], v[202:203] op_sel_hi:[1,0,1]
	v_cvt_pk_bf16_f32 v42, v46, v47
	s_nop 0
	v_cvt_pk_bf16_f32 v43, v48, v49
	v_cvt_pk_bf16_f32 v44, v44, v45
	v_cvt_pk_bf16_f32 v45, v52, v53
	flat_store_dwordx4 v[62:63], v[42:45]
;     DI void operator()(const pg8::f32x4 (&acc)[2][2][4][2], const pg8::Unit& u, int wr, int wc, int fr, int fq) const {
;     ...
;         for (int ai = 0; ai < 2; ++ai)
; #pragma unroll
;             for (int m = 0; m < 4; ++m) { const int rit = ai * 128 + wr * 64 + m * 16 + fr;
; #pragma unroll
;                 for (int bj = 0; bj < 2; ++bj) { f(rit, u.pn * 256 + bj * 128 + wc * 32 + 8 * fq, acc[ai][bj][m][0], acc[ai][bj][m][1], u, fq); __builtin_amdgcn_sched_barrier(0); } }
.LBB0_3961:
	s_or_b64 exec, exec, s[20:21]
	s_and_saveexec_b64 s[20:21], s[36:37]
	s_cbranch_execz .LBB0_3963
	v_ashrrev_i32_e32 v51, 31, v50
	v_lshl_add_u64 v[42:43], v[50:51], 2, s[70:71]
	s_lshr_b32 s12, s2, 31
	s_ashr_i32 s14, s2, 1
	s_add_i32 s12, s14, s12
	s_mul_i32 s14, s12, -9
	s_sub_i32 s33, 0, s63
	s_cmp_lg_u32 s14, s33
	s_cselect_b32 s12, s12, 32
	s_mul_hi_i32 s14, s12, 0x2800
	s_mulk_i32 s12, 0x2800
	v_mov_b64_e32 v[54:55], s[8:9]
	s_movk_i32 s4, 0x1280
	v_fmamk_f32 v42, v221, 0x3a800000, v173
	v_cmp_gt_f32_e64 s[40:41], s3, v42
	v_mul_f32_e32 v43, 0x4b800000, v42
	s_nop 0
	v_cndmask_b32_e64 v42, v42, v43, s[40:41]
	v_rsq_f32_e32 v42, v42
	s_nop 0
	v_mul_f32_e32 v43, 0x45800000, v42
	v_cndmask_b32_e64 v52, v42, v43, s[40:41]
	s_add_u32 s40, s58, s12
	s_addc_u32 s41, s59, s14
	v_lshl_add_u64 v[46:47], v[156:157], 2, s[40:41]
	v_mad_i64_i32 v[50:51], s[40:41], v50, s4, v[54:55]
	v_lshl_add_u64 v[50:51], v[156:157], 1, v[50:51]
	v_pk_fma_f32 v[38:39], v[38:39], v[52:53], v[208:209] op_sel_hi:[1,0,1]
	v_pk_fma_f32 v[42:43], v[36:37], v[52:53], v[214:215] op_sel_hi:[1,0,1]
	v_pk_fma_f32 v[36:37], v[34:35], v[52:53], v[212:213] op_sel_hi:[1,0,1]
	v_pk_fma_f32 v[40:41], v[40:41], v[52:53], v[210:211] op_sel_hi:[1,0,1]
	v_cvt_pk_bf16_f32 v34, v38, v39
	s_nop 0
	v_cvt_pk_bf16_f32 v35, v40, v41
	v_cvt_pk_bf16_f32 v36, v36, v37
	v_cvt_pk_bf16_f32 v37, v42, v43
	flat_store_dwordx4 v[50:51], v[34:37] offset:256
.LBB0_3963:
	s_or_b64 exec, exec, s[20:21]
	s_nop 0
	v_add_u32_e32 v34, 0xa0, v163
	v_lshl_add_u32 v34, s63, 8, v34
	s_and_saveexec_b64 s[20:21], vcc
	s_cbranch_execz .LBB0_3965
	v_ashrrev_i32_e32 v35, 31, v34
	v_lshl_add_u64 v[36:37], v[34:35], 2, s[70:71]
	s_lshr_b32 s12, s2, 31
	s_ashr_i32 s14, s2, 1
	s_add_i32 s12, s14, s12
	s_mul_i32 s14, s12, -9
	s_sub_i32 s33, 0, s63
	s_cmp_lg_u32 s14, s33
	s_cselect_b32 s12, s12, 32
	s_mul_hi_i32 s14, s12, 0x2800
	s_mulk_i32 s12, 0x2800
	v_mov_b64_e32 v[46:47], s[8:9]
	s_movk_i32 s4, 0x1280
	v_fmamk_f32 v35, v222, 0x3a800000, v173
	v_cmp_gt_f32_e64 s[40:41], s3, v35
	v_mul_f32_e32 v36, 0x4b800000, v35
	s_nop 0
	v_cndmask_b32_e64 v35, v35, v36, s[40:41]
	v_rsq_f32_e32 v35, v35
	s_nop 0
	v_mul_f32_e32 v36, 0x45800000, v35
	v_cndmask_b32_e64 v44, v35, v36, s[40:41]
	s_add_u32 s40, s58, s12
	s_addc_u32 s41, s59, s14
	v_lshl_add_u64 v[40:41], v[156:157], 2, s[40:41]
	v_mad_i64_i32 v[46:47], s[40:41], v34, s4, v[46:47]
	v_lshl_add_u64 v[46:47], v[156:157], 1, v[46:47]
	v_pk_fma_f32 v[30:31], v[30:31], v[44:45], v[200:201] op_sel_hi:[1,0,1]
	v_pk_fma_f32 v[36:37], v[28:29], v[44:45], v[206:207] op_sel_hi:[1,0,1]
	v_pk_fma_f32 v[28:29], v[26:27], v[44:45], v[204:205] op_sel_hi:[1,0,1]
	v_pk_fma_f32 v[32:33], v[32:33], v[44:45], v[202:203] op_sel_hi:[1,0,1]
	v_cvt_pk_bf16_f32 v26, v30, v31
	s_nop 0
	v_cvt_pk_bf16_f32 v27, v32, v33
	v_cvt_pk_bf16_f32 v28, v28, v29
	v_cvt_pk_bf16_f32 v29, v36, v37
	flat_store_dwordx4 v[46:47], v[26:29]
;     DI void operator()(const pg8::f32x4 (&acc)[2][2][4][2], const pg8::Unit& u, int wr, int wc, int fr, int fq) const {
;     ...
;         for (int ai = 0; ai < 2; ++ai)
; #pragma unroll
;             for (int m = 0; m < 4; ++m) { const int rit = ai * 128 + wr * 64 + m * 16 + fr;
; #pragma unroll
;                 for (int bj = 0; bj < 2; ++bj) { f(rit, u.pn * 256 + bj * 128 + wc * 32 + 8 * fq, acc[ai][bj][m][0], acc[ai][bj][m][1], u, fq); __builtin_amdgcn_sched_barrier(0); } }
.LBB0_3965:
	s_or_b64 exec, exec, s[20:21]
	s_and_saveexec_b64 s[20:21], s[36:37]
	s_cbranch_execz .LBB0_3967
	v_ashrrev_i32_e32 v35, 31, v34
	v_lshl_add_u64 v[26:27], v[34:35], 2, s[70:71]
	s_lshr_b32 s12, s2, 31
	s_ashr_i32 s14, s2, 1
	s_add_i32 s12, s14, s12
	s_mul_i32 s14, s12, -9
	s_sub_i32 s33, 0, s63
	s_cmp_lg_u32 s14, s33
	s_cselect_b32 s12, s12, 32
	s_mul_hi_i32 s14, s12, 0x2800
	s_mulk_i32 s12, 0x2800
	v_mov_b64_e32 v[38:39], s[8:9]
	s_movk_i32 s4, 0x1280
	v_fmamk_f32 v26, v222, 0x3a800000, v173
	v_cmp_gt_f32_e64 s[40:41], s3, v26
	v_mul_f32_e32 v27, 0x4b800000, v26
	s_nop 0
	v_cndmask_b32_e64 v26, v26, v27, s[40:41]
	v_rsq_f32_e32 v26, v26
	s_nop 0
	v_mul_f32_e32 v27, 0x45800000, v26
	v_cndmask_b32_e64 v36, v26, v27, s[40:41]
	s_add_u32 s40, s58, s12
	s_addc_u32 s41, s59, s14
	v_lshl_add_u64 v[30:31], v[156:157], 2, s[40:41]
	v_mad_i64_i32 v[34:35], s[40:41], v34, s4, v[38:39]
	v_lshl_add_u64 v[34:35], v[156:157], 1, v[34:35]
	v_pk_fma_f32 v[22:23], v[22:23], v[36:37], v[208:209] op_sel_hi:[1,0,1]
	v_pk_fma_f32 v[26:27], v[20:21], v[36:37], v[214:215] op_sel_hi:[1,0,1]
	v_pk_fma_f32 v[20:21], v[18:19], v[36:37], v[212:213] op_sel_hi:[1,0,1]
	v_pk_fma_f32 v[24:25], v[24:25], v[36:37], v[210:211] op_sel_hi:[1,0,1]
	v_cvt_pk_bf16_f32 v18, v22, v23
	s_nop 0
	v_cvt_pk_bf16_f32 v19, v24, v25
	v_cvt_pk_bf16_f32 v20, v20, v21
	v_cvt_pk_bf16_f32 v21, v26, v27
	flat_store_dwordx4 v[34:35], v[18:21] offset:256
.LBB0_3967:
	s_or_b64 exec, exec, s[20:21]
	s_nop 0
	v_add_u32_e32 v18, 0xb0, v163
	v_lshl_add_u32 v18, s63, 8, v18
	s_and_saveexec_b64 s[20:21], vcc
	s_cbranch_execz .LBB0_3969
	v_ashrrev_i32_e32 v19, 31, v18
	v_lshl_add_u64 v[20:21], v[18:19], 2, s[70:71]
	s_lshr_b32 s12, s2, 31
	s_ashr_i32 s14, s2, 1
	s_add_i32 s12, s14, s12
	s_mul_i32 s14, s12, -9
	s_sub_i32 s33, 0, s63
	s_cmp_lg_u32 s14, s33
	s_cselect_b32 s12, s12, 32
	s_mul_hi_i32 s14, s12, 0x2800
	s_mulk_i32 s12, 0x2800
	s_add_u32 s40, s58, s12
	s_addc_u32 s41, s59, s14
	v_lshl_add_u64 v[24:25], v[156:157], 2, s[40:41]
	v_mov_b64_e32 v[30:31], s[8:9]
	s_movk_i32 s4, 0x1280
	v_mad_i64_i32 v[30:31], s[40:41], v18, s4, v[30:31]
	v_lshl_add_u64 v[30:31], v[156:157], 1, v[30:31]
	v_fmamk_f32 v19, v223, 0x3a800000, v173
	v_cmp_gt_f32_e32 vcc, s3, v19
	v_mul_f32_e32 v20, 0x4b800000, v19
	s_nop 0
	v_cndmask_b32_e32 v19, v19, v20, vcc
	v_rsq_f32_e32 v19, v19
	s_nop 0
	v_mul_f32_e32 v20, 0x45800000, v19
	v_cndmask_b32_e32 v28, v19, v20, vcc
	v_pk_fma_f32 v[14:15], v[14:15], v[28:29], v[200:201] op_sel_hi:[1,0,1]
	v_pk_fma_f32 v[20:21], v[12:13], v[28:29], v[206:207] op_sel_hi:[1,0,1]
	v_pk_fma_f32 v[12:13], v[10:11], v[28:29], v[204:205] op_sel_hi:[1,0,1]
	v_pk_fma_f32 v[16:17], v[16:17], v[28:29], v[202:203] op_sel_hi:[1,0,1]
	v_cvt_pk_bf16_f32 v10, v14, v15
	s_nop 0
	v_cvt_pk_bf16_f32 v11, v16, v17
	v_cvt_pk_bf16_f32 v12, v12, v13
	v_cvt_pk_bf16_f32 v13, v20, v21
	flat_store_dwordx4 v[30:31], v[10:13]
.LBB0_3969:
	s_or_b64 exec, exec, s[20:21]
	s_and_saveexec_b64 s[20:21], s[36:37]
	s_movk_i32 s33, 0x1000
	s_cbranch_execz .LBB0_3971
	v_ashrrev_i32_e32 v19, 31, v18
	v_lshl_add_u64 v[10:11], v[18:19], 2, s[70:71]
	s_lshr_b32 s12, s2, 31
	s_ashr_i32 s2, s2, 1
	s_add_i32 s2, s2, s12
	s_mul_i32 s12, s2, -9
	s_sub_i32 s14, 0, s63
	s_cmp_lg_u32 s12, s14
	s_cselect_b32 s2, s2, 32
	s_mul_hi_i32 s12, s2, 0x2800
	s_mulk_i32 s2, 0x2800
	s_add_u32 s36, s58, s2
	s_addc_u32 s37, s59, s12
	v_lshl_add_u64 v[14:15], v[156:157], 2, s[36:37]
	v_mov_b64_e32 v[20:21], s[8:9]
	s_movk_i32 s2, 0x1280
	v_fmamk_f32 v19, v223, 0x3a800000, v173
	v_mul_f32_e32 v22, 0x4b800000, v19
	v_cmp_gt_f32_e32 vcc, s3, v19
	s_nop 1
	v_cndmask_b32_e32 v19, v19, v22, vcc
	v_rsq_f32_e32 v22, v19
	v_mad_i64_i32 v[18:19], s[36:37], v18, s2, v[20:21]
	v_lshl_add_u64 v[18:19], v[156:157], 1, v[18:19]
	v_mul_f32_e32 v20, 0x45800000, v22
	v_cndmask_b32_e32 v20, v22, v20, vcc
	v_pk_fma_f32 v[6:7], v[6:7], v[20:21], v[208:209] op_sel_hi:[1,0,1]
	v_pk_fma_f32 v[10:11], v[4:5], v[20:21], v[214:215] op_sel_hi:[1,0,1]
	v_pk_fma_f32 v[4:5], v[2:3], v[20:21], v[212:213] op_sel_hi:[1,0,1]
	v_pk_fma_f32 v[8:9], v[8:9], v[20:21], v[210:211] op_sel_hi:[1,0,1]
	v_cvt_pk_bf16_f32 v2, v6, v7
	s_nop 0
	v_cvt_pk_bf16_f32 v3, v8, v9
	v_cvt_pk_bf16_f32 v4, v4, v5
	v_cvt_pk_bf16_f32 v5, v10, v11
	flat_store_dwordx4 v[18:19], v[2:5] offset:256

; __global__ void __launch_bounds__(512, 2) trunk_fwd(Args ka) {
	.amdhsa_kernel _Z9trunk_fwd4Args
		.amdhsa_group_segment_fixed_size 0
		.amdhsa_private_segment_fixed_size 0
		.amdhsa_kernarg_size 528
		.amdhsa_user_sgpr_count 2
		.amdhsa_user_sgpr_dispatch_ptr 0
		.amdhsa_user_sgpr_queue_ptr 0
		.amdhsa_user_sgpr_kernarg_segment_ptr 1
		.amdhsa_user_sgpr_dispatch_id 0
		.amdhsa_user_sgpr_kernarg_preload_length 0
		.amdhsa_user_sgpr_kernarg_preload_offset 0
		.amdhsa_user_sgpr_private_segment_size 0
		.amdhsa_uses_dynamic_stack 0
		.amdhsa_enable_private_segment 0
		.amdhsa_system_sgpr_workgroup_id_x 1
		.amdhsa_system_sgpr_workgroup_id_y 0
		.amdhsa_system_sgpr_workgroup_id_z 0
		.amdhsa_system_sgpr_workgroup_info 0
		.amdhsa_system_vgpr_workitem_id 2
		.amdhsa_next_free_vgpr 255
		.amdhsa_next_free_sgpr 102
		.amdhsa_accum_offset 256
		.amdhsa_reserve_vcc 1
		.amdhsa_float_round_mode_32 0
		.amdhsa_float_round_mode_16_64 0
		.amdhsa_float_denorm_mode_32 3
		.amdhsa_float_denorm_mode_16_64 3
		.amdhsa_dx10_clamp 1
		.amdhsa_ieee_mode 1
		.amdhsa_fp16_overflow 0
		.amdhsa_tg_split 0
		.amdhsa_exception_fp_ieee_invalid_op 0
		.amdhsa_exception_fp_denorm_src 0
		.amdhsa_exception_fp_ieee_div_zero 0
		.amdhsa_exception_fp_ieee_overflow 0
		.amdhsa_exception_fp_ieee_underflow 0
		.amdhsa_exception_fp_ieee_inexact 0
		.amdhsa_exception_int_div_zero 0
	.end_amdhsa_kernel

; __global__ void __launch_bounds__(512, 2) trunk_fwd(Args ka) {
amdhsa.kernels:
  - .agpr_count:     0
    .args:
      - .offset:         0
        .size:           272
        .value_kind:     by_value
      - .offset:         272
        .size:           4
        .value_kind:     hidden_block_count_x
      - .offset:         276
        .size:           4
        .value_kind:     hidden_block_count_y
      - .offset:         280
        .size:           4
        .value_kind:     hidden_block_count_z
      - .offset:         284
        .size:           2
        .value_kind:     hidden_group_size_x
      - .offset:         286
        .size:           2
        .value_kind:     hidden_group_size_y
      - .offset:         288
        .size:           2
        .value_kind:     hidden_group_size_z
      - .offset:         290
        .size:           2
        .value_kind:     hidden_remainder_x
      - .offset:         292
        .size:           2
        .value_kind:     hidden_remainder_y
      - .offset:         294
        .size:           2
        .value_kind:     hidden_remainder_z
      - .offset:         312
        .size:           8
        .value_kind:     hidden_global_offset_x
      - .offset:         320
        .size:           8
        .value_kind:     hidden_global_offset_y
      - .offset:         328
        .size:           8
        .value_kind:     hidden_global_offset_z
      - .offset:         336
        .size:           2
        .value_kind:     hidden_grid_dims
      - .offset:         360
        .size:           8
        .value_kind:     hidden_multigrid_sync_arg
      - .offset:         392
        .size:           4
        .value_kind:     hidden_dynamic_lds_size
    .group_segment_fixed_size: 0
    .kernarg_segment_align: 8
    .kernarg_segment_size: 528
    .language:       OpenCL C
    .language_version:
      - 2
      - 0
    .max_flat_workgroup_size: 512
    .name:           _Z9trunk_fwd4Args
    .private_segment_fixed_size: 0
    .sgpr_count:     108
    .sgpr_spill_count: 221
    .symbol:         _Z9trunk_fwd4Args.kd
    .uniform_work_group_size: 1
    .uses_dynamic_stack: false
    .vgpr_count:     255
    .vgpr_spill_count: 0
    .wavefront_size: 64
